# v16-equivalent with the B-fragment-major boustrophedon MFMA order instead of A-major
# baseline (speedup 1.0000x reference)
.LBB0_642:
	ds_read_b128 v[148:151], v139
	ds_read_b128 v[152:155], v139 offset:1024
	ds_read_b128 v[156:159], v139 offset:2048
	ds_read_b128 v[160:163], v139 offset:3072
	ds_read_b128 v[164:167], v140
	ds_read_b128 v[168:171], v140 offset:1024
	ds_read_b128 v[172:175], v140 offset:2048
	ds_read_b128 v[176:179], v140 offset:3072
	s_add_i32 s18, s71, 0xffe80080
	s_cmp_eq_u32 s58, s73
	s_cselect_b32 s74, s69, s18
	s_cselect_b32 s76, s70, s72
	s_or_b32 s75, s74, 0x80
	s_add_i32 s18, s71, 0xfff80000
	s_mov_b32 m0, s59
	ds_read_b128 v[180:183], v141
	ds_read_b128 v[184:187], v141 offset:1024
	ds_read_b128 v[188:191], v141 offset:2048
	ds_read_b128 v[192:195], v141 offset:3072
	ds_read_b128 v[196:199], v141 offset:4096
	ds_read_b128 v[200:203], v141 offset:5120
	ds_read_b128 v[204:207], v141 offset:6144
	ds_read_b128 v[208:211], v141 offset:7168
	buffer_load_dwordx4 v137, s[12:15], s18 offen lds
	s_mov_b32 m0, s60
	s_nop 0
	buffer_load_dwordx4 v137, s[12:15], s71 offen lds
	s_waitcnt vmcnt(8) lgkmcnt(0)
	s_setprio 1
	v_mfma_f32_16x16x32_bf16 v[118:121], v[148:151], v[180:183], v[118:121]
	s_barrier
	v_mfma_f32_16x16x32_bf16 v[118:121], v[152:155], v[184:187], v[118:121]
	v_mfma_f32_16x16x32_bf16 v[110:113], v[148:151], v[188:191], v[110:113]
	v_mfma_f32_16x16x32_bf16 v[110:113], v[152:155], v[192:195], v[110:113]
	v_mfma_f32_16x16x32_bf16 v[94:97], v[148:151], v[196:199], v[94:97]
	v_mfma_f32_16x16x32_bf16 v[94:97], v[152:155], v[200:203], v[94:97]
	v_mfma_f32_16x16x32_bf16 v[78:81], v[148:151], v[204:207], v[78:81]
	v_mfma_f32_16x16x32_bf16 v[78:81], v[152:155], v[208:211], v[78:81]
	v_mfma_f32_16x16x32_bf16 v[66:69], v[156:159], v[204:207], v[66:69]
	v_mfma_f32_16x16x32_bf16 v[66:69], v[160:163], v[208:211], v[66:69]
	v_mfma_f32_16x16x32_bf16 v[86:89], v[156:159], v[196:199], v[86:89]
	v_mfma_f32_16x16x32_bf16 v[86:89], v[160:163], v[200:203], v[86:89]
	v_mfma_f32_16x16x32_bf16 v[102:105], v[156:159], v[188:191], v[102:105]
	v_mfma_f32_16x16x32_bf16 v[102:105], v[160:163], v[192:195], v[102:105]
	v_mfma_f32_16x16x32_bf16 v[114:117], v[156:159], v[180:183], v[114:117]
	v_mfma_f32_16x16x32_bf16 v[114:117], v[160:163], v[184:187], v[114:117]
	v_mfma_f32_16x16x32_bf16 v[126:129], v[164:167], v[180:183], v[126:129]
	v_mfma_f32_16x16x32_bf16 v[126:129], v[168:171], v[184:187], v[126:129]
	v_mfma_f32_16x16x32_bf16 v[106:109], v[164:167], v[188:191], v[106:109]
	v_mfma_f32_16x16x32_bf16 v[106:109], v[168:171], v[192:195], v[106:109]
	v_mfma_f32_16x16x32_bf16 v[90:93], v[164:167], v[196:199], v[90:93]
	v_mfma_f32_16x16x32_bf16 v[90:93], v[168:171], v[200:203], v[90:93]
	v_mfma_f32_16x16x32_bf16 v[74:77], v[164:167], v[204:207], v[74:77]
	v_mfma_f32_16x16x32_bf16 v[74:77], v[168:171], v[208:211], v[74:77]
	v_mfma_f32_16x16x32_bf16 v[70:73], v[172:175], v[204:207], v[70:73]
	v_mfma_f32_16x16x32_bf16 v[70:73], v[176:179], v[208:211], v[70:73]
	v_mfma_f32_16x16x32_bf16 v[82:85], v[172:175], v[196:199], v[82:85]
	v_mfma_f32_16x16x32_bf16 v[82:85], v[176:179], v[200:203], v[82:85]
	v_mfma_f32_16x16x32_bf16 v[98:101], v[172:175], v[188:191], v[98:101]
	v_mfma_f32_16x16x32_bf16 v[98:101], v[176:179], v[192:195], v[98:101]
	v_mfma_f32_16x16x32_bf16 v[122:125], v[172:175], v[180:183], v[122:125]
	v_mfma_f32_16x16x32_bf16 v[122:125], v[176:179], v[184:187], v[122:125]
	s_setprio 0
	s_barrier
	s_mov_b32 m0, s30
	s_mov_b32 s18, s14
	s_mov_b32 s19, s15
	ds_read_b128 v[180:183], v141 offset:16384
	ds_read_b128 v[184:187], v141 offset:17408
	ds_read_b128 v[188:191], v141 offset:18432
	ds_read_b128 v[192:195], v141 offset:19456
	ds_read_b128 v[196:199], v141 offset:20480
	ds_read_b128 v[200:203], v141 offset:21504
	ds_read_b128 v[204:207], v141 offset:22528
	ds_read_b128 v[208:211], v141 offset:23552
	buffer_load_dwordx4 v138, s[16:19], s76 offen lds
	s_mov_b32 m0, s31
	s_add_i32 s77, s76, 0x80000
	buffer_load_dwordx4 v138, s[16:19], s77 offen lds
	s_mov_b32 m0, s44
	s_add_i32 s77, s76, 0x100000
	buffer_load_dwordx4 v138, s[16:19], s77 offen lds
	s_mov_b32 m0, s45
	s_add_i32 s77, s76, 0x180000
	buffer_load_dwordx4 v138, s[16:19], s77 offen lds
	s_mov_b32 m0, s27
	s_add_i32 s77, s74, 0x80000
	buffer_load_dwordx4 v137, s[12:15], s74 offen lds
	s_mov_b32 m0, s46
	s_nop 0
	buffer_load_dwordx4 v137, s[12:15], s77 offen lds
	s_waitcnt vmcnt(8) lgkmcnt(0)
	s_setprio 1
	v_mfma_f32_16x16x32_bf16 v[62:65], v[148:151], v[180:183], v[62:65]
	s_barrier
	v_mfma_f32_16x16x32_bf16 v[62:65], v[152:155], v[184:187], v[62:65]
	v_mfma_f32_16x16x32_bf16 v[46:49], v[148:151], v[188:191], v[46:49]
	v_mfma_f32_16x16x32_bf16 v[46:49], v[152:155], v[192:195], v[46:49]
	v_mfma_f32_16x16x32_bf16 v[30:33], v[148:151], v[196:199], v[30:33]
	v_mfma_f32_16x16x32_bf16 v[30:33], v[152:155], v[200:203], v[30:33]
	v_mfma_f32_16x16x32_bf16 v[14:17], v[148:151], v[204:207], v[14:17]
	v_mfma_f32_16x16x32_bf16 v[14:17], v[152:155], v[208:211], v[14:17]
	v_mfma_f32_16x16x32_bf16 v[6:9], v[156:159], v[204:207], v[6:9]
	v_mfma_f32_16x16x32_bf16 v[6:9], v[160:163], v[208:211], v[6:9]
	v_mfma_f32_16x16x32_bf16 v[22:25], v[156:159], v[196:199], v[22:25]
	v_mfma_f32_16x16x32_bf16 v[22:25], v[160:163], v[200:203], v[22:25]
	v_mfma_f32_16x16x32_bf16 v[38:41], v[156:159], v[188:191], v[38:41]
	v_mfma_f32_16x16x32_bf16 v[38:41], v[160:163], v[192:195], v[38:41]
	v_mfma_f32_16x16x32_bf16 v[54:57], v[156:159], v[180:183], v[54:57]
	v_mfma_f32_16x16x32_bf16 v[54:57], v[160:163], v[184:187], v[54:57]
	v_mfma_f32_16x16x32_bf16 v[58:61], v[164:167], v[180:183], v[58:61]
	v_mfma_f32_16x16x32_bf16 v[58:61], v[168:171], v[184:187], v[58:61]
	v_mfma_f32_16x16x32_bf16 v[42:45], v[164:167], v[188:191], v[42:45]
	v_mfma_f32_16x16x32_bf16 v[42:45], v[168:171], v[192:195], v[42:45]
	v_mfma_f32_16x16x32_bf16 v[26:29], v[164:167], v[196:199], v[26:29]
	v_mfma_f32_16x16x32_bf16 v[26:29], v[168:171], v[200:203], v[26:29]
	v_mfma_f32_16x16x32_bf16 v[10:13], v[164:167], v[204:207], v[10:13]
	v_mfma_f32_16x16x32_bf16 v[10:13], v[168:171], v[208:211], v[10:13]
	v_mfma_f32_16x16x32_bf16 v[2:5], v[172:175], v[204:207], v[2:5]
	v_mfma_f32_16x16x32_bf16 v[2:5], v[176:179], v[208:211], v[2:5]
	v_mfma_f32_16x16x32_bf16 v[18:21], v[172:175], v[196:199], v[18:21]
	v_mfma_f32_16x16x32_bf16 v[18:21], v[176:179], v[200:203], v[18:21]
	v_mfma_f32_16x16x32_bf16 v[34:37], v[172:175], v[188:191], v[34:37]
	v_mfma_f32_16x16x32_bf16 v[34:37], v[176:179], v[192:195], v[34:37]
	v_mfma_f32_16x16x32_bf16 v[50:53], v[172:175], v[180:183], v[50:53]
	v_mfma_f32_16x16x32_bf16 v[50:53], v[176:179], v[184:187], v[50:53]
	s_setprio 0
	s_barrier
	ds_read_b128 v[148:151], v142
	ds_read_b128 v[152:155], v142 offset:1024
	ds_read_b128 v[156:159], v142 offset:2048
	ds_read_b128 v[160:163], v142 offset:3072
	ds_read_b128 v[164:167], v143
	ds_read_b128 v[168:171], v143 offset:1024
	ds_read_b128 v[172:175], v143 offset:2048
	ds_read_b128 v[176:179], v143 offset:3072
	s_mov_b32 m0, s47
	s_add_i32 s77, s74, 0x100000
	ds_read_b128 v[180:183], v141 offset:32768
	ds_read_b128 v[184:187], v141 offset:33792
	ds_read_b128 v[188:191], v141 offset:34816
	ds_read_b128 v[192:195], v141 offset:35840
	ds_read_b128 v[196:199], v141 offset:36864
	ds_read_b128 v[200:203], v141 offset:37888
	ds_read_b128 v[204:207], v141 offset:38912
	ds_read_b128 v[208:211], v141 offset:39936
	buffer_load_dwordx4 v137, s[12:15], s77 offen lds
	s_mov_b32 m0, s48
	s_add_i32 s77, s74, 0x180000
	buffer_load_dwordx4 v137, s[12:15], s77 offen lds
	s_waitcnt vmcnt(8) lgkmcnt(0)
	s_setprio 1
	v_mfma_f32_16x16x32_bf16 v[118:121], v[148:151], v[180:183], v[118:121]
	s_barrier
	v_mfma_f32_16x16x32_bf16 v[118:121], v[152:155], v[184:187], v[118:121]
	v_mfma_f32_16x16x32_bf16 v[110:113], v[148:151], v[188:191], v[110:113]
	v_mfma_f32_16x16x32_bf16 v[110:113], v[152:155], v[192:195], v[110:113]
	v_mfma_f32_16x16x32_bf16 v[94:97], v[148:151], v[196:199], v[94:97]
	v_mfma_f32_16x16x32_bf16 v[94:97], v[152:155], v[200:203], v[94:97]
	v_mfma_f32_16x16x32_bf16 v[78:81], v[148:151], v[204:207], v[78:81]
	v_mfma_f32_16x16x32_bf16 v[78:81], v[152:155], v[208:211], v[78:81]
	v_mfma_f32_16x16x32_bf16 v[66:69], v[156:159], v[204:207], v[66:69]
	v_mfma_f32_16x16x32_bf16 v[66:69], v[160:163], v[208:211], v[66:69]
	v_mfma_f32_16x16x32_bf16 v[86:89], v[156:159], v[196:199], v[86:89]
	v_mfma_f32_16x16x32_bf16 v[86:89], v[160:163], v[200:203], v[86:89]
	v_mfma_f32_16x16x32_bf16 v[102:105], v[156:159], v[188:191], v[102:105]
	v_mfma_f32_16x16x32_bf16 v[102:105], v[160:163], v[192:195], v[102:105]
	v_mfma_f32_16x16x32_bf16 v[114:117], v[156:159], v[180:183], v[114:117]
	v_mfma_f32_16x16x32_bf16 v[114:117], v[160:163], v[184:187], v[114:117]
	v_mfma_f32_16x16x32_bf16 v[126:129], v[164:167], v[180:183], v[126:129]
	v_mfma_f32_16x16x32_bf16 v[126:129], v[168:171], v[184:187], v[126:129]
	v_mfma_f32_16x16x32_bf16 v[106:109], v[164:167], v[188:191], v[106:109]
	v_mfma_f32_16x16x32_bf16 v[106:109], v[168:171], v[192:195], v[106:109]
	v_mfma_f32_16x16x32_bf16 v[90:93], v[164:167], v[196:199], v[90:93]
	v_mfma_f32_16x16x32_bf16 v[90:93], v[168:171], v[200:203], v[90:93]
	v_mfma_f32_16x16x32_bf16 v[74:77], v[164:167], v[204:207], v[74:77]
	v_mfma_f32_16x16x32_bf16 v[74:77], v[168:171], v[208:211], v[74:77]
	v_mfma_f32_16x16x32_bf16 v[70:73], v[172:175], v[204:207], v[70:73]
	v_mfma_f32_16x16x32_bf16 v[70:73], v[176:179], v[208:211], v[70:73]
	v_mfma_f32_16x16x32_bf16 v[82:85], v[172:175], v[196:199], v[82:85]
	v_mfma_f32_16x16x32_bf16 v[82:85], v[176:179], v[200:203], v[82:85]
	v_mfma_f32_16x16x32_bf16 v[98:101], v[172:175], v[188:191], v[98:101]
	v_mfma_f32_16x16x32_bf16 v[98:101], v[176:179], v[192:195], v[98:101]
	v_mfma_f32_16x16x32_bf16 v[122:125], v[172:175], v[180:183], v[122:125]
	v_mfma_f32_16x16x32_bf16 v[122:125], v[176:179], v[184:187], v[122:125]
	s_setprio 0
	s_barrier
	s_mov_b32 m0, s50
	s_or_b32 s77, s76, 0x80
	ds_read_b128 v[180:183], v141 offset:49152
	ds_read_b128 v[184:187], v141 offset:50176
	ds_read_b128 v[188:191], v141 offset:51200
	ds_read_b128 v[192:195], v141 offset:52224
	ds_read_b128 v[196:199], v141 offset:53248
	ds_read_b128 v[200:203], v141 offset:54272
	ds_read_b128 v[204:207], v141 offset:55296
	ds_read_b128 v[208:211], v141 offset:56320
	buffer_load_dwordx4 v138, s[16:19], s77 offen lds
	s_add_i32 s77, s76, 0x80080
	s_mov_b32 m0, s51
	s_add_i32 s74, s74, 0x80080
	buffer_load_dwordx4 v138, s[16:19], s77 offen lds
	s_add_i32 s77, s76, 0x100080
	s_mov_b32 m0, s54
	s_add_i32 s76, s76, 0x180080
	buffer_load_dwordx4 v138, s[16:19], s77 offen lds
	s_mov_b32 m0, s55
	s_nop 0
	buffer_load_dwordx4 v138, s[16:19], s76 offen lds
	s_mov_b32 m0, s52
	s_nop 0
	buffer_load_dwordx4 v137, s[12:15], s75 offen lds
	s_mov_b32 m0, s53
	s_nop 0
	buffer_load_dwordx4 v137, s[12:15], s74 offen lds
	s_waitcnt vmcnt(8) lgkmcnt(0)
	s_setprio 1
	v_mfma_f32_16x16x32_bf16 v[62:65], v[148:151], v[180:183], v[62:65]
	s_barrier
	v_mfma_f32_16x16x32_bf16 v[62:65], v[152:155], v[184:187], v[62:65]
	v_mfma_f32_16x16x32_bf16 v[46:49], v[148:151], v[188:191], v[46:49]
	v_mfma_f32_16x16x32_bf16 v[46:49], v[152:155], v[192:195], v[46:49]
	v_mfma_f32_16x16x32_bf16 v[30:33], v[148:151], v[196:199], v[30:33]
	v_mfma_f32_16x16x32_bf16 v[30:33], v[152:155], v[200:203], v[30:33]
	v_mfma_f32_16x16x32_bf16 v[14:17], v[148:151], v[204:207], v[14:17]
	v_mfma_f32_16x16x32_bf16 v[14:17], v[152:155], v[208:211], v[14:17]
	v_mfma_f32_16x16x32_bf16 v[6:9], v[156:159], v[204:207], v[6:9]
	v_mfma_f32_16x16x32_bf16 v[6:9], v[160:163], v[208:211], v[6:9]
	v_mfma_f32_16x16x32_bf16 v[22:25], v[156:159], v[196:199], v[22:25]
	v_mfma_f32_16x16x32_bf16 v[22:25], v[160:163], v[200:203], v[22:25]
	v_mfma_f32_16x16x32_bf16 v[38:41], v[156:159], v[188:191], v[38:41]
	v_mfma_f32_16x16x32_bf16 v[38:41], v[160:163], v[192:195], v[38:41]
	v_mfma_f32_16x16x32_bf16 v[54:57], v[156:159], v[180:183], v[54:57]
	v_mfma_f32_16x16x32_bf16 v[54:57], v[160:163], v[184:187], v[54:57]
	v_mfma_f32_16x16x32_bf16 v[58:61], v[164:167], v[180:183], v[58:61]
	v_mfma_f32_16x16x32_bf16 v[58:61], v[168:171], v[184:187], v[58:61]
	v_mfma_f32_16x16x32_bf16 v[42:45], v[164:167], v[188:191], v[42:45]
	v_mfma_f32_16x16x32_bf16 v[42:45], v[168:171], v[192:195], v[42:45]
	v_mfma_f32_16x16x32_bf16 v[26:29], v[164:167], v[196:199], v[26:29]
	v_mfma_f32_16x16x32_bf16 v[26:29], v[168:171], v[200:203], v[26:29]
	v_mfma_f32_16x16x32_bf16 v[10:13], v[164:167], v[204:207], v[10:13]
	v_mfma_f32_16x16x32_bf16 v[10:13], v[168:171], v[208:211], v[10:13]
	v_mfma_f32_16x16x32_bf16 v[2:5], v[172:175], v[204:207], v[2:5]
	v_mfma_f32_16x16x32_bf16 v[2:5], v[176:179], v[208:211], v[2:5]
	v_mfma_f32_16x16x32_bf16 v[18:21], v[172:175], v[196:199], v[18:21]
	v_mfma_f32_16x16x32_bf16 v[18:21], v[176:179], v[200:203], v[18:21]
	v_mfma_f32_16x16x32_bf16 v[34:37], v[172:175], v[188:191], v[34:37]
	v_mfma_f32_16x16x32_bf16 v[34:37], v[176:179], v[192:195], v[34:37]
	v_mfma_f32_16x16x32_bf16 v[50:53], v[172:175], v[180:183], v[50:53]
	v_mfma_f32_16x16x32_bf16 v[50:53], v[176:179], v[184:187], v[50:53]
	s_setprio 0
	s_barrier
	s_add_i32 s73, s73, 2
	s_addk_i32 s71, 0x100
	s_addk_i32 s72, 0x100
	s_cmp_ge_i32 s73, s3
	s_cbranch_scc0 .LBB0_642
	s_and_b64 vcc, exec, s[42:43]
	s_cbranch_vccz .LBB0_645

.LBB0_799:
	ds_read_b128 v[134:137], v210
	ds_read_b128 v[138:141], v210 offset:1024
	ds_read_b128 v[142:145], v210 offset:2048
	ds_read_b128 v[148:151], v210 offset:3072
	ds_read_b128 v[152:155], v211
	ds_read_b128 v[156:159], v211 offset:1024
	ds_read_b128 v[160:163], v211 offset:2048
	ds_read_b128 v[164:167], v211 offset:3072
	s_add_i32 s18, s77, 0xffbf8080
	s_cmp_eq_u32 s62, s79
	s_cselect_b32 s80, s6, s18
	s_cselect_b32 s82, s7, s78
	s_or_b32 s81, s80, 0x80
	s_add_i32 s18, s77, 0xffea8000
	s_mov_b32 m0, s63
	ds_read_b128 v[168:171], v212
	ds_read_b128 v[172:175], v212 offset:1024
	ds_read_b128 v[176:179], v212 offset:2048
	ds_read_b128 v[180:183], v212 offset:3072
	ds_read_b128 v[184:187], v212 offset:4096
	ds_read_b128 v[188:191], v212 offset:5120
	ds_read_b128 v[192:195], v212 offset:6144
	ds_read_b128 v[196:199], v212 offset:7168
	buffer_load_dwordx4 v208, s[12:15], s18 offen lds
	s_mov_b32 m0, s66
	s_nop 0
	buffer_load_dwordx4 v208, s[12:15], s77 offen lds
	s_waitcnt vmcnt(8) lgkmcnt(0)
	s_setprio 1
	v_mfma_f32_16x16x32_bf16 v[126:129], v[134:137], v[168:171], v[126:129]
	s_barrier
	v_mfma_f32_16x16x32_bf16 v[126:129], v[138:141], v[172:175], v[126:129]
	v_mfma_f32_16x16x32_bf16 v[118:121], v[134:137], v[176:179], v[118:121]
	v_mfma_f32_16x16x32_bf16 v[118:121], v[138:141], v[180:183], v[118:121]
	v_mfma_f32_16x16x32_bf16 v[106:109], v[134:137], v[184:187], v[106:109]
	v_mfma_f32_16x16x32_bf16 v[106:109], v[138:141], v[188:191], v[106:109]
	v_mfma_f32_16x16x32_bf16 v[90:93], v[134:137], v[192:195], v[90:93]
	v_mfma_f32_16x16x32_bf16 v[90:93], v[138:141], v[196:199], v[90:93]
	v_mfma_f32_16x16x32_bf16 v[82:85], v[142:145], v[192:195], v[82:85]
	v_mfma_f32_16x16x32_bf16 v[82:85], v[148:151], v[196:199], v[82:85]
	v_mfma_f32_16x16x32_bf16 v[98:101], v[142:145], v[184:187], v[98:101]
	v_mfma_f32_16x16x32_bf16 v[98:101], v[148:151], v[188:191], v[98:101]
	v_mfma_f32_16x16x32_bf16 v[114:117], v[142:145], v[176:179], v[114:117]
	v_mfma_f32_16x16x32_bf16 v[114:117], v[148:151], v[180:183], v[114:117]
	v_mfma_f32_16x16x32_bf16 v[122:125], v[142:145], v[168:171], v[122:125]
	v_mfma_f32_16x16x32_bf16 v[122:125], v[148:151], v[172:175], v[122:125]
	v_mfma_f32_16x16x32_bf16 v[110:113], v[152:155], v[168:171], v[110:113]
	v_mfma_f32_16x16x32_bf16 v[110:113], v[156:159], v[172:175], v[110:113]
	v_mfma_f32_16x16x32_bf16 v[94:97], v[152:155], v[176:179], v[94:97]
	v_mfma_f32_16x16x32_bf16 v[94:97], v[156:159], v[180:183], v[94:97]
	v_mfma_f32_16x16x32_bf16 v[78:81], v[152:155], v[184:187], v[78:81]
	v_mfma_f32_16x16x32_bf16 v[78:81], v[156:159], v[188:191], v[78:81]
	v_mfma_f32_16x16x32_bf16 v[70:73], v[152:155], v[192:195], v[70:73]
	v_mfma_f32_16x16x32_bf16 v[70:73], v[156:159], v[196:199], v[70:73]
	v_mfma_f32_16x16x32_bf16 v[66:69], v[160:163], v[192:195], v[66:69]
	v_mfma_f32_16x16x32_bf16 v[66:69], v[164:167], v[196:199], v[66:69]
	v_mfma_f32_16x16x32_bf16 v[74:77], v[160:163], v[184:187], v[74:77]
	v_mfma_f32_16x16x32_bf16 v[74:77], v[164:167], v[188:191], v[74:77]
	v_mfma_f32_16x16x32_bf16 v[86:89], v[160:163], v[176:179], v[86:89]
	v_mfma_f32_16x16x32_bf16 v[86:89], v[164:167], v[180:183], v[86:89]
	v_mfma_f32_16x16x32_bf16 v[102:105], v[160:163], v[168:171], v[102:105]
	v_mfma_f32_16x16x32_bf16 v[102:105], v[164:167], v[172:175], v[102:105]
	s_setprio 0
	s_barrier
	s_mov_b32 m0, s25
	s_mov_b32 s18, s14
	s_mov_b32 s19, s15
	ds_read_b128 v[168:171], v212 offset:16384
	ds_read_b128 v[172:175], v212 offset:17408
	ds_read_b128 v[176:179], v212 offset:18432
	ds_read_b128 v[180:183], v212 offset:19456
	ds_read_b128 v[184:187], v212 offset:20480
	ds_read_b128 v[188:191], v212 offset:21504
	ds_read_b128 v[192:195], v212 offset:22528
	ds_read_b128 v[196:199], v212 offset:23552
	buffer_load_dwordx4 v209, s[16:19], s82 offen lds
	s_mov_b32 m0, s27
	s_add_i32 s83, s82, 0x158000
	buffer_load_dwordx4 v209, s[16:19], s83 offen lds
	s_mov_b32 m0, s30
	s_add_i32 s83, s82, 0x2b0000
	buffer_load_dwordx4 v209, s[16:19], s83 offen lds
	s_mov_b32 m0, s31
	s_add_i32 s83, s82, 0x408000
	buffer_load_dwordx4 v209, s[16:19], s83 offen lds
	s_mov_b32 m0, s21
	s_add_i32 s83, s80, 0x158000
	buffer_load_dwordx4 v208, s[12:15], s80 offen lds
	s_mov_b32 m0, s48
	s_nop 0
	buffer_load_dwordx4 v208, s[12:15], s83 offen lds
	s_waitcnt vmcnt(8) lgkmcnt(0)
	s_setprio 1
	v_mfma_f32_16x16x32_bf16 v[62:65], v[134:137], v[168:171], v[62:65]
	s_barrier
	v_mfma_f32_16x16x32_bf16 v[62:65], v[138:141], v[172:175], v[62:65]
	v_mfma_f32_16x16x32_bf16 v[54:57], v[134:137], v[176:179], v[54:57]
	v_mfma_f32_16x16x32_bf16 v[54:57], v[138:141], v[180:183], v[54:57]
	v_mfma_f32_16x16x32_bf16 v[42:45], v[134:137], v[184:187], v[42:45]
	v_mfma_f32_16x16x32_bf16 v[42:45], v[138:141], v[188:191], v[42:45]
	v_mfma_f32_16x16x32_bf16 v[26:29], v[134:137], v[192:195], v[26:29]
	v_mfma_f32_16x16x32_bf16 v[26:29], v[138:141], v[196:199], v[26:29]
	v_mfma_f32_16x16x32_bf16 v[18:21], v[142:145], v[192:195], v[18:21]
	v_mfma_f32_16x16x32_bf16 v[18:21], v[148:151], v[196:199], v[18:21]
	v_mfma_f32_16x16x32_bf16 v[34:37], v[142:145], v[184:187], v[34:37]
	v_mfma_f32_16x16x32_bf16 v[34:37], v[148:151], v[188:191], v[34:37]
	v_mfma_f32_16x16x32_bf16 v[50:53], v[142:145], v[176:179], v[50:53]
	v_mfma_f32_16x16x32_bf16 v[50:53], v[148:151], v[180:183], v[50:53]
	v_mfma_f32_16x16x32_bf16 v[58:61], v[142:145], v[168:171], v[58:61]
	v_mfma_f32_16x16x32_bf16 v[58:61], v[148:151], v[172:175], v[58:61]
	v_mfma_f32_16x16x32_bf16 v[46:49], v[152:155], v[168:171], v[46:49]
	v_mfma_f32_16x16x32_bf16 v[46:49], v[156:159], v[172:175], v[46:49]
	v_mfma_f32_16x16x32_bf16 v[30:33], v[152:155], v[176:179], v[30:33]
	v_mfma_f32_16x16x32_bf16 v[30:33], v[156:159], v[180:183], v[30:33]
	v_mfma_f32_16x16x32_bf16 v[14:17], v[152:155], v[184:187], v[14:17]
	v_mfma_f32_16x16x32_bf16 v[14:17], v[156:159], v[188:191], v[14:17]
	v_mfma_f32_16x16x32_bf16 v[6:9], v[152:155], v[192:195], v[6:9]
	v_mfma_f32_16x16x32_bf16 v[6:9], v[156:159], v[196:199], v[6:9]
	v_mfma_f32_16x16x32_bf16 v[2:5], v[160:163], v[192:195], v[2:5]
	v_mfma_f32_16x16x32_bf16 v[2:5], v[164:167], v[196:199], v[2:5]
	v_mfma_f32_16x16x32_bf16 v[10:13], v[160:163], v[184:187], v[10:13]
	v_mfma_f32_16x16x32_bf16 v[10:13], v[164:167], v[188:191], v[10:13]
	v_mfma_f32_16x16x32_bf16 v[22:25], v[160:163], v[176:179], v[22:25]
	v_mfma_f32_16x16x32_bf16 v[22:25], v[164:167], v[180:183], v[22:25]
	v_mfma_f32_16x16x32_bf16 v[38:41], v[160:163], v[168:171], v[38:41]
	v_mfma_f32_16x16x32_bf16 v[38:41], v[164:167], v[172:175], v[38:41]
	s_setprio 0
	s_barrier
	ds_read_b128 v[134:137], v213
	ds_read_b128 v[138:141], v213 offset:1024
	ds_read_b128 v[142:145], v213 offset:2048
	ds_read_b128 v[148:151], v213 offset:3072
	ds_read_b128 v[152:155], v214
	ds_read_b128 v[156:159], v214 offset:1024
	ds_read_b128 v[160:163], v214 offset:2048
	ds_read_b128 v[164:167], v214 offset:3072
	s_mov_b32 m0, s49
	s_add_i32 s83, s80, 0x2b0000
	ds_read_b128 v[168:171], v212 offset:32768
	ds_read_b128 v[172:175], v212 offset:33792
	ds_read_b128 v[176:179], v212 offset:34816
	ds_read_b128 v[180:183], v212 offset:35840
	ds_read_b128 v[184:187], v212 offset:36864
	ds_read_b128 v[188:191], v212 offset:37888
	ds_read_b128 v[192:195], v212 offset:38912
	ds_read_b128 v[196:199], v212 offset:39936
	buffer_load_dwordx4 v208, s[12:15], s83 offen lds
	s_mov_b32 m0, s50
	s_add_i32 s83, s80, 0x408000
	buffer_load_dwordx4 v208, s[12:15], s83 offen lds
	s_waitcnt vmcnt(8) lgkmcnt(0)
	s_setprio 1
	v_mfma_f32_16x16x32_bf16 v[126:129], v[134:137], v[168:171], v[126:129]
	s_barrier
	v_mfma_f32_16x16x32_bf16 v[126:129], v[138:141], v[172:175], v[126:129]
	v_mfma_f32_16x16x32_bf16 v[118:121], v[134:137], v[176:179], v[118:121]
	v_mfma_f32_16x16x32_bf16 v[118:121], v[138:141], v[180:183], v[118:121]
	v_mfma_f32_16x16x32_bf16 v[106:109], v[134:137], v[184:187], v[106:109]
	v_mfma_f32_16x16x32_bf16 v[106:109], v[138:141], v[188:191], v[106:109]
	v_mfma_f32_16x16x32_bf16 v[90:93], v[134:137], v[192:195], v[90:93]
	v_mfma_f32_16x16x32_bf16 v[90:93], v[138:141], v[196:199], v[90:93]
	v_mfma_f32_16x16x32_bf16 v[82:85], v[142:145], v[192:195], v[82:85]
	v_mfma_f32_16x16x32_bf16 v[82:85], v[148:151], v[196:199], v[82:85]
	v_mfma_f32_16x16x32_bf16 v[98:101], v[142:145], v[184:187], v[98:101]
	v_mfma_f32_16x16x32_bf16 v[98:101], v[148:151], v[188:191], v[98:101]
	v_mfma_f32_16x16x32_bf16 v[114:117], v[142:145], v[176:179], v[114:117]
	v_mfma_f32_16x16x32_bf16 v[114:117], v[148:151], v[180:183], v[114:117]
	v_mfma_f32_16x16x32_bf16 v[122:125], v[142:145], v[168:171], v[122:125]
	v_mfma_f32_16x16x32_bf16 v[122:125], v[148:151], v[172:175], v[122:125]
	v_mfma_f32_16x16x32_bf16 v[110:113], v[152:155], v[168:171], v[110:113]
	v_mfma_f32_16x16x32_bf16 v[110:113], v[156:159], v[172:175], v[110:113]
	v_mfma_f32_16x16x32_bf16 v[94:97], v[152:155], v[176:179], v[94:97]
	v_mfma_f32_16x16x32_bf16 v[94:97], v[156:159], v[180:183], v[94:97]
	v_mfma_f32_16x16x32_bf16 v[78:81], v[152:155], v[184:187], v[78:81]
	v_mfma_f32_16x16x32_bf16 v[78:81], v[156:159], v[188:191], v[78:81]
	v_mfma_f32_16x16x32_bf16 v[70:73], v[152:155], v[192:195], v[70:73]
	v_mfma_f32_16x16x32_bf16 v[70:73], v[156:159], v[196:199], v[70:73]
	v_mfma_f32_16x16x32_bf16 v[66:69], v[160:163], v[192:195], v[66:69]
	v_mfma_f32_16x16x32_bf16 v[66:69], v[164:167], v[196:199], v[66:69]
	v_mfma_f32_16x16x32_bf16 v[74:77], v[160:163], v[184:187], v[74:77]
	v_mfma_f32_16x16x32_bf16 v[74:77], v[164:167], v[188:191], v[74:77]
	v_mfma_f32_16x16x32_bf16 v[86:89], v[160:163], v[176:179], v[86:89]
	v_mfma_f32_16x16x32_bf16 v[86:89], v[164:167], v[180:183], v[86:89]
	v_mfma_f32_16x16x32_bf16 v[102:105], v[160:163], v[168:171], v[102:105]
	v_mfma_f32_16x16x32_bf16 v[102:105], v[164:167], v[172:175], v[102:105]
	s_setprio 0
	s_barrier
	s_mov_b32 m0, s54
	s_or_b32 s83, s82, 0x80
	ds_read_b128 v[168:171], v212 offset:49152
	ds_read_b128 v[172:175], v212 offset:50176
	ds_read_b128 v[176:179], v212 offset:51200
	ds_read_b128 v[180:183], v212 offset:52224
	ds_read_b128 v[184:187], v212 offset:53248
	ds_read_b128 v[188:191], v212 offset:54272
	ds_read_b128 v[192:195], v212 offset:55296
	ds_read_b128 v[196:199], v212 offset:56320
	buffer_load_dwordx4 v209, s[16:19], s83 offen lds
	s_add_i32 s83, s82, 0x158080
	s_mov_b32 m0, s55
	s_add_i32 s80, s80, 0x158080
	buffer_load_dwordx4 v209, s[16:19], s83 offen lds
	s_add_i32 s83, s82, 0x2b0080
	s_mov_b32 m0, s58
	s_add_i32 s82, s82, 0x408080
	buffer_load_dwordx4 v209, s[16:19], s83 offen lds
	s_mov_b32 m0, s59
	s_nop 0
	buffer_load_dwordx4 v209, s[16:19], s82 offen lds
	s_mov_b32 m0, s56
	s_nop 0
	buffer_load_dwordx4 v208, s[12:15], s81 offen lds
	s_mov_b32 m0, s57
	s_nop 0
	buffer_load_dwordx4 v208, s[12:15], s80 offen lds
	s_waitcnt vmcnt(8) lgkmcnt(0)
	s_setprio 1
	v_mfma_f32_16x16x32_bf16 v[62:65], v[134:137], v[168:171], v[62:65]
	s_barrier
	v_mfma_f32_16x16x32_bf16 v[62:65], v[138:141], v[172:175], v[62:65]
	v_mfma_f32_16x16x32_bf16 v[54:57], v[134:137], v[176:179], v[54:57]
	v_mfma_f32_16x16x32_bf16 v[54:57], v[138:141], v[180:183], v[54:57]
	v_mfma_f32_16x16x32_bf16 v[42:45], v[134:137], v[184:187], v[42:45]
	v_mfma_f32_16x16x32_bf16 v[42:45], v[138:141], v[188:191], v[42:45]
	v_mfma_f32_16x16x32_bf16 v[26:29], v[134:137], v[192:195], v[26:29]
	v_mfma_f32_16x16x32_bf16 v[26:29], v[138:141], v[196:199], v[26:29]
	v_mfma_f32_16x16x32_bf16 v[18:21], v[142:145], v[192:195], v[18:21]
	v_mfma_f32_16x16x32_bf16 v[18:21], v[148:151], v[196:199], v[18:21]
	v_mfma_f32_16x16x32_bf16 v[34:37], v[142:145], v[184:187], v[34:37]
	v_mfma_f32_16x16x32_bf16 v[34:37], v[148:151], v[188:191], v[34:37]
	v_mfma_f32_16x16x32_bf16 v[50:53], v[142:145], v[176:179], v[50:53]
	v_mfma_f32_16x16x32_bf16 v[50:53], v[148:151], v[180:183], v[50:53]
	v_mfma_f32_16x16x32_bf16 v[58:61], v[142:145], v[168:171], v[58:61]
	v_mfma_f32_16x16x32_bf16 v[58:61], v[148:151], v[172:175], v[58:61]
	v_mfma_f32_16x16x32_bf16 v[46:49], v[152:155], v[168:171], v[46:49]
	v_mfma_f32_16x16x32_bf16 v[46:49], v[156:159], v[172:175], v[46:49]
	v_mfma_f32_16x16x32_bf16 v[30:33], v[152:155], v[176:179], v[30:33]
	v_mfma_f32_16x16x32_bf16 v[30:33], v[156:159], v[180:183], v[30:33]
	v_mfma_f32_16x16x32_bf16 v[14:17], v[152:155], v[184:187], v[14:17]
	v_mfma_f32_16x16x32_bf16 v[14:17], v[156:159], v[188:191], v[14:17]
	v_mfma_f32_16x16x32_bf16 v[6:9], v[152:155], v[192:195], v[6:9]
	v_mfma_f32_16x16x32_bf16 v[6:9], v[156:159], v[196:199], v[6:9]
	v_mfma_f32_16x16x32_bf16 v[2:5], v[160:163], v[192:195], v[2:5]
	v_mfma_f32_16x16x32_bf16 v[2:5], v[164:167], v[196:199], v[2:5]
	v_mfma_f32_16x16x32_bf16 v[10:13], v[160:163], v[184:187], v[10:13]
	v_mfma_f32_16x16x32_bf16 v[10:13], v[164:167], v[188:191], v[10:13]
	v_mfma_f32_16x16x32_bf16 v[22:25], v[160:163], v[176:179], v[22:25]
	v_mfma_f32_16x16x32_bf16 v[22:25], v[164:167], v[180:183], v[22:25]
	v_mfma_f32_16x16x32_bf16 v[38:41], v[160:163], v[168:171], v[38:41]
	v_mfma_f32_16x16x32_bf16 v[38:41], v[164:167], v[172:175], v[38:41]
	s_setprio 0
	s_barrier
	s_add_i32 s79, s79, 2
	s_addk_i32 s77, 0x100
	s_addk_i32 s78, 0x100
	s_cmp_ge_i32 s79, s3
	s_cbranch_scc0 .LBB0_799
	v_pk_mul_f32 v[184:185], v[128:129], 0.5 op_sel_hi:[1,0]
	v_pk_mul_f32 v[186:187], v[126:127], 0.5 op_sel_hi:[1,0]
	v_pk_mul_f32 v[188:189], v[124:125], 0.5 op_sel_hi:[1,0]
	v_pk_mul_f32 v[190:191], v[122:123], 0.5 op_sel_hi:[1,0]
	v_pk_mul_f32 v[198:199], v[112:113], 0.5 op_sel_hi:[1,0]
	v_pk_mul_f32 v[196:197], v[110:111], 0.5 op_sel_hi:[1,0]
	v_pk_mul_f32 v[194:195], v[104:105], 0.5 op_sel_hi:[1,0]
	v_pk_mul_f32 v[192:193], v[102:103], 0.5 op_sel_hi:[1,0]
	v_pk_mul_f32 v[182:183], v[120:121], 0.5 op_sel_hi:[1,0]
	v_pk_mul_f32 v[180:181], v[118:119], 0.5 op_sel_hi:[1,0]
	v_pk_mul_f32 v[178:179], v[116:117], 0.5 op_sel_hi:[1,0]
	v_pk_mul_f32 v[176:177], v[114:115], 0.5 op_sel_hi:[1,0]
	v_pk_mul_f32 v[172:173], v[96:97], 0.5 op_sel_hi:[1,0]
	v_pk_mul_f32 v[170:171], v[94:95], 0.5 op_sel_hi:[1,0]
	v_pk_mul_f32 v[168:169], v[88:89], 0.5 op_sel_hi:[1,0]
	v_pk_mul_f32 v[166:167], v[86:87], 0.5 op_sel_hi:[1,0]
	v_pk_mul_f32 v[164:165], v[108:109], 0.5 op_sel_hi:[1,0]
	v_pk_mul_f32 v[162:163], v[106:107], 0.5 op_sel_hi:[1,0]
	v_pk_mul_f32 v[160:161], v[100:101], 0.5 op_sel_hi:[1,0]
	v_pk_mul_f32 v[158:159], v[98:99], 0.5 op_sel_hi:[1,0]
	v_pk_mul_f32 v[156:157], v[80:81], 0.5 op_sel_hi:[1,0]
	v_pk_mul_f32 v[154:155], v[78:79], 0.5 op_sel_hi:[1,0]
	v_pk_mul_f32 v[152:153], v[76:77], 0.5 op_sel_hi:[1,0]
	v_pk_mul_f32 v[150:151], v[74:75], 0.5 op_sel_hi:[1,0]
	v_pk_mul_f32 v[144:145], v[92:93], 0.5 op_sel_hi:[1,0]
	v_pk_mul_f32 v[142:143], v[90:91], 0.5 op_sel_hi:[1,0]
	v_pk_mul_f32 v[140:141], v[84:85], 0.5 op_sel_hi:[1,0]
	v_pk_mul_f32 v[138:139], v[82:83], 0.5 op_sel_hi:[1,0]
	v_pk_mul_f32 v[136:137], v[72:73], 0.5 op_sel_hi:[1,0]
	v_pk_mul_f32 v[134:135], v[70:71], 0.5 op_sel_hi:[1,0]
	v_pk_mul_f32 v[128:129], v[68:69], 0.5 op_sel_hi:[1,0]
	v_pk_mul_f32 v[126:127], v[66:67], 0.5 op_sel_hi:[1,0]
	v_pk_mul_f32 v[122:123], v[64:65], 0.5 op_sel_hi:[1,0]
	v_pk_mul_f32 v[120:121], v[62:63], 0.5 op_sel_hi:[1,0]
	v_pk_mul_f32 v[118:119], v[60:61], 0.5 op_sel_hi:[1,0]
	v_pk_mul_f32 v[116:117], v[58:59], 0.5 op_sel_hi:[1,0]
	v_pk_mul_f32 v[112:113], v[48:49], 0.5 op_sel_hi:[1,0]
	v_pk_mul_f32 v[110:111], v[46:47], 0.5 op_sel_hi:[1,0]
	v_pk_mul_f32 v[108:109], v[40:41], 0.5 op_sel_hi:[1,0]
	v_pk_mul_f32 v[106:107], v[38:39], 0.5 op_sel_hi:[1,0]
	v_pk_mul_f32 v[104:105], v[56:57], 0.5 op_sel_hi:[1,0]
	v_pk_mul_f32 v[102:103], v[54:55], 0.5 op_sel_hi:[1,0]
	v_pk_mul_f32 v[100:101], v[52:53], 0.5 op_sel_hi:[1,0]
	v_pk_mul_f32 v[98:99], v[50:51], 0.5 op_sel_hi:[1,0]
	v_pk_mul_f32 v[96:97], v[32:33], 0.5 op_sel_hi:[1,0]
	v_pk_mul_f32 v[94:95], v[30:31], 0.5 op_sel_hi:[1,0]
	v_pk_mul_f32 v[92:93], v[24:25], 0.5 op_sel_hi:[1,0]
	v_pk_mul_f32 v[90:91], v[22:23], 0.5 op_sel_hi:[1,0]
	v_pk_mul_f32 v[88:89], v[44:45], 0.5 op_sel_hi:[1,0]
	v_pk_mul_f32 v[86:87], v[42:43], 0.5 op_sel_hi:[1,0]
	v_pk_mul_f32 v[84:85], v[36:37], 0.5 op_sel_hi:[1,0]
	v_pk_mul_f32 v[82:83], v[34:35], 0.5 op_sel_hi:[1,0]
	v_pk_mul_f32 v[80:81], v[16:17], 0.5 op_sel_hi:[1,0]
	v_pk_mul_f32 v[78:79], v[14:15], 0.5 op_sel_hi:[1,0]
	v_pk_mul_f32 v[76:77], v[12:13], 0.5 op_sel_hi:[1,0]
	v_pk_mul_f32 v[74:75], v[10:11], 0.5 op_sel_hi:[1,0]
	v_pk_mul_f32 v[72:73], v[28:29], 0.5 op_sel_hi:[1,0]
	v_pk_mul_f32 v[70:71], v[26:27], 0.5 op_sel_hi:[1,0]
	v_pk_mul_f32 v[68:69], v[20:21], 0.5 op_sel_hi:[1,0]
	v_pk_mul_f32 v[66:67], v[18:19], 0.5 op_sel_hi:[1,0]
	v_pk_mul_f32 v[64:65], v[8:9], 0.5 op_sel_hi:[1,0]
	v_pk_mul_f32 v[62:63], v[6:7], 0.5 op_sel_hi:[1,0]
	v_pk_mul_f32 v[60:61], v[4:5], 0.5 op_sel_hi:[1,0]
	v_pk_mul_f32 v[58:59], v[2:3], 0.5 op_sel_hi:[1,0]
	s_and_b64 vcc, exec, s[38:39]
	s_cbranch_vccz .LBB0_802

.LBB0_892:
	ds_read_b128 v[130:133], v172
	ds_read_b128 v[134:137], v172 offset:1024
	ds_read_b128 v[148:151], v172 offset:2048
	ds_read_b128 v[152:155], v172 offset:3072
	ds_read_b128 v[156:159], v173
	ds_read_b128 v[160:163], v173 offset:1024
	ds_read_b128 v[164:167], v173 offset:2048
	ds_read_b128 v[180:183], v173 offset:3072
	s_add_i32 s18, s8, 0xffe80080
	s_cmp_eq_u32 s77, s52
	s_cselect_b32 s53, s6, s18
	s_cselect_b32 s58, s7, s9
	s_or_b32 s57, s53, 0x80
	s_add_i32 s18, s8, 0xfff80000
	s_mov_b32 m0, s78
	ds_read_b128 v[184:187], v174
	ds_read_b128 v[188:191], v174 offset:1024
	ds_read_b128 v[192:195], v174 offset:2048
	ds_read_b128 v[196:199], v174 offset:3072
	ds_read_b128 v[200:203], v174 offset:4096
	ds_read_b128 v[204:207], v174 offset:5120
	ds_read_b128 v[208:211], v174 offset:6144
	ds_read_b128 v[212:215], v174 offset:7168
	buffer_load_dwordx4 v170, s[12:15], s18 offen lds
	s_mov_b32 m0, s79
	s_nop 0
	buffer_load_dwordx4 v170, s[12:15], s8 offen lds
	s_waitcnt vmcnt(8) lgkmcnt(0)
	s_setprio 1
	v_mfma_f32_16x16x32_bf16 v[126:129], v[130:133], v[184:187], v[126:129]
	s_barrier
	v_mfma_f32_16x16x32_bf16 v[126:129], v[134:137], v[188:191], v[126:129]
	v_mfma_f32_16x16x32_bf16 v[110:113], v[130:133], v[192:195], v[110:113]
	v_mfma_f32_16x16x32_bf16 v[110:113], v[134:137], v[196:199], v[110:113]
	v_mfma_f32_16x16x32_bf16 v[94:97], v[130:133], v[200:203], v[94:97]
	v_mfma_f32_16x16x32_bf16 v[94:97], v[134:137], v[204:207], v[94:97]
	v_mfma_f32_16x16x32_bf16 v[78:81], v[130:133], v[208:211], v[78:81]
	v_mfma_f32_16x16x32_bf16 v[78:81], v[134:137], v[212:215], v[78:81]
	v_mfma_f32_16x16x32_bf16 v[70:73], v[148:151], v[208:211], v[70:73]
	v_mfma_f32_16x16x32_bf16 v[70:73], v[152:155], v[212:215], v[70:73]
	v_mfma_f32_16x16x32_bf16 v[90:93], v[148:151], v[200:203], v[90:93]
	v_mfma_f32_16x16x32_bf16 v[90:93], v[152:155], v[204:207], v[90:93]
	v_mfma_f32_16x16x32_bf16 v[102:105], v[148:151], v[192:195], v[102:105]
	v_mfma_f32_16x16x32_bf16 v[102:105], v[152:155], v[196:199], v[102:105]
	v_mfma_f32_16x16x32_bf16 v[118:121], v[148:151], v[184:187], v[118:121]
	v_mfma_f32_16x16x32_bf16 v[118:121], v[152:155], v[188:191], v[118:121]
	v_mfma_f32_16x16x32_bf16 v[122:125], v[156:159], v[184:187], v[122:125]
	v_mfma_f32_16x16x32_bf16 v[122:125], v[160:163], v[188:191], v[122:125]
	v_mfma_f32_16x16x32_bf16 v[106:109], v[156:159], v[192:195], v[106:109]
	v_mfma_f32_16x16x32_bf16 v[106:109], v[160:163], v[196:199], v[106:109]
	v_mfma_f32_16x16x32_bf16 v[86:89], v[156:159], v[200:203], v[86:89]
	v_mfma_f32_16x16x32_bf16 v[86:89], v[160:163], v[204:207], v[86:89]
	v_mfma_f32_16x16x32_bf16 v[74:77], v[156:159], v[208:211], v[74:77]
	v_mfma_f32_16x16x32_bf16 v[74:77], v[160:163], v[212:215], v[74:77]
	v_mfma_f32_16x16x32_bf16 v[66:69], v[164:167], v[208:211], v[66:69]
	v_mfma_f32_16x16x32_bf16 v[66:69], v[180:183], v[212:215], v[66:69]
	v_mfma_f32_16x16x32_bf16 v[82:85], v[164:167], v[200:203], v[82:85]
	v_mfma_f32_16x16x32_bf16 v[82:85], v[180:183], v[204:207], v[82:85]
	v_mfma_f32_16x16x32_bf16 v[98:101], v[164:167], v[192:195], v[98:101]
	v_mfma_f32_16x16x32_bf16 v[98:101], v[180:183], v[196:199], v[98:101]
	v_mfma_f32_16x16x32_bf16 v[114:117], v[164:167], v[184:187], v[114:117]
	v_mfma_f32_16x16x32_bf16 v[114:117], v[180:183], v[188:191], v[114:117]
	s_setprio 0
	s_barrier
	s_mov_b32 m0, s27
	s_mov_b32 s18, s14
	s_mov_b32 s19, s15
	ds_read_b128 v[184:187], v174 offset:16384
	ds_read_b128 v[188:191], v174 offset:17408
	ds_read_b128 v[192:195], v174 offset:18432
	ds_read_b128 v[196:199], v174 offset:19456
	ds_read_b128 v[200:203], v174 offset:20480
	ds_read_b128 v[204:207], v174 offset:21504
	ds_read_b128 v[208:211], v174 offset:22528
	ds_read_b128 v[212:215], v174 offset:23552
	buffer_load_dwordx4 v171, s[16:19], s58 offen lds
	s_mov_b32 m0, s60
	s_add_i32 s59, s58, 0x80000
	buffer_load_dwordx4 v171, s[16:19], s59 offen lds
	s_mov_b32 m0, s61
	s_add_i32 s59, s58, 0x100000
	buffer_load_dwordx4 v171, s[16:19], s59 offen lds
	s_mov_b32 m0, s62
	s_add_i32 s59, s58, 0x180000
	buffer_load_dwordx4 v171, s[16:19], s59 offen lds
	s_mov_b32 m0, s25
	s_add_i32 s59, s53, 0x80000
	buffer_load_dwordx4 v170, s[12:15], s53 offen lds
	s_mov_b32 m0, s63
	s_nop 0
	buffer_load_dwordx4 v170, s[12:15], s59 offen lds
	s_waitcnt vmcnt(8) lgkmcnt(0)
	s_setprio 1
	v_mfma_f32_16x16x32_bf16 v[62:65], v[130:133], v[184:187], v[62:65]
	s_barrier
	v_mfma_f32_16x16x32_bf16 v[62:65], v[134:137], v[188:191], v[62:65]
	v_mfma_f32_16x16x32_bf16 v[46:49], v[130:133], v[192:195], v[46:49]
	v_mfma_f32_16x16x32_bf16 v[46:49], v[134:137], v[196:199], v[46:49]
	v_mfma_f32_16x16x32_bf16 v[30:33], v[130:133], v[200:203], v[30:33]
	v_mfma_f32_16x16x32_bf16 v[30:33], v[134:137], v[204:207], v[30:33]
	v_mfma_f32_16x16x32_bf16 v[14:17], v[130:133], v[208:211], v[14:17]
	v_mfma_f32_16x16x32_bf16 v[14:17], v[134:137], v[212:215], v[14:17]
	v_mfma_f32_16x16x32_bf16 v[6:9], v[148:151], v[208:211], v[6:9]
	v_mfma_f32_16x16x32_bf16 v[6:9], v[152:155], v[212:215], v[6:9]
	v_mfma_f32_16x16x32_bf16 v[22:25], v[148:151], v[200:203], v[22:25]
	v_mfma_f32_16x16x32_bf16 v[22:25], v[152:155], v[204:207], v[22:25]
	v_mfma_f32_16x16x32_bf16 v[38:41], v[148:151], v[192:195], v[38:41]
	v_mfma_f32_16x16x32_bf16 v[38:41], v[152:155], v[196:199], v[38:41]
	v_mfma_f32_16x16x32_bf16 v[54:57], v[148:151], v[184:187], v[54:57]
	v_mfma_f32_16x16x32_bf16 v[54:57], v[152:155], v[188:191], v[54:57]
	v_mfma_f32_16x16x32_bf16 v[58:61], v[156:159], v[184:187], v[58:61]
	v_mfma_f32_16x16x32_bf16 v[58:61], v[160:163], v[188:191], v[58:61]
	v_mfma_f32_16x16x32_bf16 v[42:45], v[156:159], v[192:195], v[42:45]
	v_mfma_f32_16x16x32_bf16 v[42:45], v[160:163], v[196:199], v[42:45]
	v_mfma_f32_16x16x32_bf16 v[26:29], v[156:159], v[200:203], v[26:29]
	v_mfma_f32_16x16x32_bf16 v[26:29], v[160:163], v[204:207], v[26:29]
	v_mfma_f32_16x16x32_bf16 v[10:13], v[156:159], v[208:211], v[10:13]
	v_mfma_f32_16x16x32_bf16 v[10:13], v[160:163], v[212:215], v[10:13]
	v_mfma_f32_16x16x32_bf16 v[2:5], v[164:167], v[208:211], v[2:5]
	v_mfma_f32_16x16x32_bf16 v[2:5], v[180:183], v[212:215], v[2:5]
	v_mfma_f32_16x16x32_bf16 v[18:21], v[164:167], v[200:203], v[18:21]
	v_mfma_f32_16x16x32_bf16 v[18:21], v[180:183], v[204:207], v[18:21]
	v_mfma_f32_16x16x32_bf16 v[34:37], v[164:167], v[192:195], v[34:37]
	v_mfma_f32_16x16x32_bf16 v[34:37], v[180:183], v[196:199], v[34:37]
	v_mfma_f32_16x16x32_bf16 v[50:53], v[164:167], v[184:187], v[50:53]
	v_mfma_f32_16x16x32_bf16 v[50:53], v[180:183], v[188:191], v[50:53]
	s_setprio 0
	s_barrier
	ds_read_b128 v[130:133], v175
	ds_read_b128 v[134:137], v175 offset:1024
	ds_read_b128 v[148:151], v175 offset:2048
	ds_read_b128 v[152:155], v175 offset:3072
	ds_read_b128 v[156:159], v176
	ds_read_b128 v[160:163], v176 offset:1024
	ds_read_b128 v[164:167], v176 offset:2048
	ds_read_b128 v[180:183], v176 offset:3072
	s_mov_b32 m0, s64
	s_add_i32 s59, s53, 0x100000
	ds_read_b128 v[184:187], v174 offset:32768
	ds_read_b128 v[188:191], v174 offset:33792
	ds_read_b128 v[192:195], v174 offset:34816
	ds_read_b128 v[196:199], v174 offset:35840
	ds_read_b128 v[200:203], v174 offset:36864
	ds_read_b128 v[204:207], v174 offset:37888
	ds_read_b128 v[208:211], v174 offset:38912
	ds_read_b128 v[212:215], v174 offset:39936
	buffer_load_dwordx4 v170, s[12:15], s59 offen lds
	s_mov_b32 m0, s65
	s_add_i32 s59, s53, 0x180000
	buffer_load_dwordx4 v170, s[12:15], s59 offen lds
	s_waitcnt vmcnt(8) lgkmcnt(0)
	s_setprio 1
	v_mfma_f32_16x16x32_bf16 v[126:129], v[130:133], v[184:187], v[126:129]
	s_barrier
	v_mfma_f32_16x16x32_bf16 v[126:129], v[134:137], v[188:191], v[126:129]
	v_mfma_f32_16x16x32_bf16 v[110:113], v[130:133], v[192:195], v[110:113]
	v_mfma_f32_16x16x32_bf16 v[110:113], v[134:137], v[196:199], v[110:113]
	v_mfma_f32_16x16x32_bf16 v[94:97], v[130:133], v[200:203], v[94:97]
	v_mfma_f32_16x16x32_bf16 v[94:97], v[134:137], v[204:207], v[94:97]
	v_mfma_f32_16x16x32_bf16 v[78:81], v[130:133], v[208:211], v[78:81]
	v_mfma_f32_16x16x32_bf16 v[78:81], v[134:137], v[212:215], v[78:81]
	v_mfma_f32_16x16x32_bf16 v[70:73], v[148:151], v[208:211], v[70:73]
	v_mfma_f32_16x16x32_bf16 v[70:73], v[152:155], v[212:215], v[70:73]
	v_mfma_f32_16x16x32_bf16 v[90:93], v[148:151], v[200:203], v[90:93]
	v_mfma_f32_16x16x32_bf16 v[90:93], v[152:155], v[204:207], v[90:93]
	v_mfma_f32_16x16x32_bf16 v[102:105], v[148:151], v[192:195], v[102:105]
	v_mfma_f32_16x16x32_bf16 v[102:105], v[152:155], v[196:199], v[102:105]
	v_mfma_f32_16x16x32_bf16 v[118:121], v[148:151], v[184:187], v[118:121]
	v_mfma_f32_16x16x32_bf16 v[118:121], v[152:155], v[188:191], v[118:121]
	v_mfma_f32_16x16x32_bf16 v[122:125], v[156:159], v[184:187], v[122:125]
	v_mfma_f32_16x16x32_bf16 v[122:125], v[160:163], v[188:191], v[122:125]
	v_mfma_f32_16x16x32_bf16 v[106:109], v[156:159], v[192:195], v[106:109]
	v_mfma_f32_16x16x32_bf16 v[106:109], v[160:163], v[196:199], v[106:109]
	v_mfma_f32_16x16x32_bf16 v[86:89], v[156:159], v[200:203], v[86:89]
	v_mfma_f32_16x16x32_bf16 v[86:89], v[160:163], v[204:207], v[86:89]
	v_mfma_f32_16x16x32_bf16 v[74:77], v[156:159], v[208:211], v[74:77]
	v_mfma_f32_16x16x32_bf16 v[74:77], v[160:163], v[212:215], v[74:77]
	v_mfma_f32_16x16x32_bf16 v[66:69], v[164:167], v[208:211], v[66:69]
	v_mfma_f32_16x16x32_bf16 v[66:69], v[180:183], v[212:215], v[66:69]
	v_mfma_f32_16x16x32_bf16 v[82:85], v[164:167], v[200:203], v[82:85]
	v_mfma_f32_16x16x32_bf16 v[82:85], v[180:183], v[204:207], v[82:85]
	v_mfma_f32_16x16x32_bf16 v[98:101], v[164:167], v[192:195], v[98:101]
	v_mfma_f32_16x16x32_bf16 v[98:101], v[180:183], v[196:199], v[98:101]
	v_mfma_f32_16x16x32_bf16 v[114:117], v[164:167], v[184:187], v[114:117]
	v_mfma_f32_16x16x32_bf16 v[114:117], v[180:183], v[188:191], v[114:117]
	s_setprio 0
	s_barrier
	s_mov_b32 m0, s70
	s_or_b32 s59, s58, 0x80
	ds_read_b128 v[184:187], v174 offset:49152
	ds_read_b128 v[188:191], v174 offset:50176
	ds_read_b128 v[192:195], v174 offset:51200
	ds_read_b128 v[196:199], v174 offset:52224
	ds_read_b128 v[200:203], v174 offset:53248
	ds_read_b128 v[204:207], v174 offset:54272
	ds_read_b128 v[208:211], v174 offset:55296
	ds_read_b128 v[212:215], v174 offset:56320
	buffer_load_dwordx4 v171, s[16:19], s59 offen lds
	s_add_i32 s59, s58, 0x80080
	s_mov_b32 m0, s71
	s_add_i32 s53, s53, 0x80080
	buffer_load_dwordx4 v171, s[16:19], s59 offen lds
	s_add_i32 s59, s58, 0x100080
	s_mov_b32 m0, s74
	s_add_i32 s58, s58, 0x180080
	buffer_load_dwordx4 v171, s[16:19], s59 offen lds
	s_mov_b32 m0, s75
	s_nop 0
	buffer_load_dwordx4 v171, s[16:19], s58 offen lds
	s_mov_b32 m0, s72
	s_nop 0
	buffer_load_dwordx4 v170, s[12:15], s57 offen lds
	s_mov_b32 m0, s73
	s_nop 0
	buffer_load_dwordx4 v170, s[12:15], s53 offen lds
	s_waitcnt vmcnt(8) lgkmcnt(0)
	s_setprio 1
	v_mfma_f32_16x16x32_bf16 v[62:65], v[130:133], v[184:187], v[62:65]
	s_barrier
	v_mfma_f32_16x16x32_bf16 v[62:65], v[134:137], v[188:191], v[62:65]
	v_mfma_f32_16x16x32_bf16 v[46:49], v[130:133], v[192:195], v[46:49]
	v_mfma_f32_16x16x32_bf16 v[46:49], v[134:137], v[196:199], v[46:49]
	v_mfma_f32_16x16x32_bf16 v[30:33], v[130:133], v[200:203], v[30:33]
	v_mfma_f32_16x16x32_bf16 v[30:33], v[134:137], v[204:207], v[30:33]
	v_mfma_f32_16x16x32_bf16 v[14:17], v[130:133], v[208:211], v[14:17]
	v_mfma_f32_16x16x32_bf16 v[14:17], v[134:137], v[212:215], v[14:17]
	v_mfma_f32_16x16x32_bf16 v[6:9], v[148:151], v[208:211], v[6:9]
	v_mfma_f32_16x16x32_bf16 v[6:9], v[152:155], v[212:215], v[6:9]
	v_mfma_f32_16x16x32_bf16 v[22:25], v[148:151], v[200:203], v[22:25]
	v_mfma_f32_16x16x32_bf16 v[22:25], v[152:155], v[204:207], v[22:25]
	v_mfma_f32_16x16x32_bf16 v[38:41], v[148:151], v[192:195], v[38:41]
	v_mfma_f32_16x16x32_bf16 v[38:41], v[152:155], v[196:199], v[38:41]
	v_mfma_f32_16x16x32_bf16 v[54:57], v[148:151], v[184:187], v[54:57]
	v_mfma_f32_16x16x32_bf16 v[54:57], v[152:155], v[188:191], v[54:57]
	v_mfma_f32_16x16x32_bf16 v[58:61], v[156:159], v[184:187], v[58:61]
	v_mfma_f32_16x16x32_bf16 v[58:61], v[160:163], v[188:191], v[58:61]
	v_mfma_f32_16x16x32_bf16 v[42:45], v[156:159], v[192:195], v[42:45]
	v_mfma_f32_16x16x32_bf16 v[42:45], v[160:163], v[196:199], v[42:45]
	v_mfma_f32_16x16x32_bf16 v[26:29], v[156:159], v[200:203], v[26:29]
	v_mfma_f32_16x16x32_bf16 v[26:29], v[160:163], v[204:207], v[26:29]
	v_mfma_f32_16x16x32_bf16 v[10:13], v[156:159], v[208:211], v[10:13]
	v_mfma_f32_16x16x32_bf16 v[10:13], v[160:163], v[212:215], v[10:13]
	v_mfma_f32_16x16x32_bf16 v[2:5], v[164:167], v[208:211], v[2:5]
	v_mfma_f32_16x16x32_bf16 v[2:5], v[180:183], v[212:215], v[2:5]
	v_mfma_f32_16x16x32_bf16 v[18:21], v[164:167], v[200:203], v[18:21]
	v_mfma_f32_16x16x32_bf16 v[18:21], v[180:183], v[204:207], v[18:21]
	v_mfma_f32_16x16x32_bf16 v[34:37], v[164:167], v[192:195], v[34:37]
	v_mfma_f32_16x16x32_bf16 v[34:37], v[180:183], v[196:199], v[34:37]
	v_mfma_f32_16x16x32_bf16 v[50:53], v[164:167], v[184:187], v[50:53]
	v_mfma_f32_16x16x32_bf16 v[50:53], v[180:183], v[188:191], v[50:53]
	s_setprio 0
	s_barrier
	s_add_i32 s52, s52, 2
	s_addk_i32 s8, 0x100
	s_addk_i32 s9, 0x100
	s_cmp_ge_i32 s52, s21
	s_cbranch_scc0 .LBB0_892
	s_and_b64 vcc, exec, s[48:49]
	s_cbranch_vccz .LBB0_895

.LBB0_1020:
	v_add_u32_e32 v142, 0x10000, v162
	v_add_u32_e32 v150, 0x14000, v162
	ds_read_b128 v[130:133], v142
	ds_read_b128 v[134:137], v142 offset:1024
	ds_read_b128 v[138:141], v142 offset:2048
	ds_read_b128 v[142:145], v142 offset:3072
	ds_read_b128 v[154:157], v150
	ds_read_b128 v[164:167], v150 offset:1024
	ds_read_b128 v[168:171], v150 offset:2048
	ds_read_b128 v[172:175], v150 offset:3072
	s_add_i32 s90, s6, 0x100
	s_add_i32 s7, s88, s6
	s_cmp_eq_u32 s81, s89
	s_cselect_b32 s91, 0, s90
	s_cselect_b32 s93, s87, s7
	s_add_i32 s91, s91, s70
	s_or_b32 s92, s91, 0x80
	s_add_i32 s6, s3, s6
	s_mov_b32 m0, s82
	s_add_i32 s7, s6, 0x20080
	ds_read_b128 v[176:179], v163
	ds_read_b128 v[180:183], v163 offset:1024
	ds_read_b128 v[184:187], v163 offset:2048
	ds_read_b128 v[188:191], v163 offset:3072
	ds_read_b128 v[192:195], v163 offset:4096
	ds_read_b128 v[196:199], v163 offset:5120
	ds_read_b128 v[200:203], v163 offset:6144
	ds_read_b128 v[204:207], v163 offset:7168
	buffer_load_dwordx4 v161, s[12:15], s7 offen lds
	s_mov_b32 m0, s83
	s_add_i32 s6, s6, 0x30080
	buffer_load_dwordx4 v161, s[12:15], s6 offen lds
	s_waitcnt vmcnt(8) lgkmcnt(0)
	s_setprio 1
	v_mfma_f32_16x16x32_bf16 v[126:129], v[130:133], v[176:179], v[126:129]
	s_barrier
	v_mfma_f32_16x16x32_bf16 v[126:129], v[134:137], v[180:183], v[126:129]
	v_mfma_f32_16x16x32_bf16 v[110:113], v[130:133], v[184:187], v[110:113]
	v_mfma_f32_16x16x32_bf16 v[110:113], v[134:137], v[188:191], v[110:113]
	v_mfma_f32_16x16x32_bf16 v[94:97], v[130:133], v[192:195], v[94:97]
	v_mfma_f32_16x16x32_bf16 v[94:97], v[134:137], v[196:199], v[94:97]
	v_mfma_f32_16x16x32_bf16 v[78:81], v[130:133], v[200:203], v[78:81]
	v_mfma_f32_16x16x32_bf16 v[78:81], v[134:137], v[204:207], v[78:81]
	v_mfma_f32_16x16x32_bf16 v[74:77], v[138:141], v[200:203], v[74:77]
	v_mfma_f32_16x16x32_bf16 v[74:77], v[142:145], v[204:207], v[74:77]
	v_mfma_f32_16x16x32_bf16 v[90:93], v[138:141], v[192:195], v[90:93]
	v_mfma_f32_16x16x32_bf16 v[90:93], v[142:145], v[196:199], v[90:93]
	v_mfma_f32_16x16x32_bf16 v[106:109], v[138:141], v[184:187], v[106:109]
	v_mfma_f32_16x16x32_bf16 v[106:109], v[142:145], v[188:191], v[106:109]
	v_mfma_f32_16x16x32_bf16 v[122:125], v[138:141], v[176:179], v[122:125]
	v_mfma_f32_16x16x32_bf16 v[122:125], v[142:145], v[180:183], v[122:125]
	v_mfma_f32_16x16x32_bf16 v[118:121], v[154:157], v[176:179], v[118:121]
	v_mfma_f32_16x16x32_bf16 v[118:121], v[164:167], v[180:183], v[118:121]
	v_mfma_f32_16x16x32_bf16 v[102:105], v[154:157], v[184:187], v[102:105]
	v_mfma_f32_16x16x32_bf16 v[102:105], v[164:167], v[188:191], v[102:105]
	v_mfma_f32_16x16x32_bf16 v[86:89], v[154:157], v[192:195], v[86:89]
	v_mfma_f32_16x16x32_bf16 v[86:89], v[164:167], v[196:199], v[86:89]
	v_mfma_f32_16x16x32_bf16 v[70:73], v[154:157], v[200:203], v[70:73]
	v_mfma_f32_16x16x32_bf16 v[70:73], v[164:167], v[204:207], v[70:73]
	v_mfma_f32_16x16x32_bf16 v[66:69], v[168:171], v[200:203], v[66:69]
	v_mfma_f32_16x16x32_bf16 v[66:69], v[172:175], v[204:207], v[66:69]
	v_mfma_f32_16x16x32_bf16 v[82:85], v[168:171], v[192:195], v[82:85]
	v_mfma_f32_16x16x32_bf16 v[82:85], v[172:175], v[196:199], v[82:85]
	v_mfma_f32_16x16x32_bf16 v[98:101], v[168:171], v[184:187], v[98:101]
	v_mfma_f32_16x16x32_bf16 v[98:101], v[172:175], v[188:191], v[98:101]
	v_mfma_f32_16x16x32_bf16 v[114:117], v[168:171], v[176:179], v[114:117]
	v_mfma_f32_16x16x32_bf16 v[114:117], v[172:175], v[180:183], v[114:117]
	s_setprio 0
	s_barrier
	s_mov_b32 m0, s66
	s_mov_b32 s6, s14
	s_mov_b32 s7, s15
	ds_read_b128 v[176:179], v163 offset:16384
	ds_read_b128 v[180:183], v163 offset:17408
	ds_read_b128 v[184:187], v163 offset:18432
	ds_read_b128 v[188:191], v163 offset:19456
	ds_read_b128 v[192:195], v163 offset:20480
	ds_read_b128 v[196:199], v163 offset:21504
	ds_read_b128 v[200:203], v163 offset:22528
	ds_read_b128 v[204:207], v163 offset:23552
	buffer_load_dwordx4 v160, s[4:7], s93 offen lds
	s_mov_b32 m0, s67
	s_add_i32 s94, s93, 0x10000
	buffer_load_dwordx4 v160, s[4:7], s94 offen lds
	s_mov_b32 m0, s68
	s_add_i32 s94, s93, 0x20000
	buffer_load_dwordx4 v160, s[4:7], s94 offen lds
	s_mov_b32 m0, s69
	s_add_i32 s94, s93, 0x30000
	buffer_load_dwordx4 v160, s[4:7], s94 offen lds
	s_mov_b32 m0, s65
	s_add_i32 s94, s91, 0x10000
	buffer_load_dwordx4 v161, s[12:15], s91 offen lds
	s_mov_b32 m0, s71
	s_nop 0
	buffer_load_dwordx4 v161, s[12:15], s94 offen lds
	s_waitcnt vmcnt(8) lgkmcnt(0)
	s_setprio 1
	v_mfma_f32_16x16x32_bf16 v[62:65], v[130:133], v[176:179], v[62:65]
	s_barrier
	v_mfma_f32_16x16x32_bf16 v[62:65], v[134:137], v[180:183], v[62:65]
	v_mfma_f32_16x16x32_bf16 v[46:49], v[130:133], v[184:187], v[46:49]
	v_mfma_f32_16x16x32_bf16 v[46:49], v[134:137], v[188:191], v[46:49]
	v_mfma_f32_16x16x32_bf16 v[30:33], v[130:133], v[192:195], v[30:33]
	v_mfma_f32_16x16x32_bf16 v[30:33], v[134:137], v[196:199], v[30:33]
	v_mfma_f32_16x16x32_bf16 v[14:17], v[130:133], v[200:203], v[14:17]
	v_mfma_f32_16x16x32_bf16 v[14:17], v[134:137], v[204:207], v[14:17]
	v_mfma_f32_16x16x32_bf16 v[10:13], v[138:141], v[200:203], v[10:13]
	v_mfma_f32_16x16x32_bf16 v[10:13], v[142:145], v[204:207], v[10:13]
	v_mfma_f32_16x16x32_bf16 v[26:29], v[138:141], v[192:195], v[26:29]
	v_mfma_f32_16x16x32_bf16 v[26:29], v[142:145], v[196:199], v[26:29]
	v_mfma_f32_16x16x32_bf16 v[42:45], v[138:141], v[184:187], v[42:45]
	v_mfma_f32_16x16x32_bf16 v[42:45], v[142:145], v[188:191], v[42:45]
	v_mfma_f32_16x16x32_bf16 v[58:61], v[138:141], v[176:179], v[58:61]
	v_mfma_f32_16x16x32_bf16 v[58:61], v[142:145], v[180:183], v[58:61]
	v_mfma_f32_16x16x32_bf16 v[54:57], v[154:157], v[176:179], v[54:57]
	v_mfma_f32_16x16x32_bf16 v[54:57], v[164:167], v[180:183], v[54:57]
	v_mfma_f32_16x16x32_bf16 v[38:41], v[154:157], v[184:187], v[38:41]
	v_mfma_f32_16x16x32_bf16 v[38:41], v[164:167], v[188:191], v[38:41]
	v_mfma_f32_16x16x32_bf16 v[22:25], v[154:157], v[192:195], v[22:25]
	v_mfma_f32_16x16x32_bf16 v[22:25], v[164:167], v[196:199], v[22:25]
	v_mfma_f32_16x16x32_bf16 v[6:9], v[154:157], v[200:203], v[6:9]
	v_mfma_f32_16x16x32_bf16 v[6:9], v[164:167], v[204:207], v[6:9]
	v_mfma_f32_16x16x32_bf16 v[2:5], v[168:171], v[200:203], v[2:5]
	v_mfma_f32_16x16x32_bf16 v[2:5], v[172:175], v[204:207], v[2:5]
	v_mfma_f32_16x16x32_bf16 v[18:21], v[168:171], v[192:195], v[18:21]
	v_mfma_f32_16x16x32_bf16 v[18:21], v[172:175], v[196:199], v[18:21]
	v_mfma_f32_16x16x32_bf16 v[34:37], v[168:171], v[184:187], v[34:37]
	v_mfma_f32_16x16x32_bf16 v[34:37], v[172:175], v[188:191], v[34:37]
	v_mfma_f32_16x16x32_bf16 v[50:53], v[168:171], v[176:179], v[50:53]
	v_mfma_f32_16x16x32_bf16 v[50:53], v[172:175], v[180:183], v[50:53]
	s_setprio 0
	s_barrier
	v_add_u32_e32 v142, 0x18000, v162
	v_add_u32_e32 v150, 0x1c000, v162
	ds_read_b128 v[130:133], v142
	ds_read_b128 v[134:137], v142 offset:1024
	ds_read_b128 v[138:141], v142 offset:2048
	ds_read_b128 v[142:145], v142 offset:3072
	ds_read_b128 v[154:157], v150
	ds_read_b128 v[164:167], v150 offset:1024
	ds_read_b128 v[168:171], v150 offset:2048
	ds_read_b128 v[172:175], v150 offset:3072
	s_mov_b32 m0, s72
	s_add_i32 s94, s91, 0x20000
	ds_read_b128 v[176:179], v163 offset:32768
	ds_read_b128 v[180:183], v163 offset:33792
	ds_read_b128 v[184:187], v163 offset:34816
	ds_read_b128 v[188:191], v163 offset:35840
	ds_read_b128 v[192:195], v163 offset:36864
	ds_read_b128 v[196:199], v163 offset:37888
	ds_read_b128 v[200:203], v163 offset:38912
	ds_read_b128 v[204:207], v163 offset:39936
	buffer_load_dwordx4 v161, s[12:15], s94 offen lds
	s_mov_b32 m0, s73
	s_add_i32 s94, s91, 0x30000
	buffer_load_dwordx4 v161, s[12:15], s94 offen lds
	s_waitcnt vmcnt(8) lgkmcnt(0)
	s_setprio 1
	v_mfma_f32_16x16x32_bf16 v[126:129], v[130:133], v[176:179], v[126:129]
	s_barrier
	v_mfma_f32_16x16x32_bf16 v[126:129], v[134:137], v[180:183], v[126:129]
	v_mfma_f32_16x16x32_bf16 v[110:113], v[130:133], v[184:187], v[110:113]
	v_mfma_f32_16x16x32_bf16 v[110:113], v[134:137], v[188:191], v[110:113]
	v_mfma_f32_16x16x32_bf16 v[94:97], v[130:133], v[192:195], v[94:97]
	v_mfma_f32_16x16x32_bf16 v[94:97], v[134:137], v[196:199], v[94:97]
	v_mfma_f32_16x16x32_bf16 v[78:81], v[130:133], v[200:203], v[78:81]
	v_mfma_f32_16x16x32_bf16 v[78:81], v[134:137], v[204:207], v[78:81]
	v_mfma_f32_16x16x32_bf16 v[74:77], v[138:141], v[200:203], v[74:77]
	v_mfma_f32_16x16x32_bf16 v[74:77], v[142:145], v[204:207], v[74:77]
	v_mfma_f32_16x16x32_bf16 v[90:93], v[138:141], v[192:195], v[90:93]
	v_mfma_f32_16x16x32_bf16 v[90:93], v[142:145], v[196:199], v[90:93]
	v_mfma_f32_16x16x32_bf16 v[106:109], v[138:141], v[184:187], v[106:109]
	v_mfma_f32_16x16x32_bf16 v[106:109], v[142:145], v[188:191], v[106:109]
	v_mfma_f32_16x16x32_bf16 v[122:125], v[138:141], v[176:179], v[122:125]
	v_mfma_f32_16x16x32_bf16 v[122:125], v[142:145], v[180:183], v[122:125]
	v_mfma_f32_16x16x32_bf16 v[118:121], v[154:157], v[176:179], v[118:121]
	v_mfma_f32_16x16x32_bf16 v[118:121], v[164:167], v[180:183], v[118:121]
	v_mfma_f32_16x16x32_bf16 v[102:105], v[154:157], v[184:187], v[102:105]
	v_mfma_f32_16x16x32_bf16 v[102:105], v[164:167], v[188:191], v[102:105]
	v_mfma_f32_16x16x32_bf16 v[86:89], v[154:157], v[192:195], v[86:89]
	v_mfma_f32_16x16x32_bf16 v[86:89], v[164:167], v[196:199], v[86:89]
	v_mfma_f32_16x16x32_bf16 v[70:73], v[154:157], v[200:203], v[70:73]
	v_mfma_f32_16x16x32_bf16 v[70:73], v[164:167], v[204:207], v[70:73]
	v_mfma_f32_16x16x32_bf16 v[66:69], v[168:171], v[200:203], v[66:69]
	v_mfma_f32_16x16x32_bf16 v[66:69], v[172:175], v[204:207], v[66:69]
	v_mfma_f32_16x16x32_bf16 v[82:85], v[168:171], v[192:195], v[82:85]
	v_mfma_f32_16x16x32_bf16 v[82:85], v[172:175], v[196:199], v[82:85]
	v_mfma_f32_16x16x32_bf16 v[98:101], v[168:171], v[184:187], v[98:101]
	v_mfma_f32_16x16x32_bf16 v[98:101], v[172:175], v[188:191], v[98:101]
	v_mfma_f32_16x16x32_bf16 v[114:117], v[168:171], v[176:179], v[114:117]
	v_mfma_f32_16x16x32_bf16 v[114:117], v[172:175], v[180:183], v[114:117]
	s_setprio 0
	s_barrier
	s_mov_b32 m0, s74
	s_or_b32 s94, s93, 0x80
	ds_read_b128 v[176:179], v163 offset:49152
	ds_read_b128 v[180:183], v163 offset:50176
	ds_read_b128 v[184:187], v163 offset:51200
	ds_read_b128 v[188:191], v163 offset:52224
	ds_read_b128 v[192:195], v163 offset:53248
	ds_read_b128 v[196:199], v163 offset:54272
	ds_read_b128 v[200:203], v163 offset:55296
	ds_read_b128 v[204:207], v163 offset:56320
	buffer_load_dwordx4 v160, s[4:7], s94 offen lds
	s_add_i32 s94, s93, 0x10080
	s_mov_b32 m0, s75
	s_add_i32 s91, s91, 0x10080
	buffer_load_dwordx4 v160, s[4:7], s94 offen lds
	s_add_i32 s94, s93, 0x20080
	s_mov_b32 m0, s78
	s_add_i32 s93, s93, 0x30080
	buffer_load_dwordx4 v160, s[4:7], s94 offen lds
	s_mov_b32 m0, s79
	s_nop 0
	buffer_load_dwordx4 v160, s[4:7], s93 offen lds
	s_mov_b32 m0, s76
	s_nop 0
	buffer_load_dwordx4 v161, s[12:15], s92 offen lds
	s_mov_b32 m0, s77
	s_nop 0
	buffer_load_dwordx4 v161, s[12:15], s91 offen lds
	s_waitcnt vmcnt(8) lgkmcnt(0)
	s_setprio 1
	v_mfma_f32_16x16x32_bf16 v[62:65], v[130:133], v[176:179], v[62:65]
	s_barrier
	v_mfma_f32_16x16x32_bf16 v[62:65], v[134:137], v[180:183], v[62:65]
	v_mfma_f32_16x16x32_bf16 v[46:49], v[130:133], v[184:187], v[46:49]
	v_mfma_f32_16x16x32_bf16 v[46:49], v[134:137], v[188:191], v[46:49]
	v_mfma_f32_16x16x32_bf16 v[30:33], v[130:133], v[192:195], v[30:33]
	v_mfma_f32_16x16x32_bf16 v[30:33], v[134:137], v[196:199], v[30:33]
	v_mfma_f32_16x16x32_bf16 v[14:17], v[130:133], v[200:203], v[14:17]
	v_mfma_f32_16x16x32_bf16 v[14:17], v[134:137], v[204:207], v[14:17]
	v_mfma_f32_16x16x32_bf16 v[10:13], v[138:141], v[200:203], v[10:13]
	v_mfma_f32_16x16x32_bf16 v[10:13], v[142:145], v[204:207], v[10:13]
	v_mfma_f32_16x16x32_bf16 v[26:29], v[138:141], v[192:195], v[26:29]
	v_mfma_f32_16x16x32_bf16 v[26:29], v[142:145], v[196:199], v[26:29]
	v_mfma_f32_16x16x32_bf16 v[42:45], v[138:141], v[184:187], v[42:45]
	v_mfma_f32_16x16x32_bf16 v[42:45], v[142:145], v[188:191], v[42:45]
	v_mfma_f32_16x16x32_bf16 v[58:61], v[138:141], v[176:179], v[58:61]
	v_mfma_f32_16x16x32_bf16 v[58:61], v[142:145], v[180:183], v[58:61]
	v_mfma_f32_16x16x32_bf16 v[54:57], v[154:157], v[176:179], v[54:57]
	v_mfma_f32_16x16x32_bf16 v[54:57], v[164:167], v[180:183], v[54:57]
	v_mfma_f32_16x16x32_bf16 v[38:41], v[154:157], v[184:187], v[38:41]
	v_mfma_f32_16x16x32_bf16 v[38:41], v[164:167], v[188:191], v[38:41]
	v_mfma_f32_16x16x32_bf16 v[22:25], v[154:157], v[192:195], v[22:25]
	v_mfma_f32_16x16x32_bf16 v[22:25], v[164:167], v[196:199], v[22:25]
	v_mfma_f32_16x16x32_bf16 v[6:9], v[154:157], v[200:203], v[6:9]
	v_mfma_f32_16x16x32_bf16 v[6:9], v[164:167], v[204:207], v[6:9]
	v_mfma_f32_16x16x32_bf16 v[2:5], v[168:171], v[200:203], v[2:5]
	v_mfma_f32_16x16x32_bf16 v[2:5], v[172:175], v[204:207], v[2:5]
	v_mfma_f32_16x16x32_bf16 v[18:21], v[168:171], v[192:195], v[18:21]
	v_mfma_f32_16x16x32_bf16 v[18:21], v[172:175], v[196:199], v[18:21]
	v_mfma_f32_16x16x32_bf16 v[34:37], v[168:171], v[184:187], v[34:37]
	v_mfma_f32_16x16x32_bf16 v[34:37], v[172:175], v[188:191], v[34:37]
	v_mfma_f32_16x16x32_bf16 v[50:53], v[168:171], v[176:179], v[50:53]
	v_mfma_f32_16x16x32_bf16 v[50:53], v[172:175], v[180:183], v[50:53]
	s_setprio 0
	s_barrier
	s_add_i32 s89, s89, 2
	s_cmp_ge_i32 s89, s63
	s_mov_b32 s6, s90
	s_cbranch_scc0 .LBB0_1020
	s_and_b64 vcc, exec, s[54:55]
	s_cbranch_vccz .LBB0_1023

.LBB0_1035:
	ds_read_b128 v[140:143], v134
	ds_read_b128 v[148:151], v134 offset:1024
	ds_read_b128 v[152:155], v134 offset:2048
	ds_read_b128 v[156:159], v134 offset:3072
	ds_read_b128 v[160:163], v135
	ds_read_b128 v[164:167], v135 offset:1024
	ds_read_b128 v[168:171], v135 offset:2048
	ds_read_b128 v[172:175], v135 offset:3072
	s_add_i32 s73, s70, 0xfffb8080
	s_cmp_eq_u32 s53, s72
	s_cselect_b32 s73, s68, s73
	s_cselect_b32 s75, s69, s71
	s_add_i32 s74, s73, 0x80
	s_add_i32 s76, s70, 0xfffe8000
	s_mov_b32 m0, s54
	ds_read_b128 v[176:179], v136
	ds_read_b128 v[180:183], v136 offset:1024
	ds_read_b128 v[184:187], v136 offset:2048
	ds_read_b128 v[188:191], v136 offset:3072
	ds_read_b128 v[192:195], v136 offset:4096
	ds_read_b128 v[196:199], v136 offset:5120
	ds_read_b128 v[200:203], v136 offset:6144
	ds_read_b128 v[204:207], v136 offset:7168
	buffer_load_dwordx4 v132, s[12:15], s76 offen lds
	s_mov_b32 m0, s55
	s_nop 0
	buffer_load_dwordx4 v132, s[12:15], s70 offen lds
	s_waitcnt vmcnt(8) lgkmcnt(0)
	s_setprio 1
	v_mfma_f32_16x16x32_bf16 v[126:129], v[140:143], v[176:179], v[126:129]
	s_barrier
	v_mfma_f32_16x16x32_bf16 v[126:129], v[148:151], v[180:183], v[126:129]
	v_mfma_f32_16x16x32_bf16 v[110:113], v[140:143], v[184:187], v[110:113]
	v_mfma_f32_16x16x32_bf16 v[110:113], v[148:151], v[188:191], v[110:113]
	v_mfma_f32_16x16x32_bf16 v[94:97], v[140:143], v[192:195], v[94:97]
	v_mfma_f32_16x16x32_bf16 v[94:97], v[148:151], v[196:199], v[94:97]
	v_mfma_f32_16x16x32_bf16 v[78:81], v[140:143], v[200:203], v[78:81]
	v_mfma_f32_16x16x32_bf16 v[78:81], v[148:151], v[204:207], v[78:81]
	v_mfma_f32_16x16x32_bf16 v[74:77], v[152:155], v[200:203], v[74:77]
	v_mfma_f32_16x16x32_bf16 v[74:77], v[156:159], v[204:207], v[74:77]
	v_mfma_f32_16x16x32_bf16 v[90:93], v[152:155], v[192:195], v[90:93]
	v_mfma_f32_16x16x32_bf16 v[90:93], v[156:159], v[196:199], v[90:93]
	v_mfma_f32_16x16x32_bf16 v[106:109], v[152:155], v[184:187], v[106:109]
	v_mfma_f32_16x16x32_bf16 v[106:109], v[156:159], v[188:191], v[106:109]
	v_mfma_f32_16x16x32_bf16 v[122:125], v[152:155], v[176:179], v[122:125]
	v_mfma_f32_16x16x32_bf16 v[122:125], v[156:159], v[180:183], v[122:125]
	v_mfma_f32_16x16x32_bf16 v[118:121], v[160:163], v[176:179], v[118:121]
	v_mfma_f32_16x16x32_bf16 v[118:121], v[164:167], v[180:183], v[118:121]
	v_mfma_f32_16x16x32_bf16 v[102:105], v[160:163], v[184:187], v[102:105]
	v_mfma_f32_16x16x32_bf16 v[102:105], v[164:167], v[188:191], v[102:105]
	v_mfma_f32_16x16x32_bf16 v[86:89], v[160:163], v[192:195], v[86:89]
	v_mfma_f32_16x16x32_bf16 v[86:89], v[164:167], v[196:199], v[86:89]
	v_mfma_f32_16x16x32_bf16 v[70:73], v[160:163], v[200:203], v[70:73]
	v_mfma_f32_16x16x32_bf16 v[70:73], v[164:167], v[204:207], v[70:73]
	v_mfma_f32_16x16x32_bf16 v[66:69], v[168:171], v[200:203], v[66:69]
	v_mfma_f32_16x16x32_bf16 v[66:69], v[172:175], v[204:207], v[66:69]
	v_mfma_f32_16x16x32_bf16 v[82:85], v[168:171], v[192:195], v[82:85]
	v_mfma_f32_16x16x32_bf16 v[82:85], v[172:175], v[196:199], v[82:85]
	v_mfma_f32_16x16x32_bf16 v[98:101], v[168:171], v[184:187], v[98:101]
	v_mfma_f32_16x16x32_bf16 v[98:101], v[172:175], v[188:191], v[98:101]
	v_mfma_f32_16x16x32_bf16 v[114:117], v[168:171], v[176:179], v[114:117]
	v_mfma_f32_16x16x32_bf16 v[114:117], v[172:175], v[180:183], v[114:117]
	s_setprio 0
	s_barrier
	s_mov_b32 m0, s30
	ds_read_b128 v[176:179], v136 offset:16384
	ds_read_b128 v[180:183], v136 offset:17408
	ds_read_b128 v[184:187], v136 offset:18432
	ds_read_b128 v[188:191], v136 offset:19456
	ds_read_b128 v[192:195], v136 offset:20480
	ds_read_b128 v[196:199], v136 offset:21504
	ds_read_b128 v[200:203], v136 offset:22528
	ds_read_b128 v[204:207], v136 offset:23552
	buffer_load_dwordx4 v133, s[16:19], s75 offen lds
	s_mov_b32 m0, s31
	s_add_i32 s76, s75, 0x200000
	buffer_load_dwordx4 v133, s[16:19], s76 offen lds
	s_mov_b32 m0, s35
	s_add_i32 s76, s75, 0x400000
	buffer_load_dwordx4 v133, s[16:19], s76 offen lds
	s_mov_b32 m0, s42
	s_add_i32 s76, s75, 0x600000
	buffer_load_dwordx4 v133, s[16:19], s76 offen lds
	s_mov_b32 m0, s27
	s_add_i32 s76, s73, 0x18000
	buffer_load_dwordx4 v132, s[12:15], s73 offen lds
	s_mov_b32 m0, s43
	s_nop 0
	buffer_load_dwordx4 v132, s[12:15], s76 offen lds
	s_waitcnt vmcnt(8) lgkmcnt(0)
	s_setprio 1
	v_mfma_f32_16x16x32_bf16 v[62:65], v[140:143], v[176:179], v[62:65]
	s_barrier
	v_mfma_f32_16x16x32_bf16 v[62:65], v[148:151], v[180:183], v[62:65]
	v_mfma_f32_16x16x32_bf16 v[46:49], v[140:143], v[184:187], v[46:49]
	v_mfma_f32_16x16x32_bf16 v[46:49], v[148:151], v[188:191], v[46:49]
	v_mfma_f32_16x16x32_bf16 v[30:33], v[140:143], v[192:195], v[30:33]
	v_mfma_f32_16x16x32_bf16 v[30:33], v[148:151], v[196:199], v[30:33]
	v_mfma_f32_16x16x32_bf16 v[14:17], v[140:143], v[200:203], v[14:17]
	v_mfma_f32_16x16x32_bf16 v[14:17], v[148:151], v[204:207], v[14:17]
	v_mfma_f32_16x16x32_bf16 v[10:13], v[152:155], v[200:203], v[10:13]
	v_mfma_f32_16x16x32_bf16 v[10:13], v[156:159], v[204:207], v[10:13]
	v_mfma_f32_16x16x32_bf16 v[26:29], v[152:155], v[192:195], v[26:29]
	v_mfma_f32_16x16x32_bf16 v[26:29], v[156:159], v[196:199], v[26:29]
	v_mfma_f32_16x16x32_bf16 v[42:45], v[152:155], v[184:187], v[42:45]
	v_mfma_f32_16x16x32_bf16 v[42:45], v[156:159], v[188:191], v[42:45]
	v_mfma_f32_16x16x32_bf16 v[58:61], v[152:155], v[176:179], v[58:61]
	v_mfma_f32_16x16x32_bf16 v[58:61], v[156:159], v[180:183], v[58:61]
	v_mfma_f32_16x16x32_bf16 v[54:57], v[160:163], v[176:179], v[54:57]
	v_mfma_f32_16x16x32_bf16 v[54:57], v[164:167], v[180:183], v[54:57]
	v_mfma_f32_16x16x32_bf16 v[38:41], v[160:163], v[184:187], v[38:41]
	v_mfma_f32_16x16x32_bf16 v[38:41], v[164:167], v[188:191], v[38:41]
	v_mfma_f32_16x16x32_bf16 v[22:25], v[160:163], v[192:195], v[22:25]
	v_mfma_f32_16x16x32_bf16 v[22:25], v[164:167], v[196:199], v[22:25]
	v_mfma_f32_16x16x32_bf16 v[6:9], v[160:163], v[200:203], v[6:9]
	v_mfma_f32_16x16x32_bf16 v[6:9], v[164:167], v[204:207], v[6:9]
	v_mfma_f32_16x16x32_bf16 v[2:5], v[168:171], v[200:203], v[2:5]
	v_mfma_f32_16x16x32_bf16 v[2:5], v[172:175], v[204:207], v[2:5]
	v_mfma_f32_16x16x32_bf16 v[18:21], v[168:171], v[192:195], v[18:21]
	v_mfma_f32_16x16x32_bf16 v[18:21], v[172:175], v[196:199], v[18:21]
	v_mfma_f32_16x16x32_bf16 v[34:37], v[168:171], v[184:187], v[34:37]
	v_mfma_f32_16x16x32_bf16 v[34:37], v[172:175], v[188:191], v[34:37]
	v_mfma_f32_16x16x32_bf16 v[50:53], v[168:171], v[176:179], v[50:53]
	v_mfma_f32_16x16x32_bf16 v[50:53], v[172:175], v[180:183], v[50:53]
	s_setprio 0
	s_barrier
	ds_read_b128 v[140:143], v137
	ds_read_b128 v[148:151], v137 offset:1024
	ds_read_b128 v[152:155], v137 offset:2048
	ds_read_b128 v[156:159], v137 offset:3072
	ds_read_b128 v[160:163], v138
	ds_read_b128 v[164:167], v138 offset:1024
	ds_read_b128 v[168:171], v138 offset:2048
	ds_read_b128 v[172:175], v138 offset:3072
	s_mov_b32 m0, s44
	s_add_i32 s76, s73, 0x30000
	ds_read_b128 v[176:179], v136 offset:32768
	ds_read_b128 v[180:183], v136 offset:33792
	ds_read_b128 v[184:187], v136 offset:34816
	ds_read_b128 v[188:191], v136 offset:35840
	ds_read_b128 v[192:195], v136 offset:36864
	ds_read_b128 v[196:199], v136 offset:37888
	ds_read_b128 v[200:203], v136 offset:38912
	ds_read_b128 v[204:207], v136 offset:39936
	buffer_load_dwordx4 v132, s[12:15], s76 offen lds
	s_mov_b32 m0, s45
	s_add_i32 s76, s73, 0x48000
	buffer_load_dwordx4 v132, s[12:15], s76 offen lds
	s_waitcnt vmcnt(8) lgkmcnt(0)
	s_setprio 1
	v_mfma_f32_16x16x32_bf16 v[126:129], v[140:143], v[176:179], v[126:129]
	s_barrier
	v_mfma_f32_16x16x32_bf16 v[126:129], v[148:151], v[180:183], v[126:129]
	v_mfma_f32_16x16x32_bf16 v[110:113], v[140:143], v[184:187], v[110:113]
	v_mfma_f32_16x16x32_bf16 v[110:113], v[148:151], v[188:191], v[110:113]
	v_mfma_f32_16x16x32_bf16 v[94:97], v[140:143], v[192:195], v[94:97]
	v_mfma_f32_16x16x32_bf16 v[94:97], v[148:151], v[196:199], v[94:97]
	v_mfma_f32_16x16x32_bf16 v[78:81], v[140:143], v[200:203], v[78:81]
	v_mfma_f32_16x16x32_bf16 v[78:81], v[148:151], v[204:207], v[78:81]
	v_mfma_f32_16x16x32_bf16 v[74:77], v[152:155], v[200:203], v[74:77]
	v_mfma_f32_16x16x32_bf16 v[74:77], v[156:159], v[204:207], v[74:77]
	v_mfma_f32_16x16x32_bf16 v[90:93], v[152:155], v[192:195], v[90:93]
	v_mfma_f32_16x16x32_bf16 v[90:93], v[156:159], v[196:199], v[90:93]
	v_mfma_f32_16x16x32_bf16 v[106:109], v[152:155], v[184:187], v[106:109]
	v_mfma_f32_16x16x32_bf16 v[106:109], v[156:159], v[188:191], v[106:109]
	v_mfma_f32_16x16x32_bf16 v[122:125], v[152:155], v[176:179], v[122:125]
	v_mfma_f32_16x16x32_bf16 v[122:125], v[156:159], v[180:183], v[122:125]
	v_mfma_f32_16x16x32_bf16 v[118:121], v[160:163], v[176:179], v[118:121]
	v_mfma_f32_16x16x32_bf16 v[118:121], v[164:167], v[180:183], v[118:121]
	v_mfma_f32_16x16x32_bf16 v[102:105], v[160:163], v[184:187], v[102:105]
	v_mfma_f32_16x16x32_bf16 v[102:105], v[164:167], v[188:191], v[102:105]
	v_mfma_f32_16x16x32_bf16 v[86:89], v[160:163], v[192:195], v[86:89]
	v_mfma_f32_16x16x32_bf16 v[86:89], v[164:167], v[196:199], v[86:89]
	v_mfma_f32_16x16x32_bf16 v[70:73], v[160:163], v[200:203], v[70:73]
	v_mfma_f32_16x16x32_bf16 v[70:73], v[164:167], v[204:207], v[70:73]
	v_mfma_f32_16x16x32_bf16 v[66:69], v[168:171], v[200:203], v[66:69]
	v_mfma_f32_16x16x32_bf16 v[66:69], v[172:175], v[204:207], v[66:69]
	v_mfma_f32_16x16x32_bf16 v[82:85], v[168:171], v[192:195], v[82:85]
	v_mfma_f32_16x16x32_bf16 v[82:85], v[172:175], v[196:199], v[82:85]
	v_mfma_f32_16x16x32_bf16 v[98:101], v[168:171], v[184:187], v[98:101]
	v_mfma_f32_16x16x32_bf16 v[98:101], v[172:175], v[188:191], v[98:101]
	v_mfma_f32_16x16x32_bf16 v[114:117], v[168:171], v[176:179], v[114:117]
	v_mfma_f32_16x16x32_bf16 v[114:117], v[172:175], v[180:183], v[114:117]
	s_setprio 0
	s_barrier
	s_mov_b32 m0, s46
	s_add_i32 s76, s75, 0x80
	ds_read_b128 v[176:179], v136 offset:49152
	ds_read_b128 v[180:183], v136 offset:50176
	ds_read_b128 v[184:187], v136 offset:51200
	ds_read_b128 v[188:191], v136 offset:52224
	ds_read_b128 v[192:195], v136 offset:53248
	ds_read_b128 v[196:199], v136 offset:54272
	ds_read_b128 v[200:203], v136 offset:55296
	ds_read_b128 v[204:207], v136 offset:56320
	buffer_load_dwordx4 v133, s[16:19], s76 offen lds
	s_add_i32 s76, s75, 0x200080
	s_mov_b32 m0, s47
	s_add_i32 s73, s73, 0x18080
	buffer_load_dwordx4 v133, s[16:19], s76 offen lds
	s_add_i32 s76, s75, 0x400080
	s_mov_b32 m0, s50
	s_add_i32 s75, s75, 0x600080
	buffer_load_dwordx4 v133, s[16:19], s76 offen lds
	s_mov_b32 m0, s51
	s_nop 0
	buffer_load_dwordx4 v133, s[16:19], s75 offen lds
	s_mov_b32 m0, s48
	s_nop 0
	buffer_load_dwordx4 v132, s[12:15], s74 offen lds
	s_mov_b32 m0, s49
	s_nop 0
	buffer_load_dwordx4 v132, s[12:15], s73 offen lds
	s_waitcnt vmcnt(8) lgkmcnt(0)
	s_setprio 1
	v_mfma_f32_16x16x32_bf16 v[62:65], v[140:143], v[176:179], v[62:65]
	s_barrier
	v_mfma_f32_16x16x32_bf16 v[62:65], v[148:151], v[180:183], v[62:65]
	v_mfma_f32_16x16x32_bf16 v[46:49], v[140:143], v[184:187], v[46:49]
	v_mfma_f32_16x16x32_bf16 v[46:49], v[148:151], v[188:191], v[46:49]
	v_mfma_f32_16x16x32_bf16 v[30:33], v[140:143], v[192:195], v[30:33]
	v_mfma_f32_16x16x32_bf16 v[30:33], v[148:151], v[196:199], v[30:33]
	v_mfma_f32_16x16x32_bf16 v[14:17], v[140:143], v[200:203], v[14:17]
	v_mfma_f32_16x16x32_bf16 v[14:17], v[148:151], v[204:207], v[14:17]
	v_mfma_f32_16x16x32_bf16 v[10:13], v[152:155], v[200:203], v[10:13]
	v_mfma_f32_16x16x32_bf16 v[10:13], v[156:159], v[204:207], v[10:13]
	v_mfma_f32_16x16x32_bf16 v[26:29], v[152:155], v[192:195], v[26:29]
	v_mfma_f32_16x16x32_bf16 v[26:29], v[156:159], v[196:199], v[26:29]
	v_mfma_f32_16x16x32_bf16 v[42:45], v[152:155], v[184:187], v[42:45]
	v_mfma_f32_16x16x32_bf16 v[42:45], v[156:159], v[188:191], v[42:45]
	v_mfma_f32_16x16x32_bf16 v[58:61], v[152:155], v[176:179], v[58:61]
	v_mfma_f32_16x16x32_bf16 v[58:61], v[156:159], v[180:183], v[58:61]
	v_mfma_f32_16x16x32_bf16 v[54:57], v[160:163], v[176:179], v[54:57]
	v_mfma_f32_16x16x32_bf16 v[54:57], v[164:167], v[180:183], v[54:57]
	v_mfma_f32_16x16x32_bf16 v[38:41], v[160:163], v[184:187], v[38:41]
	v_mfma_f32_16x16x32_bf16 v[38:41], v[164:167], v[188:191], v[38:41]
	v_mfma_f32_16x16x32_bf16 v[22:25], v[160:163], v[192:195], v[22:25]
	v_mfma_f32_16x16x32_bf16 v[22:25], v[164:167], v[196:199], v[22:25]
	v_mfma_f32_16x16x32_bf16 v[6:9], v[160:163], v[200:203], v[6:9]
	v_mfma_f32_16x16x32_bf16 v[6:9], v[164:167], v[204:207], v[6:9]
	v_mfma_f32_16x16x32_bf16 v[2:5], v[168:171], v[200:203], v[2:5]
	v_mfma_f32_16x16x32_bf16 v[2:5], v[172:175], v[204:207], v[2:5]
	v_mfma_f32_16x16x32_bf16 v[18:21], v[168:171], v[192:195], v[18:21]
	v_mfma_f32_16x16x32_bf16 v[18:21], v[172:175], v[196:199], v[18:21]
	v_mfma_f32_16x16x32_bf16 v[34:37], v[168:171], v[184:187], v[34:37]
	v_mfma_f32_16x16x32_bf16 v[34:37], v[172:175], v[188:191], v[34:37]
	v_mfma_f32_16x16x32_bf16 v[50:53], v[168:171], v[176:179], v[50:53]
	v_mfma_f32_16x16x32_bf16 v[50:53], v[172:175], v[180:183], v[50:53]
	s_setprio 0
	s_barrier
	s_add_i32 s72, s72, 2
	s_addk_i32 s70, 0x100
	s_addk_i32 s71, 0x100
	s_cmp_ge_i32 s72, s21
	s_cbranch_scc0 .LBB0_1035

.LBB0_1050:
	ds_read_b128 v[132:135], v142
	ds_read_b128 v[136:139], v142 offset:1024
	ds_read_b128 v[148:151], v142 offset:2048
	ds_read_b128 v[152:155], v142 offset:3072
	ds_read_b128 v[156:159], v143
	ds_read_b128 v[160:163], v143 offset:1024
	ds_read_b128 v[164:167], v143 offset:2048
	ds_read_b128 v[168:171], v143 offset:3072
	s_add_i32 s18, s61, 0xfff40080
	s_cmp_eq_u32 s54, s62
	s_cselect_b32 s64, s35, s18
	s_add_i32 s63, s64, 0x80
	s_add_i32 s18, s61, 0xfffc0000
	s_mov_b32 m0, s55
	ds_read_b128 v[172:175], v144
	ds_read_b128 v[176:179], v144 offset:1024
	ds_read_b128 v[180:183], v144 offset:2048
	ds_read_b128 v[184:187], v144 offset:3072
	ds_read_b128 v[188:191], v144 offset:4096
	ds_read_b128 v[192:195], v144 offset:5120
	ds_read_b128 v[196:199], v144 offset:6144
	ds_read_b128 v[200:203], v144 offset:7168
	buffer_load_dwordx4 v140, s[12:15], s18 offen lds
	s_mov_b32 m0, s56
	s_nop 0
	buffer_load_dwordx4 v140, s[12:15], s61 offen lds
	s_waitcnt vmcnt(8) lgkmcnt(0)
	s_setprio 1
	v_mfma_f32_16x16x32_bf16 v[126:129], v[132:135], v[172:175], v[126:129]
	s_barrier
	v_mfma_f32_16x16x32_bf16 v[126:129], v[136:139], v[176:179], v[126:129]
	v_mfma_f32_16x16x32_bf16 v[110:113], v[132:135], v[180:183], v[110:113]
	v_mfma_f32_16x16x32_bf16 v[110:113], v[136:139], v[184:187], v[110:113]
	v_mfma_f32_16x16x32_bf16 v[94:97], v[132:135], v[188:191], v[94:97]
	v_mfma_f32_16x16x32_bf16 v[94:97], v[136:139], v[192:195], v[94:97]
	v_mfma_f32_16x16x32_bf16 v[78:81], v[132:135], v[196:199], v[78:81]
	v_mfma_f32_16x16x32_bf16 v[78:81], v[136:139], v[200:203], v[78:81]
	v_mfma_f32_16x16x32_bf16 v[74:77], v[148:151], v[196:199], v[74:77]
	v_mfma_f32_16x16x32_bf16 v[74:77], v[152:155], v[200:203], v[74:77]
	v_mfma_f32_16x16x32_bf16 v[90:93], v[148:151], v[188:191], v[90:93]
	v_mfma_f32_16x16x32_bf16 v[90:93], v[152:155], v[192:195], v[90:93]
	v_mfma_f32_16x16x32_bf16 v[106:109], v[148:151], v[180:183], v[106:109]
	v_mfma_f32_16x16x32_bf16 v[106:109], v[152:155], v[184:187], v[106:109]
	v_mfma_f32_16x16x32_bf16 v[122:125], v[148:151], v[172:175], v[122:125]
	v_mfma_f32_16x16x32_bf16 v[122:125], v[152:155], v[176:179], v[122:125]
	v_mfma_f32_16x16x32_bf16 v[118:121], v[156:159], v[172:175], v[118:121]
	v_mfma_f32_16x16x32_bf16 v[118:121], v[160:163], v[176:179], v[118:121]
	v_mfma_f32_16x16x32_bf16 v[102:105], v[156:159], v[180:183], v[102:105]
	v_mfma_f32_16x16x32_bf16 v[102:105], v[160:163], v[184:187], v[102:105]
	v_mfma_f32_16x16x32_bf16 v[86:89], v[156:159], v[188:191], v[86:89]
	v_mfma_f32_16x16x32_bf16 v[86:89], v[160:163], v[192:195], v[86:89]
	v_mfma_f32_16x16x32_bf16 v[70:73], v[156:159], v[196:199], v[70:73]
	v_mfma_f32_16x16x32_bf16 v[70:73], v[160:163], v[200:203], v[70:73]
	v_mfma_f32_16x16x32_bf16 v[66:69], v[164:167], v[196:199], v[66:69]
	v_mfma_f32_16x16x32_bf16 v[66:69], v[168:171], v[200:203], v[66:69]
	v_mfma_f32_16x16x32_bf16 v[82:85], v[164:167], v[188:191], v[82:85]
	v_mfma_f32_16x16x32_bf16 v[82:85], v[168:171], v[192:195], v[82:85]
	v_mfma_f32_16x16x32_bf16 v[98:101], v[164:167], v[180:183], v[98:101]
	v_mfma_f32_16x16x32_bf16 v[98:101], v[168:171], v[184:187], v[98:101]
	v_mfma_f32_16x16x32_bf16 v[114:117], v[164:167], v[172:175], v[114:117]
	v_mfma_f32_16x16x32_bf16 v[114:117], v[168:171], v[176:179], v[114:117]
	s_setprio 0
	s_barrier
	s_mov_b32 m0, s25
	s_mov_b32 s18, s14
	s_mov_b32 s19, s15
	ds_read_b128 v[172:175], v144 offset:16384
	ds_read_b128 v[176:179], v144 offset:17408
	ds_read_b128 v[180:183], v144 offset:18432
	ds_read_b128 v[184:187], v144 offset:19456
	ds_read_b128 v[188:191], v144 offset:20480
	ds_read_b128 v[192:195], v144 offset:21504
	ds_read_b128 v[196:199], v144 offset:22528
	ds_read_b128 v[200:203], v144 offset:23552
	buffer_load_dwordx4 v141, s[16:19], s64 offen lds
	s_add_i32 s65, s64, 0x40000
	s_mov_b32 m0, s27
	s_add_i32 s66, s64, 0x80000
	buffer_load_dwordx4 v141, s[16:19], s65 offen lds
	s_mov_b32 m0, s30
	s_add_i32 s67, s64, 0xc0000
	buffer_load_dwordx4 v141, s[16:19], s66 offen lds
	s_mov_b32 m0, s31
	s_nop 0
	buffer_load_dwordx4 v141, s[16:19], s67 offen lds
	s_mov_b32 m0, s21
	s_nop 0
	buffer_load_dwordx4 v140, s[12:15], s64 offen lds
	s_mov_b32 m0, s38
	s_nop 0
	buffer_load_dwordx4 v140, s[12:15], s65 offen lds
	s_waitcnt vmcnt(8) lgkmcnt(0)
	s_setprio 1
	v_mfma_f32_16x16x32_bf16 v[62:65], v[132:135], v[172:175], v[62:65]
	s_barrier
	v_mfma_f32_16x16x32_bf16 v[62:65], v[136:139], v[176:179], v[62:65]
	v_mfma_f32_16x16x32_bf16 v[46:49], v[132:135], v[180:183], v[46:49]
	v_mfma_f32_16x16x32_bf16 v[46:49], v[136:139], v[184:187], v[46:49]
	v_mfma_f32_16x16x32_bf16 v[30:33], v[132:135], v[188:191], v[30:33]
	v_mfma_f32_16x16x32_bf16 v[30:33], v[136:139], v[192:195], v[30:33]
	v_mfma_f32_16x16x32_bf16 v[14:17], v[132:135], v[196:199], v[14:17]
	v_mfma_f32_16x16x32_bf16 v[14:17], v[136:139], v[200:203], v[14:17]
	v_mfma_f32_16x16x32_bf16 v[10:13], v[148:151], v[196:199], v[10:13]
	v_mfma_f32_16x16x32_bf16 v[10:13], v[152:155], v[200:203], v[10:13]
	v_mfma_f32_16x16x32_bf16 v[26:29], v[148:151], v[188:191], v[26:29]
	v_mfma_f32_16x16x32_bf16 v[26:29], v[152:155], v[192:195], v[26:29]
	v_mfma_f32_16x16x32_bf16 v[42:45], v[148:151], v[180:183], v[42:45]
	v_mfma_f32_16x16x32_bf16 v[42:45], v[152:155], v[184:187], v[42:45]
	v_mfma_f32_16x16x32_bf16 v[58:61], v[148:151], v[172:175], v[58:61]
	v_mfma_f32_16x16x32_bf16 v[58:61], v[152:155], v[176:179], v[58:61]
	v_mfma_f32_16x16x32_bf16 v[54:57], v[156:159], v[172:175], v[54:57]
	v_mfma_f32_16x16x32_bf16 v[54:57], v[160:163], v[176:179], v[54:57]
	v_mfma_f32_16x16x32_bf16 v[38:41], v[156:159], v[180:183], v[38:41]
	v_mfma_f32_16x16x32_bf16 v[38:41], v[160:163], v[184:187], v[38:41]
	v_mfma_f32_16x16x32_bf16 v[22:25], v[156:159], v[188:191], v[22:25]
	v_mfma_f32_16x16x32_bf16 v[22:25], v[160:163], v[192:195], v[22:25]
	v_mfma_f32_16x16x32_bf16 v[6:9], v[156:159], v[196:199], v[6:9]
	v_mfma_f32_16x16x32_bf16 v[6:9], v[160:163], v[200:203], v[6:9]
	v_mfma_f32_16x16x32_bf16 v[2:5], v[164:167], v[196:199], v[2:5]
	v_mfma_f32_16x16x32_bf16 v[2:5], v[168:171], v[200:203], v[2:5]
	v_mfma_f32_16x16x32_bf16 v[18:21], v[164:167], v[188:191], v[18:21]
	v_mfma_f32_16x16x32_bf16 v[18:21], v[168:171], v[192:195], v[18:21]
	v_mfma_f32_16x16x32_bf16 v[34:37], v[164:167], v[180:183], v[34:37]
	v_mfma_f32_16x16x32_bf16 v[34:37], v[168:171], v[184:187], v[34:37]
	v_mfma_f32_16x16x32_bf16 v[50:53], v[164:167], v[172:175], v[50:53]
	v_mfma_f32_16x16x32_bf16 v[50:53], v[168:171], v[176:179], v[50:53]
	s_setprio 0
	s_barrier
	ds_read_b128 v[132:135], v145
	ds_read_b128 v[136:139], v145 offset:1024
	ds_read_b128 v[148:151], v145 offset:2048
	ds_read_b128 v[152:155], v145 offset:3072
	ds_read_b128 v[156:159], v147
	ds_read_b128 v[160:163], v147 offset:1024
	ds_read_b128 v[164:167], v147 offset:2048
	ds_read_b128 v[168:171], v147 offset:3072
	s_mov_b32 m0, s39
	ds_read_b128 v[172:175], v144 offset:32768
	ds_read_b128 v[176:179], v144 offset:33792
	ds_read_b128 v[180:183], v144 offset:34816
	ds_read_b128 v[184:187], v144 offset:35840
	ds_read_b128 v[188:191], v144 offset:36864
	ds_read_b128 v[192:195], v144 offset:37888
	ds_read_b128 v[196:199], v144 offset:38912
	ds_read_b128 v[200:203], v144 offset:39936
	buffer_load_dwordx4 v140, s[12:15], s66 offen lds
	s_mov_b32 m0, s40
	s_nop 0
	buffer_load_dwordx4 v140, s[12:15], s67 offen lds
	s_waitcnt vmcnt(8) lgkmcnt(0)
	s_setprio 1
	v_mfma_f32_16x16x32_bf16 v[126:129], v[132:135], v[172:175], v[126:129]
	s_barrier
	v_mfma_f32_16x16x32_bf16 v[126:129], v[136:139], v[176:179], v[126:129]
	v_mfma_f32_16x16x32_bf16 v[110:113], v[132:135], v[180:183], v[110:113]
	v_mfma_f32_16x16x32_bf16 v[110:113], v[136:139], v[184:187], v[110:113]
	v_mfma_f32_16x16x32_bf16 v[94:97], v[132:135], v[188:191], v[94:97]
	v_mfma_f32_16x16x32_bf16 v[94:97], v[136:139], v[192:195], v[94:97]
	v_mfma_f32_16x16x32_bf16 v[78:81], v[132:135], v[196:199], v[78:81]
	v_mfma_f32_16x16x32_bf16 v[78:81], v[136:139], v[200:203], v[78:81]
	v_mfma_f32_16x16x32_bf16 v[74:77], v[148:151], v[196:199], v[74:77]
	v_mfma_f32_16x16x32_bf16 v[74:77], v[152:155], v[200:203], v[74:77]
	v_mfma_f32_16x16x32_bf16 v[90:93], v[148:151], v[188:191], v[90:93]
	v_mfma_f32_16x16x32_bf16 v[90:93], v[152:155], v[192:195], v[90:93]
	v_mfma_f32_16x16x32_bf16 v[106:109], v[148:151], v[180:183], v[106:109]
	v_mfma_f32_16x16x32_bf16 v[106:109], v[152:155], v[184:187], v[106:109]
	v_mfma_f32_16x16x32_bf16 v[122:125], v[148:151], v[172:175], v[122:125]
	v_mfma_f32_16x16x32_bf16 v[122:125], v[152:155], v[176:179], v[122:125]
	v_mfma_f32_16x16x32_bf16 v[118:121], v[156:159], v[172:175], v[118:121]
	v_mfma_f32_16x16x32_bf16 v[118:121], v[160:163], v[176:179], v[118:121]
	v_mfma_f32_16x16x32_bf16 v[102:105], v[156:159], v[180:183], v[102:105]
	v_mfma_f32_16x16x32_bf16 v[102:105], v[160:163], v[184:187], v[102:105]
	v_mfma_f32_16x16x32_bf16 v[86:89], v[156:159], v[188:191], v[86:89]
	v_mfma_f32_16x16x32_bf16 v[86:89], v[160:163], v[192:195], v[86:89]
	v_mfma_f32_16x16x32_bf16 v[70:73], v[156:159], v[196:199], v[70:73]
	v_mfma_f32_16x16x32_bf16 v[70:73], v[160:163], v[200:203], v[70:73]
	v_mfma_f32_16x16x32_bf16 v[66:69], v[164:167], v[196:199], v[66:69]
	v_mfma_f32_16x16x32_bf16 v[66:69], v[168:171], v[200:203], v[66:69]
	v_mfma_f32_16x16x32_bf16 v[82:85], v[164:167], v[188:191], v[82:85]
	v_mfma_f32_16x16x32_bf16 v[82:85], v[168:171], v[192:195], v[82:85]
	v_mfma_f32_16x16x32_bf16 v[98:101], v[164:167], v[180:183], v[98:101]
	v_mfma_f32_16x16x32_bf16 v[98:101], v[168:171], v[184:187], v[98:101]
	v_mfma_f32_16x16x32_bf16 v[114:117], v[164:167], v[172:175], v[114:117]
	v_mfma_f32_16x16x32_bf16 v[114:117], v[168:171], v[176:179], v[114:117]
	s_setprio 0
	s_barrier
	s_mov_b32 m0, s48
	ds_read_b128 v[172:175], v144 offset:49152
	ds_read_b128 v[176:179], v144 offset:50176
	ds_read_b128 v[180:183], v144 offset:51200
	ds_read_b128 v[184:187], v144 offset:52224
	ds_read_b128 v[188:191], v144 offset:53248
	ds_read_b128 v[192:195], v144 offset:54272
	ds_read_b128 v[196:199], v144 offset:55296
	ds_read_b128 v[200:203], v144 offset:56320
	buffer_load_dwordx4 v141, s[16:19], s63 offen lds
	s_add_i32 s65, s64, 0x40080
	s_mov_b32 m0, s49
	s_add_i32 s66, s64, 0x80080
	buffer_load_dwordx4 v141, s[16:19], s65 offen lds
	s_mov_b32 m0, s52
	s_add_i32 s64, s64, 0xc0080
	buffer_load_dwordx4 v141, s[16:19], s66 offen lds
	s_mov_b32 m0, s53
	s_nop 0
	buffer_load_dwordx4 v141, s[16:19], s64 offen lds
	s_mov_b32 m0, s50
	s_nop 0
	buffer_load_dwordx4 v140, s[12:15], s63 offen lds
	s_mov_b32 m0, s51
	s_nop 0
	buffer_load_dwordx4 v140, s[12:15], s65 offen lds
	s_waitcnt vmcnt(8) lgkmcnt(0)
	s_setprio 1
	v_mfma_f32_16x16x32_bf16 v[62:65], v[132:135], v[172:175], v[62:65]
	s_barrier
	v_mfma_f32_16x16x32_bf16 v[62:65], v[136:139], v[176:179], v[62:65]
	v_mfma_f32_16x16x32_bf16 v[46:49], v[132:135], v[180:183], v[46:49]
	v_mfma_f32_16x16x32_bf16 v[46:49], v[136:139], v[184:187], v[46:49]
	v_mfma_f32_16x16x32_bf16 v[30:33], v[132:135], v[188:191], v[30:33]
	v_mfma_f32_16x16x32_bf16 v[30:33], v[136:139], v[192:195], v[30:33]
	v_mfma_f32_16x16x32_bf16 v[14:17], v[132:135], v[196:199], v[14:17]
	v_mfma_f32_16x16x32_bf16 v[14:17], v[136:139], v[200:203], v[14:17]
	v_mfma_f32_16x16x32_bf16 v[10:13], v[148:151], v[196:199], v[10:13]
	v_mfma_f32_16x16x32_bf16 v[10:13], v[152:155], v[200:203], v[10:13]
	v_mfma_f32_16x16x32_bf16 v[26:29], v[148:151], v[188:191], v[26:29]
	v_mfma_f32_16x16x32_bf16 v[26:29], v[152:155], v[192:195], v[26:29]
	v_mfma_f32_16x16x32_bf16 v[42:45], v[148:151], v[180:183], v[42:45]
	v_mfma_f32_16x16x32_bf16 v[42:45], v[152:155], v[184:187], v[42:45]
	v_mfma_f32_16x16x32_bf16 v[58:61], v[148:151], v[172:175], v[58:61]
	v_mfma_f32_16x16x32_bf16 v[58:61], v[152:155], v[176:179], v[58:61]
	v_mfma_f32_16x16x32_bf16 v[54:57], v[156:159], v[172:175], v[54:57]
	v_mfma_f32_16x16x32_bf16 v[54:57], v[160:163], v[176:179], v[54:57]
	v_mfma_f32_16x16x32_bf16 v[38:41], v[156:159], v[180:183], v[38:41]
	v_mfma_f32_16x16x32_bf16 v[38:41], v[160:163], v[184:187], v[38:41]
	v_mfma_f32_16x16x32_bf16 v[22:25], v[156:159], v[188:191], v[22:25]
	v_mfma_f32_16x16x32_bf16 v[22:25], v[160:163], v[192:195], v[22:25]
	v_mfma_f32_16x16x32_bf16 v[6:9], v[156:159], v[196:199], v[6:9]
	v_mfma_f32_16x16x32_bf16 v[6:9], v[160:163], v[200:203], v[6:9]
	v_mfma_f32_16x16x32_bf16 v[2:5], v[164:167], v[196:199], v[2:5]
	v_mfma_f32_16x16x32_bf16 v[2:5], v[168:171], v[200:203], v[2:5]
	v_mfma_f32_16x16x32_bf16 v[18:21], v[164:167], v[188:191], v[18:21]
	v_mfma_f32_16x16x32_bf16 v[18:21], v[168:171], v[192:195], v[18:21]
	v_mfma_f32_16x16x32_bf16 v[34:37], v[164:167], v[180:183], v[34:37]
	v_mfma_f32_16x16x32_bf16 v[34:37], v[168:171], v[184:187], v[34:37]
	v_mfma_f32_16x16x32_bf16 v[50:53], v[164:167], v[172:175], v[50:53]
	v_mfma_f32_16x16x32_bf16 v[50:53], v[168:171], v[176:179], v[50:53]
	s_setprio 0
	s_barrier
	s_add_i32 s62, s62, 2
	s_addk_i32 s61, 0x100
	s_cmp_ge_i32 s62, s3
	s_cbranch_scc0 .LBB0_1050

.LBB0_1181:
	v_add_u32_e32 v2, 0x10000, v232
	ds_read_b128 v[134:137], v2
	ds_read_b128 v[138:141], v2 offset:1024
	ds_read_b128 v[142:145], v2 offset:2048
	ds_read_b128 v[146:149], v2 offset:3072
	v_add_u32_e32 v2, 0x14000, v232
	ds_read_b128 v[150:153], v2
	ds_read_b128 v[154:157], v2 offset:1024
	ds_read_b128 v[158:161], v2 offset:2048
	ds_read_b128 v[162:165], v2 offset:3072
	s_add_i32 s50, s47, s90
	s_and_b64 s[18:19], exec, s[18:19]
	s_cselect_b32 s51, s88, s50
	s_add_i32 s50, s92, 0x80
	s_or_b32 s52, s51, 0x80
	s_add_i32 s18, s89, s93
	s_add_i32 s94, s94, 0x1bfffc80
	s_cmp_lt_u32 s91, 8
	s_cselect_b32 s18, s18, s94
	s_mov_b32 m0, s74
	s_add_i32 s19, s18, 0x80000
	ds_read_b128 v[166:169], v233
	ds_read_b128 v[170:173], v233 offset:1024
	ds_read_b128 v[174:177], v233 offset:2048
	ds_read_b128 v[178:181], v233 offset:3072
	ds_read_b128 v[182:185], v233 offset:4096
	ds_read_b128 v[186:189], v233 offset:5120
	ds_read_b128 v[190:193], v233 offset:6144
	ds_read_b128 v[194:197], v233 offset:7168
	buffer_load_dwordx4 v230, s[12:15], s19 offen lds
	s_mov_b32 m0, s75
	s_add_i32 s18, s18, 0xc0000
	buffer_load_dwordx4 v230, s[12:15], s18 offen lds
	s_waitcnt vmcnt(8) lgkmcnt(0)
	s_setprio 1
	v_mfma_f32_16x16x32_bf16 v[130:133], v[134:137], v[166:169], v[130:133]
	s_barrier
	v_mfma_f32_16x16x32_bf16 v[130:133], v[138:141], v[170:173], v[130:133]
	v_mfma_f32_16x16x32_bf16 v[114:117], v[134:137], v[174:177], v[114:117]
	v_mfma_f32_16x16x32_bf16 v[114:117], v[138:141], v[178:181], v[114:117]
	v_mfma_f32_16x16x32_bf16 v[98:101], v[134:137], v[182:185], v[98:101]
	v_mfma_f32_16x16x32_bf16 v[98:101], v[138:141], v[186:189], v[98:101]
	v_mfma_f32_16x16x32_bf16 v[82:85], v[134:137], v[190:193], v[82:85]
	v_mfma_f32_16x16x32_bf16 v[82:85], v[138:141], v[194:197], v[82:85]
	v_mfma_f32_16x16x32_bf16 v[78:81], v[142:145], v[190:193], v[78:81]
	v_mfma_f32_16x16x32_bf16 v[78:81], v[146:149], v[194:197], v[78:81]
	v_mfma_f32_16x16x32_bf16 v[94:97], v[142:145], v[182:185], v[94:97]
	v_mfma_f32_16x16x32_bf16 v[94:97], v[146:149], v[186:189], v[94:97]
	v_mfma_f32_16x16x32_bf16 v[110:113], v[142:145], v[174:177], v[110:113]
	v_mfma_f32_16x16x32_bf16 v[110:113], v[146:149], v[178:181], v[110:113]
	v_mfma_f32_16x16x32_bf16 v[126:129], v[142:145], v[166:169], v[126:129]
	v_mfma_f32_16x16x32_bf16 v[126:129], v[146:149], v[170:173], v[126:129]
	v_mfma_f32_16x16x32_bf16 v[122:125], v[150:153], v[166:169], v[122:125]
	v_mfma_f32_16x16x32_bf16 v[122:125], v[154:157], v[170:173], v[122:125]
	v_mfma_f32_16x16x32_bf16 v[106:109], v[150:153], v[174:177], v[106:109]
	v_mfma_f32_16x16x32_bf16 v[106:109], v[154:157], v[178:181], v[106:109]
	v_mfma_f32_16x16x32_bf16 v[90:93], v[150:153], v[182:185], v[90:93]
	v_mfma_f32_16x16x32_bf16 v[90:93], v[154:157], v[186:189], v[90:93]
	v_mfma_f32_16x16x32_bf16 v[74:77], v[150:153], v[190:193], v[74:77]
	v_mfma_f32_16x16x32_bf16 v[74:77], v[154:157], v[194:197], v[74:77]
	v_mfma_f32_16x16x32_bf16 v[70:73], v[158:161], v[190:193], v[70:73]
	v_mfma_f32_16x16x32_bf16 v[70:73], v[162:165], v[194:197], v[70:73]
	v_mfma_f32_16x16x32_bf16 v[86:89], v[158:161], v[182:185], v[86:89]
	v_mfma_f32_16x16x32_bf16 v[86:89], v[162:165], v[186:189], v[86:89]
	v_mfma_f32_16x16x32_bf16 v[102:105], v[158:161], v[174:177], v[102:105]
	v_mfma_f32_16x16x32_bf16 v[102:105], v[162:165], v[178:181], v[102:105]
	v_mfma_f32_16x16x32_bf16 v[118:121], v[158:161], v[166:169], v[118:121]
	v_mfma_f32_16x16x32_bf16 v[118:121], v[162:165], v[170:173], v[118:121]
	s_setprio 0
	s_barrier
	s_mov_b32 m0, s27
	s_mov_b32 s18, s14
	s_mov_b32 s19, s15
	ds_read_b128 v[166:169], v233 offset:16384
	ds_read_b128 v[170:173], v233 offset:17408
	ds_read_b128 v[174:177], v233 offset:18432
	ds_read_b128 v[178:181], v233 offset:19456
	ds_read_b128 v[182:185], v233 offset:20480
	ds_read_b128 v[186:189], v233 offset:21504
	ds_read_b128 v[190:193], v233 offset:22528
	ds_read_b128 v[194:197], v233 offset:23552
	buffer_load_dwordx4 v231, s[16:19], s51 offen lds
	s_mov_b32 m0, s30
	s_add_i32 s53, s51, 0x18000
	buffer_load_dwordx4 v231, s[16:19], s53 offen lds
	s_mov_b32 m0, s31
	s_add_i32 s53, s51, 0x30000
	buffer_load_dwordx4 v231, s[16:19], s53 offen lds
	s_mov_b32 m0, s54
	s_add_i32 s53, s51, 0x48000
	buffer_load_dwordx4 v231, s[16:19], s53 offen lds
	s_mov_b32 m0, s25
	s_add_i32 s53, s92, 0x40000
	buffer_load_dwordx4 v230, s[12:15], s92 offen lds
	s_mov_b32 m0, s55
	s_nop 0
	buffer_load_dwordx4 v230, s[12:15], s53 offen lds
	s_waitcnt vmcnt(8) lgkmcnt(0)
	s_setprio 1
	v_mfma_f32_16x16x32_bf16 v[66:69], v[134:137], v[166:169], v[66:69]
	s_barrier
	v_mfma_f32_16x16x32_bf16 v[62:65], v[142:145], v[166:169], v[62:65]
	v_mfma_f32_16x16x32_bf16 v[50:53], v[134:137], v[174:177], v[50:53]
	v_mfma_f32_16x16x32_bf16 v[46:49], v[142:145], v[174:177], v[46:49]
	v_mfma_f32_16x16x32_bf16 v[34:37], v[134:137], v[182:185], v[34:37]
	v_mfma_f32_16x16x32_bf16 v[30:33], v[142:145], v[182:185], v[30:33]
	v_mfma_f32_16x16x32_bf16 v[18:21], v[134:137], v[190:193], v[18:21]
	v_mfma_f32_16x16x32_bf16 v[14:17], v[142:145], v[190:193], v[14:17]
	v_mfma_f32_16x16x32_bf16 v[58:61], v[150:153], v[166:169], v[58:61]
	v_mfma_f32_16x16x32_bf16 v[54:57], v[158:161], v[166:169], v[54:57]
	v_mfma_f32_16x16x32_bf16 v[42:45], v[150:153], v[174:177], v[42:45]
	v_mfma_f32_16x16x32_bf16 v[38:41], v[158:161], v[174:177], v[38:41]
	v_mfma_f32_16x16x32_bf16 v[26:29], v[150:153], v[182:185], v[26:29]
	v_mfma_f32_16x16x32_bf16 v[22:25], v[158:161], v[182:185], v[22:25]
	v_mfma_f32_16x16x32_bf16 v[10:13], v[150:153], v[190:193], v[10:13]
	v_mfma_f32_16x16x32_bf16 v[4:7], v[158:161], v[190:193], v[6:9]
	v_mfma_f32_16x16x32_bf16 v[66:69], v[138:141], v[170:173], v[66:69]
	v_mfma_f32_16x16x32_bf16 v[62:65], v[146:149], v[170:173], v[62:65]
	v_mfma_f32_16x16x32_bf16 v[50:53], v[138:141], v[178:181], v[50:53]
	v_mfma_f32_16x16x32_bf16 v[46:49], v[146:149], v[178:181], v[46:49]
	v_mfma_f32_16x16x32_bf16 v[34:37], v[138:141], v[186:189], v[34:37]
	v_mfma_f32_16x16x32_bf16 v[30:33], v[146:149], v[186:189], v[30:33]
	v_mfma_f32_16x16x32_bf16 v[18:21], v[138:141], v[194:197], v[18:21]
	v_mfma_f32_16x16x32_bf16 v[14:17], v[146:149], v[194:197], v[14:17]
	v_mfma_f32_16x16x32_bf16 v[58:61], v[154:157], v[170:173], v[58:61]
	v_mfma_f32_16x16x32_bf16 v[54:57], v[162:165], v[170:173], v[54:57]
	v_mfma_f32_16x16x32_bf16 v[42:45], v[154:157], v[178:181], v[42:45]
	v_mfma_f32_16x16x32_bf16 v[38:41], v[162:165], v[178:181], v[38:41]
	v_mfma_f32_16x16x32_bf16 v[26:29], v[154:157], v[186:189], v[26:29]
	v_mfma_f32_16x16x32_bf16 v[22:25], v[162:165], v[186:189], v[22:25]
	v_mfma_f32_16x16x32_bf16 v[10:13], v[154:157], v[194:197], v[10:13]
	v_mfma_f32_16x16x32_bf16 v[4:7], v[162:165], v[194:197], v[4:7]
	s_setprio 0
	s_barrier
	v_add_u32_e32 v2, 0x18000, v232
	ds_read_b128 v[134:137], v2
	ds_read_b128 v[138:141], v2 offset:1024
	ds_read_b128 v[142:145], v2 offset:2048
	ds_read_b128 v[146:149], v2 offset:3072
	v_add_u32_e32 v2, 0x1c000, v232
	ds_read_b128 v[150:153], v2
	ds_read_b128 v[154:157], v2 offset:1024
	ds_read_b128 v[158:161], v2 offset:2048
	ds_read_b128 v[162:165], v2 offset:3072
	s_mov_b32 m0, s56
	s_add_i32 s53, s92, 0x80000
	ds_read_b128 v[166:169], v233 offset:32768
	ds_read_b128 v[170:173], v233 offset:33792
	ds_read_b128 v[174:177], v233 offset:34816
	ds_read_b128 v[178:181], v233 offset:35840
	ds_read_b128 v[182:185], v233 offset:36864
	ds_read_b128 v[186:189], v233 offset:37888
	ds_read_b128 v[190:193], v233 offset:38912
	ds_read_b128 v[194:197], v233 offset:39936
	buffer_load_dwordx4 v230, s[12:15], s53 offen lds
	s_mov_b32 m0, s57
	s_add_i32 s53, s92, 0xc0000
	buffer_load_dwordx4 v230, s[12:15], s53 offen lds
	s_waitcnt vmcnt(8) lgkmcnt(0)
	s_setprio 1
	v_mfma_f32_16x16x32_bf16 v[130:133], v[134:137], v[166:169], v[130:133]
	s_barrier
	v_mfma_f32_16x16x32_bf16 v[130:133], v[138:141], v[170:173], v[130:133]
	v_mfma_f32_16x16x32_bf16 v[114:117], v[134:137], v[174:177], v[114:117]
	v_mfma_f32_16x16x32_bf16 v[114:117], v[138:141], v[178:181], v[114:117]
	v_mfma_f32_16x16x32_bf16 v[98:101], v[134:137], v[182:185], v[98:101]
	v_mfma_f32_16x16x32_bf16 v[98:101], v[138:141], v[186:189], v[98:101]
	v_mfma_f32_16x16x32_bf16 v[82:85], v[134:137], v[190:193], v[82:85]
	v_mfma_f32_16x16x32_bf16 v[82:85], v[138:141], v[194:197], v[82:85]
	v_mfma_f32_16x16x32_bf16 v[78:81], v[142:145], v[190:193], v[78:81]
	v_mfma_f32_16x16x32_bf16 v[78:81], v[146:149], v[194:197], v[78:81]
	v_mfma_f32_16x16x32_bf16 v[94:97], v[142:145], v[182:185], v[94:97]
	v_mfma_f32_16x16x32_bf16 v[94:97], v[146:149], v[186:189], v[94:97]
	v_mfma_f32_16x16x32_bf16 v[110:113], v[142:145], v[174:177], v[110:113]
	v_mfma_f32_16x16x32_bf16 v[110:113], v[146:149], v[178:181], v[110:113]
	v_mfma_f32_16x16x32_bf16 v[126:129], v[142:145], v[166:169], v[126:129]
	v_mfma_f32_16x16x32_bf16 v[126:129], v[146:149], v[170:173], v[126:129]
	v_mfma_f32_16x16x32_bf16 v[122:125], v[150:153], v[166:169], v[122:125]
	v_mfma_f32_16x16x32_bf16 v[122:125], v[154:157], v[170:173], v[122:125]
	v_mfma_f32_16x16x32_bf16 v[106:109], v[150:153], v[174:177], v[106:109]
	v_mfma_f32_16x16x32_bf16 v[106:109], v[154:157], v[178:181], v[106:109]
	v_mfma_f32_16x16x32_bf16 v[90:93], v[150:153], v[182:185], v[90:93]
	v_mfma_f32_16x16x32_bf16 v[90:93], v[154:157], v[186:189], v[90:93]
	v_mfma_f32_16x16x32_bf16 v[74:77], v[150:153], v[190:193], v[74:77]
	v_mfma_f32_16x16x32_bf16 v[74:77], v[154:157], v[194:197], v[74:77]
	v_mfma_f32_16x16x32_bf16 v[70:73], v[158:161], v[190:193], v[70:73]
	v_mfma_f32_16x16x32_bf16 v[70:73], v[162:165], v[194:197], v[70:73]
	v_mfma_f32_16x16x32_bf16 v[86:89], v[158:161], v[182:185], v[86:89]
	v_mfma_f32_16x16x32_bf16 v[86:89], v[162:165], v[186:189], v[86:89]
	v_mfma_f32_16x16x32_bf16 v[102:105], v[158:161], v[174:177], v[102:105]
	v_mfma_f32_16x16x32_bf16 v[102:105], v[162:165], v[178:181], v[102:105]
	v_mfma_f32_16x16x32_bf16 v[118:121], v[158:161], v[166:169], v[118:121]
	v_mfma_f32_16x16x32_bf16 v[118:121], v[162:165], v[170:173], v[118:121]
	s_setprio 0
	s_barrier
	s_mov_b32 m0, s64
	ds_read_b128 v[166:169], v233 offset:49152
	ds_read_b128 v[170:173], v233 offset:50176
	ds_read_b128 v[174:177], v233 offset:51200
	ds_read_b128 v[178:181], v233 offset:52224
	ds_read_b128 v[182:185], v233 offset:53248
	ds_read_b128 v[186:189], v233 offset:54272
	ds_read_b128 v[190:193], v233 offset:55296
	ds_read_b128 v[194:197], v233 offset:56320
	buffer_load_dwordx4 v231, s[16:19], s52 offen lds
	s_mov_b32 m0, s65
	s_add_i32 s52, s51, 0x18080
	buffer_load_dwordx4 v231, s[16:19], s52 offen lds
	s_add_i32 s52, s51, 0x30080
	s_mov_b32 m0, s68
	s_add_i32 s51, s51, 0x48080
	buffer_load_dwordx4 v231, s[16:19], s52 offen lds
	s_mov_b32 m0, s69
	s_nop 0
	buffer_load_dwordx4 v231, s[16:19], s51 offen lds
	s_mov_b32 m0, s66
	s_add_i32 s18, s92, 0x40080
	buffer_load_dwordx4 v230, s[12:15], s50 offen lds
	s_mov_b32 m0, s67
	s_nop 0
	buffer_load_dwordx4 v230, s[12:15], s18 offen lds
	s_waitcnt vmcnt(8) lgkmcnt(0)
	s_setprio 1
	v_mfma_f32_16x16x32_bf16 v[66:69], v[134:137], v[166:169], v[66:69]
	s_barrier
	v_mfma_f32_16x16x32_bf16 v[62:65], v[142:145], v[166:169], v[62:65]
	v_mfma_f32_16x16x32_bf16 v[50:53], v[134:137], v[174:177], v[50:53]
	v_mfma_f32_16x16x32_bf16 v[46:49], v[142:145], v[174:177], v[46:49]
	v_mfma_f32_16x16x32_bf16 v[34:37], v[134:137], v[182:185], v[34:37]
	v_mfma_f32_16x16x32_bf16 v[30:33], v[142:145], v[182:185], v[30:33]
	v_mfma_f32_16x16x32_bf16 v[18:21], v[134:137], v[190:193], v[18:21]
	v_mfma_f32_16x16x32_bf16 v[14:17], v[142:145], v[190:193], v[14:17]
	v_mfma_f32_16x16x32_bf16 v[58:61], v[150:153], v[166:169], v[58:61]
	v_mfma_f32_16x16x32_bf16 v[54:57], v[158:161], v[166:169], v[54:57]
	v_mfma_f32_16x16x32_bf16 v[42:45], v[150:153], v[174:177], v[42:45]
	v_mfma_f32_16x16x32_bf16 v[38:41], v[158:161], v[174:177], v[38:41]
	v_mfma_f32_16x16x32_bf16 v[26:29], v[150:153], v[182:185], v[26:29]
	v_mfma_f32_16x16x32_bf16 v[22:25], v[158:161], v[182:185], v[22:25]
	v_mfma_f32_16x16x32_bf16 v[8:11], v[150:153], v[190:193], v[10:13]
	v_mfma_f32_16x16x32_bf16 v[4:7], v[158:161], v[190:193], v[4:7]
	v_mfma_f32_16x16x32_bf16 v[66:69], v[138:141], v[170:173], v[66:69]
	v_mfma_f32_16x16x32_bf16 v[62:65], v[146:149], v[170:173], v[62:65]
	v_mfma_f32_16x16x32_bf16 v[50:53], v[138:141], v[178:181], v[50:53]
	v_mfma_f32_16x16x32_bf16 v[46:49], v[146:149], v[178:181], v[46:49]
	v_mfma_f32_16x16x32_bf16 v[34:37], v[138:141], v[186:189], v[34:37]
	v_mfma_f32_16x16x32_bf16 v[30:33], v[146:149], v[186:189], v[30:33]
	v_mfma_f32_16x16x32_bf16 v[18:21], v[138:141], v[194:197], v[18:21]
	v_mfma_f32_16x16x32_bf16 v[14:17], v[146:149], v[194:197], v[14:17]
	v_mfma_f32_16x16x32_bf16 v[58:61], v[154:157], v[170:173], v[58:61]
	v_mfma_f32_16x16x32_bf16 v[54:57], v[162:165], v[170:173], v[54:57]
	v_mfma_f32_16x16x32_bf16 v[42:45], v[154:157], v[178:181], v[42:45]
	v_mfma_f32_16x16x32_bf16 v[38:41], v[162:165], v[178:181], v[38:41]
	v_mfma_f32_16x16x32_bf16 v[26:29], v[154:157], v[186:189], v[26:29]
	v_mfma_f32_16x16x32_bf16 v[22:25], v[162:165], v[186:189], v[22:25]
	v_mfma_f32_16x16x32_bf16 v[10:13], v[154:157], v[194:197], v[8:11]
	v_mfma_f32_16x16x32_bf16 v[6:9], v[162:165], v[194:197], v[4:7]
	s_setprio 0
	s_barrier
	s_add_i32 s91, s91, 2
	s_addk_i32 s90, 0x100
	s_cmp_ge_i32 s91, s3
	s_cbranch_scc1 .LBB0_1193

.LBB0_1290:
	ds_read_b128 v[106:109], v224
	ds_read_b128 v[118:121], v224 offset:1024
	ds_read_b128 v[130:133], v224 offset:2048
	ds_read_b128 v[138:141], v224 offset:3072
	ds_read_b128 v[146:149], v225
	ds_read_b128 v[150:153], v225 offset:1024
	ds_read_b128 v[154:157], v225 offset:2048
	ds_read_b128 v[158:161], v225 offset:3072
	s_add_i32 s18, s72, 0xffe80080
	s_cmp_eq_u32 s56, s74
	s_cselect_b32 s75, s6, s18
	s_cselect_b32 s77, s7, s73
	s_or_b32 s76, s75, 0x80
	s_add_i32 s18, s72, 0xfff80000
	s_mov_b32 m0, s57
	ds_read_b128 v[162:165], v226
	ds_read_b128 v[166:169], v226 offset:1024
	ds_read_b128 v[170:173], v226 offset:2048
	ds_read_b128 v[174:177], v226 offset:3072
	ds_read_b128 v[178:181], v226 offset:4096
	ds_read_b128 v[182:185], v226 offset:5120
	ds_read_b128 v[190:193], v226 offset:6144
	ds_read_b128 v[194:197], v226 offset:7168
	buffer_load_dwordx4 v222, s[12:15], s18 offen lds
	s_mov_b32 m0, s60
	s_nop 0
	buffer_load_dwordx4 v222, s[12:15], s72 offen lds
	s_waitcnt vmcnt(8) lgkmcnt(0)
	s_setprio 1
	v_mfma_f32_16x16x32_bf16 v[142:145], v[106:109], v[162:165], v[142:145]
	s_barrier
	v_mfma_f32_16x16x32_bf16 v[142:145], v[118:121], v[166:169], v[142:145]
	v_mfma_f32_16x16x32_bf16 v[114:117], v[106:109], v[170:173], v[114:117]
	v_mfma_f32_16x16x32_bf16 v[114:117], v[118:121], v[174:177], v[114:117]
	v_mfma_f32_16x16x32_bf16 v[94:97], v[106:109], v[178:181], v[94:97]
	v_mfma_f32_16x16x32_bf16 v[94:97], v[118:121], v[182:185], v[94:97]
	v_mfma_f32_16x16x32_bf16 v[78:81], v[106:109], v[190:193], v[78:81]
	v_mfma_f32_16x16x32_bf16 v[78:81], v[118:121], v[194:197], v[78:81]
	v_mfma_f32_16x16x32_bf16 v[74:77], v[130:133], v[190:193], v[74:77]
	v_mfma_f32_16x16x32_bf16 v[74:77], v[138:141], v[194:197], v[74:77]
	v_mfma_f32_16x16x32_bf16 v[90:93], v[130:133], v[178:181], v[90:93]
	v_mfma_f32_16x16x32_bf16 v[90:93], v[138:141], v[182:185], v[90:93]
	v_mfma_f32_16x16x32_bf16 v[110:113], v[130:133], v[170:173], v[110:113]
	v_mfma_f32_16x16x32_bf16 v[110:113], v[138:141], v[174:177], v[110:113]
	v_mfma_f32_16x16x32_bf16 v[134:137], v[130:133], v[162:165], v[134:137]
	v_mfma_f32_16x16x32_bf16 v[134:137], v[138:141], v[166:169], v[134:137]
	v_mfma_f32_16x16x32_bf16 v[126:129], v[146:149], v[162:165], v[126:129]
	v_mfma_f32_16x16x32_bf16 v[126:129], v[150:153], v[166:169], v[126:129]
	v_mfma_f32_16x16x32_bf16 v[102:105], v[146:149], v[170:173], v[102:105]
	v_mfma_f32_16x16x32_bf16 v[102:105], v[150:153], v[174:177], v[102:105]
	v_mfma_f32_16x16x32_bf16 v[86:89], v[146:149], v[178:181], v[86:89]
	v_mfma_f32_16x16x32_bf16 v[86:89], v[150:153], v[182:185], v[86:89]
	v_mfma_f32_16x16x32_bf16 v[70:73], v[146:149], v[190:193], v[70:73]
	v_mfma_f32_16x16x32_bf16 v[70:73], v[150:153], v[194:197], v[70:73]
	v_mfma_f32_16x16x32_bf16 v[66:69], v[154:157], v[190:193], v[66:69]
	v_mfma_f32_16x16x32_bf16 v[66:69], v[158:161], v[194:197], v[66:69]
	v_mfma_f32_16x16x32_bf16 v[82:85], v[154:157], v[178:181], v[82:85]
	v_mfma_f32_16x16x32_bf16 v[82:85], v[158:161], v[182:185], v[82:85]
	v_mfma_f32_16x16x32_bf16 v[98:101], v[154:157], v[170:173], v[98:101]
	v_mfma_f32_16x16x32_bf16 v[98:101], v[158:161], v[174:177], v[98:101]
	v_mfma_f32_16x16x32_bf16 v[122:125], v[154:157], v[162:165], v[122:125]
	v_mfma_f32_16x16x32_bf16 v[122:125], v[158:161], v[166:169], v[122:125]
	s_setprio 0
	s_barrier
	s_mov_b32 m0, s27
	s_mov_b32 s18, s14
	s_mov_b32 s19, s15
	ds_read_b128 v[162:165], v226 offset:16384
	ds_read_b128 v[166:169], v226 offset:17408
	ds_read_b128 v[170:173], v226 offset:18432
	ds_read_b128 v[174:177], v226 offset:19456
	ds_read_b128 v[178:181], v226 offset:20480
	ds_read_b128 v[182:185], v226 offset:21504
	ds_read_b128 v[190:193], v226 offset:22528
	ds_read_b128 v[194:197], v226 offset:23552
	buffer_load_dwordx4 v223, s[16:19], s77 offen lds
	s_mov_b32 m0, s30
	s_add_i32 s78, s77, 0x80000
	buffer_load_dwordx4 v223, s[16:19], s78 offen lds
	s_mov_b32 m0, s31
	s_add_i32 s78, s77, 0x100000
	buffer_load_dwordx4 v223, s[16:19], s78 offen lds
	s_mov_b32 m0, s41
	s_add_i32 s78, s77, 0x180000
	buffer_load_dwordx4 v223, s[16:19], s78 offen lds
	s_mov_b32 m0, s25
	s_add_i32 s78, s75, 0x80000
	buffer_load_dwordx4 v222, s[12:15], s75 offen lds
	s_mov_b32 m0, s42
	s_nop 0
	buffer_load_dwordx4 v222, s[12:15], s78 offen lds
	s_waitcnt vmcnt(8) lgkmcnt(0)
	s_setprio 1
	v_mfma_f32_16x16x32_bf16 v[62:65], v[106:109], v[162:165], v[62:65]
	s_barrier
	v_mfma_f32_16x16x32_bf16 v[62:65], v[118:121], v[166:169], v[62:65]
	v_mfma_f32_16x16x32_bf16 v[46:49], v[106:109], v[170:173], v[46:49]
	v_mfma_f32_16x16x32_bf16 v[46:49], v[118:121], v[174:177], v[46:49]
	v_mfma_f32_16x16x32_bf16 v[30:33], v[106:109], v[178:181], v[30:33]
	v_mfma_f32_16x16x32_bf16 v[30:33], v[118:121], v[182:185], v[30:33]
	v_mfma_f32_16x16x32_bf16 v[14:17], v[106:109], v[190:193], v[14:17]
	v_mfma_f32_16x16x32_bf16 v[14:17], v[118:121], v[194:197], v[14:17]
	v_mfma_f32_16x16x32_bf16 v[10:13], v[130:133], v[190:193], v[10:13]
	v_mfma_f32_16x16x32_bf16 v[10:13], v[138:141], v[194:197], v[10:13]
	v_mfma_f32_16x16x32_bf16 v[26:29], v[130:133], v[178:181], v[26:29]
	v_mfma_f32_16x16x32_bf16 v[26:29], v[138:141], v[182:185], v[26:29]
	v_mfma_f32_16x16x32_bf16 v[42:45], v[130:133], v[170:173], v[42:45]
	v_mfma_f32_16x16x32_bf16 v[42:45], v[138:141], v[174:177], v[42:45]
	v_mfma_f32_16x16x32_bf16 v[58:61], v[130:133], v[162:165], v[58:61]
	v_mfma_f32_16x16x32_bf16 v[58:61], v[138:141], v[166:169], v[58:61]
	v_mfma_f32_16x16x32_bf16 v[54:57], v[146:149], v[162:165], v[54:57]
	v_mfma_f32_16x16x32_bf16 v[54:57], v[150:153], v[166:169], v[54:57]
	v_mfma_f32_16x16x32_bf16 v[38:41], v[146:149], v[170:173], v[38:41]
	v_mfma_f32_16x16x32_bf16 v[38:41], v[150:153], v[174:177], v[38:41]
	v_mfma_f32_16x16x32_bf16 v[22:25], v[146:149], v[178:181], v[22:25]
	v_mfma_f32_16x16x32_bf16 v[22:25], v[150:153], v[182:185], v[22:25]
	v_mfma_f32_16x16x32_bf16 v[6:9], v[146:149], v[190:193], v[6:9]
	v_mfma_f32_16x16x32_bf16 v[6:9], v[150:153], v[194:197], v[6:9]
	v_mfma_f32_16x16x32_bf16 v[2:5], v[154:157], v[190:193], v[2:5]
	v_mfma_f32_16x16x32_bf16 v[2:5], v[158:161], v[194:197], v[2:5]
	v_mfma_f32_16x16x32_bf16 v[18:21], v[154:157], v[178:181], v[18:21]
	v_mfma_f32_16x16x32_bf16 v[18:21], v[158:161], v[182:185], v[18:21]
	v_mfma_f32_16x16x32_bf16 v[34:37], v[154:157], v[170:173], v[34:37]
	v_mfma_f32_16x16x32_bf16 v[34:37], v[158:161], v[174:177], v[34:37]
	v_mfma_f32_16x16x32_bf16 v[50:53], v[154:157], v[162:165], v[50:53]
	v_mfma_f32_16x16x32_bf16 v[50:53], v[158:161], v[166:169], v[50:53]
	s_setprio 0
	s_barrier
	ds_read_b128 v[106:109], v227
	ds_read_b128 v[118:121], v227 offset:1024
	ds_read_b128 v[130:133], v227 offset:2048
	ds_read_b128 v[138:141], v227 offset:3072
	ds_read_b128 v[146:149], v228
	ds_read_b128 v[150:153], v228 offset:1024
	ds_read_b128 v[154:157], v228 offset:2048
	ds_read_b128 v[158:161], v228 offset:3072
	s_mov_b32 m0, s43
	s_add_i32 s78, s75, 0x100000
	ds_read_b128 v[162:165], v226 offset:32768
	ds_read_b128 v[166:169], v226 offset:33792
	ds_read_b128 v[170:173], v226 offset:34816
	ds_read_b128 v[174:177], v226 offset:35840
	ds_read_b128 v[178:181], v226 offset:36864
	ds_read_b128 v[182:185], v226 offset:37888
	ds_read_b128 v[190:193], v226 offset:38912
	ds_read_b128 v[194:197], v226 offset:39936
	buffer_load_dwordx4 v222, s[12:15], s78 offen lds
	s_mov_b32 m0, s44
	s_add_i32 s78, s75, 0x180000
	buffer_load_dwordx4 v222, s[12:15], s78 offen lds
	s_waitcnt vmcnt(8) lgkmcnt(0)
	s_setprio 1
	v_mfma_f32_16x16x32_bf16 v[142:145], v[106:109], v[162:165], v[142:145]
	s_barrier
	v_mfma_f32_16x16x32_bf16 v[142:145], v[118:121], v[166:169], v[142:145]
	v_mfma_f32_16x16x32_bf16 v[114:117], v[106:109], v[170:173], v[114:117]
	v_mfma_f32_16x16x32_bf16 v[114:117], v[118:121], v[174:177], v[114:117]
	v_mfma_f32_16x16x32_bf16 v[94:97], v[106:109], v[178:181], v[94:97]
	v_mfma_f32_16x16x32_bf16 v[94:97], v[118:121], v[182:185], v[94:97]
	v_mfma_f32_16x16x32_bf16 v[78:81], v[106:109], v[190:193], v[78:81]
	v_mfma_f32_16x16x32_bf16 v[78:81], v[118:121], v[194:197], v[78:81]
	v_mfma_f32_16x16x32_bf16 v[74:77], v[130:133], v[190:193], v[74:77]
	v_mfma_f32_16x16x32_bf16 v[74:77], v[138:141], v[194:197], v[74:77]
	v_mfma_f32_16x16x32_bf16 v[90:93], v[130:133], v[178:181], v[90:93]
	v_mfma_f32_16x16x32_bf16 v[90:93], v[138:141], v[182:185], v[90:93]
	v_mfma_f32_16x16x32_bf16 v[110:113], v[130:133], v[170:173], v[110:113]
	v_mfma_f32_16x16x32_bf16 v[110:113], v[138:141], v[174:177], v[110:113]
	v_mfma_f32_16x16x32_bf16 v[134:137], v[130:133], v[162:165], v[134:137]
	v_mfma_f32_16x16x32_bf16 v[134:137], v[138:141], v[166:169], v[134:137]
	v_mfma_f32_16x16x32_bf16 v[126:129], v[146:149], v[162:165], v[126:129]
	v_mfma_f32_16x16x32_bf16 v[126:129], v[150:153], v[166:169], v[126:129]
	v_mfma_f32_16x16x32_bf16 v[102:105], v[146:149], v[170:173], v[102:105]
	v_mfma_f32_16x16x32_bf16 v[102:105], v[150:153], v[174:177], v[102:105]
	v_mfma_f32_16x16x32_bf16 v[86:89], v[146:149], v[178:181], v[86:89]
	v_mfma_f32_16x16x32_bf16 v[86:89], v[150:153], v[182:185], v[86:89]
	v_mfma_f32_16x16x32_bf16 v[70:73], v[146:149], v[190:193], v[70:73]
	v_mfma_f32_16x16x32_bf16 v[70:73], v[150:153], v[194:197], v[70:73]
	v_mfma_f32_16x16x32_bf16 v[66:69], v[154:157], v[190:193], v[66:69]
	v_mfma_f32_16x16x32_bf16 v[66:69], v[158:161], v[194:197], v[66:69]
	v_mfma_f32_16x16x32_bf16 v[82:85], v[154:157], v[178:181], v[82:85]
	v_mfma_f32_16x16x32_bf16 v[82:85], v[158:161], v[182:185], v[82:85]
	v_mfma_f32_16x16x32_bf16 v[98:101], v[154:157], v[170:173], v[98:101]
	v_mfma_f32_16x16x32_bf16 v[98:101], v[158:161], v[174:177], v[98:101]
	v_mfma_f32_16x16x32_bf16 v[122:125], v[154:157], v[162:165], v[122:125]
	v_mfma_f32_16x16x32_bf16 v[122:125], v[158:161], v[166:169], v[122:125]
	s_setprio 0
	s_barrier
	s_mov_b32 m0, s48
	s_or_b32 s78, s77, 0x80
	ds_read_b128 v[162:165], v226 offset:49152
	ds_read_b128 v[166:169], v226 offset:50176
	ds_read_b128 v[170:173], v226 offset:51200
	ds_read_b128 v[174:177], v226 offset:52224
	ds_read_b128 v[178:181], v226 offset:53248
	ds_read_b128 v[182:185], v226 offset:54272
	ds_read_b128 v[190:193], v226 offset:55296
	ds_read_b128 v[194:197], v226 offset:56320
	buffer_load_dwordx4 v223, s[16:19], s78 offen lds
	s_add_i32 s78, s77, 0x80080
	s_mov_b32 m0, s49
	s_add_i32 s75, s75, 0x80080
	buffer_load_dwordx4 v223, s[16:19], s78 offen lds
	s_add_i32 s78, s77, 0x100080
	s_mov_b32 m0, s52
	s_add_i32 s77, s77, 0x180080
	buffer_load_dwordx4 v223, s[16:19], s78 offen lds
	s_mov_b32 m0, s53
	s_nop 0
	buffer_load_dwordx4 v223, s[16:19], s77 offen lds
	s_mov_b32 m0, s50
	s_nop 0
	buffer_load_dwordx4 v222, s[12:15], s76 offen lds
	s_mov_b32 m0, s51
	s_nop 0
	buffer_load_dwordx4 v222, s[12:15], s75 offen lds
	s_waitcnt vmcnt(8) lgkmcnt(0)
	s_setprio 1
	v_mfma_f32_16x16x32_bf16 v[62:65], v[106:109], v[162:165], v[62:65]
	s_barrier
	v_mfma_f32_16x16x32_bf16 v[62:65], v[118:121], v[166:169], v[62:65]
	v_mfma_f32_16x16x32_bf16 v[46:49], v[106:109], v[170:173], v[46:49]
	v_mfma_f32_16x16x32_bf16 v[46:49], v[118:121], v[174:177], v[46:49]
	v_mfma_f32_16x16x32_bf16 v[30:33], v[106:109], v[178:181], v[30:33]
	v_mfma_f32_16x16x32_bf16 v[30:33], v[118:121], v[182:185], v[30:33]
	v_mfma_f32_16x16x32_bf16 v[14:17], v[106:109], v[190:193], v[14:17]
	v_mfma_f32_16x16x32_bf16 v[14:17], v[118:121], v[194:197], v[14:17]
	v_mfma_f32_16x16x32_bf16 v[10:13], v[130:133], v[190:193], v[10:13]
	v_mfma_f32_16x16x32_bf16 v[10:13], v[138:141], v[194:197], v[10:13]
	v_mfma_f32_16x16x32_bf16 v[26:29], v[130:133], v[178:181], v[26:29]
	v_mfma_f32_16x16x32_bf16 v[26:29], v[138:141], v[182:185], v[26:29]
	v_mfma_f32_16x16x32_bf16 v[42:45], v[130:133], v[170:173], v[42:45]
	v_mfma_f32_16x16x32_bf16 v[42:45], v[138:141], v[174:177], v[42:45]
	v_mfma_f32_16x16x32_bf16 v[58:61], v[130:133], v[162:165], v[58:61]
	v_mfma_f32_16x16x32_bf16 v[58:61], v[138:141], v[166:169], v[58:61]
	v_mfma_f32_16x16x32_bf16 v[54:57], v[146:149], v[162:165], v[54:57]
	v_mfma_f32_16x16x32_bf16 v[54:57], v[150:153], v[166:169], v[54:57]
	v_mfma_f32_16x16x32_bf16 v[38:41], v[146:149], v[170:173], v[38:41]
	v_mfma_f32_16x16x32_bf16 v[38:41], v[150:153], v[174:177], v[38:41]
	v_mfma_f32_16x16x32_bf16 v[22:25], v[146:149], v[178:181], v[22:25]
	v_mfma_f32_16x16x32_bf16 v[22:25], v[150:153], v[182:185], v[22:25]
	v_mfma_f32_16x16x32_bf16 v[6:9], v[146:149], v[190:193], v[6:9]
	v_mfma_f32_16x16x32_bf16 v[6:9], v[150:153], v[194:197], v[6:9]
	v_mfma_f32_16x16x32_bf16 v[2:5], v[154:157], v[190:193], v[2:5]
	v_mfma_f32_16x16x32_bf16 v[2:5], v[158:161], v[194:197], v[2:5]
	v_mfma_f32_16x16x32_bf16 v[18:21], v[154:157], v[178:181], v[18:21]
	v_mfma_f32_16x16x32_bf16 v[18:21], v[158:161], v[182:185], v[18:21]
	v_mfma_f32_16x16x32_bf16 v[34:37], v[154:157], v[170:173], v[34:37]
	v_mfma_f32_16x16x32_bf16 v[34:37], v[158:161], v[174:177], v[34:37]
	v_mfma_f32_16x16x32_bf16 v[50:53], v[154:157], v[162:165], v[50:53]
	v_mfma_f32_16x16x32_bf16 v[50:53], v[158:161], v[166:169], v[50:53]
	s_setprio 0
	s_barrier
	s_add_i32 s74, s74, 2
	s_addk_i32 s72, 0x100
	s_addk_i32 s73, 0x100
	s_cmp_ge_i32 s74, s3
	s_cbranch_scc0 .LBB0_1290
	s_and_b64 vcc, exec, s[38:39]
	s_cbranch_vccz .LBB0_1293

.LBB0_1382:
	ds_read_b128 v[144:147], v138
	ds_read_b128 v[148:151], v138 offset:1024
	ds_read_b128 v[152:155], v138 offset:2048
	ds_read_b128 v[156:159], v138 offset:3072
	ds_read_b128 v[160:163], v139
	ds_read_b128 v[164:167], v139 offset:1024
	ds_read_b128 v[168:171], v139 offset:2048
	ds_read_b128 v[172:175], v139 offset:3072
	s_add_i32 s14, s74, 0xffe80080
	s_cmp_eq_u32 s61, s76
	s_cselect_b32 s77, s72, s14
	s_cselect_b32 s79, s73, s75
	s_or_b32 s78, s77, 0x80
	s_add_i32 s14, s74, 0xfff80000
	s_mov_b32 m0, s62
	ds_read_b128 v[176:179], v140
	ds_read_b128 v[180:183], v140 offset:1024
	ds_read_b128 v[184:187], v140 offset:2048
	ds_read_b128 v[188:191], v140 offset:3072
	ds_read_b128 v[192:195], v140 offset:4096
	ds_read_b128 v[196:199], v140 offset:5120
	ds_read_b128 v[200:203], v140 offset:6144
	ds_read_b128 v[204:207], v140 offset:7168
	buffer_load_dwordx4 v136, s[16:19], s14 offen lds
	s_mov_b32 m0, s63
	s_nop 0
	buffer_load_dwordx4 v136, s[16:19], s74 offen lds
	s_waitcnt vmcnt(8) lgkmcnt(0)
	s_setprio 1
	v_mfma_f32_16x16x32_bf16 v[118:121], v[144:147], v[176:179], v[118:121]
	s_barrier
	v_mfma_f32_16x16x32_bf16 v[118:121], v[148:151], v[180:183], v[118:121]
	v_mfma_f32_16x16x32_bf16 v[110:113], v[144:147], v[184:187], v[110:113]
	v_mfma_f32_16x16x32_bf16 v[110:113], v[148:151], v[188:191], v[110:113]
	v_mfma_f32_16x16x32_bf16 v[94:97], v[144:147], v[192:195], v[94:97]
	v_mfma_f32_16x16x32_bf16 v[94:97], v[148:151], v[196:199], v[94:97]
	v_mfma_f32_16x16x32_bf16 v[78:81], v[144:147], v[200:203], v[78:81]
	v_mfma_f32_16x16x32_bf16 v[78:81], v[148:151], v[204:207], v[78:81]
	v_mfma_f32_16x16x32_bf16 v[66:69], v[152:155], v[200:203], v[66:69]
	v_mfma_f32_16x16x32_bf16 v[66:69], v[156:159], v[204:207], v[66:69]
	v_mfma_f32_16x16x32_bf16 v[86:89], v[152:155], v[192:195], v[86:89]
	v_mfma_f32_16x16x32_bf16 v[86:89], v[156:159], v[196:199], v[86:89]
	v_mfma_f32_16x16x32_bf16 v[102:105], v[152:155], v[184:187], v[102:105]
	v_mfma_f32_16x16x32_bf16 v[102:105], v[156:159], v[188:191], v[102:105]
	v_mfma_f32_16x16x32_bf16 v[114:117], v[152:155], v[176:179], v[114:117]
	v_mfma_f32_16x16x32_bf16 v[114:117], v[156:159], v[180:183], v[114:117]
	v_mfma_f32_16x16x32_bf16 v[126:129], v[160:163], v[176:179], v[126:129]
	v_mfma_f32_16x16x32_bf16 v[126:129], v[164:167], v[180:183], v[126:129]
	v_mfma_f32_16x16x32_bf16 v[106:109], v[160:163], v[184:187], v[106:109]
	v_mfma_f32_16x16x32_bf16 v[106:109], v[164:167], v[188:191], v[106:109]
	v_mfma_f32_16x16x32_bf16 v[90:93], v[160:163], v[192:195], v[90:93]
	v_mfma_f32_16x16x32_bf16 v[90:93], v[164:167], v[196:199], v[90:93]
	v_mfma_f32_16x16x32_bf16 v[74:77], v[160:163], v[200:203], v[74:77]
	v_mfma_f32_16x16x32_bf16 v[74:77], v[164:167], v[204:207], v[74:77]
	v_mfma_f32_16x16x32_bf16 v[70:73], v[168:171], v[200:203], v[70:73]
	v_mfma_f32_16x16x32_bf16 v[70:73], v[172:175], v[204:207], v[70:73]
	v_mfma_f32_16x16x32_bf16 v[82:85], v[168:171], v[192:195], v[82:85]
	v_mfma_f32_16x16x32_bf16 v[82:85], v[172:175], v[196:199], v[82:85]
	v_mfma_f32_16x16x32_bf16 v[98:101], v[168:171], v[184:187], v[98:101]
	v_mfma_f32_16x16x32_bf16 v[98:101], v[172:175], v[188:191], v[98:101]
	v_mfma_f32_16x16x32_bf16 v[122:125], v[168:171], v[176:179], v[122:125]
	v_mfma_f32_16x16x32_bf16 v[122:125], v[172:175], v[180:183], v[122:125]
	s_setprio 0
	s_barrier
	s_mov_b32 m0, s45
	s_mov_b32 s14, s18
	s_mov_b32 s15, s19
	ds_read_b128 v[176:179], v140 offset:16384
	ds_read_b128 v[180:183], v140 offset:17408
	ds_read_b128 v[184:187], v140 offset:18432
	ds_read_b128 v[188:191], v140 offset:19456
	ds_read_b128 v[192:195], v140 offset:20480
	ds_read_b128 v[196:199], v140 offset:21504
	ds_read_b128 v[200:203], v140 offset:22528
	ds_read_b128 v[204:207], v140 offset:23552
	buffer_load_dwordx4 v137, s[12:15], s79 offen lds
	s_mov_b32 m0, s46
	s_add_i32 s80, s79, 0x80000
	buffer_load_dwordx4 v137, s[12:15], s80 offen lds
	s_mov_b32 m0, s47
	s_add_i32 s80, s79, 0x100000
	buffer_load_dwordx4 v137, s[12:15], s80 offen lds
	s_mov_b32 m0, s48
	s_add_i32 s80, s79, 0x180000
	buffer_load_dwordx4 v137, s[12:15], s80 offen lds
	s_mov_b32 m0, s44
	s_add_i32 s80, s77, 0x80000
	buffer_load_dwordx4 v136, s[16:19], s77 offen lds
	s_mov_b32 m0, s49
	s_nop 0
	buffer_load_dwordx4 v136, s[16:19], s80 offen lds
	s_waitcnt vmcnt(8) lgkmcnt(0)
	s_setprio 1
	v_mfma_f32_16x16x32_bf16 v[62:65], v[144:147], v[176:179], v[62:65]
	s_barrier
	v_mfma_f32_16x16x32_bf16 v[62:65], v[148:151], v[180:183], v[62:65]
	v_mfma_f32_16x16x32_bf16 v[46:49], v[144:147], v[184:187], v[46:49]
	v_mfma_f32_16x16x32_bf16 v[46:49], v[148:151], v[188:191], v[46:49]
	v_mfma_f32_16x16x32_bf16 v[30:33], v[144:147], v[192:195], v[30:33]
	v_mfma_f32_16x16x32_bf16 v[30:33], v[148:151], v[196:199], v[30:33]
	v_mfma_f32_16x16x32_bf16 v[14:17], v[144:147], v[200:203], v[14:17]
	v_mfma_f32_16x16x32_bf16 v[14:17], v[148:151], v[204:207], v[14:17]
	v_mfma_f32_16x16x32_bf16 v[6:9], v[152:155], v[200:203], v[6:9]
	v_mfma_f32_16x16x32_bf16 v[6:9], v[156:159], v[204:207], v[6:9]
	v_mfma_f32_16x16x32_bf16 v[22:25], v[152:155], v[192:195], v[22:25]
	v_mfma_f32_16x16x32_bf16 v[22:25], v[156:159], v[196:199], v[22:25]
	v_mfma_f32_16x16x32_bf16 v[38:41], v[152:155], v[184:187], v[38:41]
	v_mfma_f32_16x16x32_bf16 v[38:41], v[156:159], v[188:191], v[38:41]
	v_mfma_f32_16x16x32_bf16 v[54:57], v[152:155], v[176:179], v[54:57]
	v_mfma_f32_16x16x32_bf16 v[54:57], v[156:159], v[180:183], v[54:57]
	v_mfma_f32_16x16x32_bf16 v[58:61], v[160:163], v[176:179], v[58:61]
	v_mfma_f32_16x16x32_bf16 v[58:61], v[164:167], v[180:183], v[58:61]
	v_mfma_f32_16x16x32_bf16 v[42:45], v[160:163], v[184:187], v[42:45]
	v_mfma_f32_16x16x32_bf16 v[42:45], v[164:167], v[188:191], v[42:45]
	v_mfma_f32_16x16x32_bf16 v[26:29], v[160:163], v[192:195], v[26:29]
	v_mfma_f32_16x16x32_bf16 v[26:29], v[164:167], v[196:199], v[26:29]
	v_mfma_f32_16x16x32_bf16 v[10:13], v[160:163], v[200:203], v[10:13]
	v_mfma_f32_16x16x32_bf16 v[10:13], v[164:167], v[204:207], v[10:13]
	v_mfma_f32_16x16x32_bf16 v[2:5], v[168:171], v[200:203], v[2:5]
	v_mfma_f32_16x16x32_bf16 v[2:5], v[172:175], v[204:207], v[2:5]
	v_mfma_f32_16x16x32_bf16 v[18:21], v[168:171], v[192:195], v[18:21]
	v_mfma_f32_16x16x32_bf16 v[18:21], v[172:175], v[196:199], v[18:21]
	v_mfma_f32_16x16x32_bf16 v[34:37], v[168:171], v[184:187], v[34:37]
	v_mfma_f32_16x16x32_bf16 v[34:37], v[172:175], v[188:191], v[34:37]
	v_mfma_f32_16x16x32_bf16 v[50:53], v[168:171], v[176:179], v[50:53]
	v_mfma_f32_16x16x32_bf16 v[50:53], v[172:175], v[180:183], v[50:53]
	s_setprio 0
	s_barrier
	ds_read_b128 v[144:147], v141
	ds_read_b128 v[148:151], v141 offset:1024
	ds_read_b128 v[152:155], v141 offset:2048
	ds_read_b128 v[156:159], v141 offset:3072
	ds_read_b128 v[160:163], v142
	ds_read_b128 v[164:167], v142 offset:1024
	ds_read_b128 v[168:171], v142 offset:2048
	ds_read_b128 v[172:175], v142 offset:3072
	s_mov_b32 m0, s50
	s_add_i32 s80, s77, 0x100000
	ds_read_b128 v[176:179], v140 offset:32768
	ds_read_b128 v[180:183], v140 offset:33792
	ds_read_b128 v[184:187], v140 offset:34816
	ds_read_b128 v[188:191], v140 offset:35840
	ds_read_b128 v[192:195], v140 offset:36864
	ds_read_b128 v[196:199], v140 offset:37888
	ds_read_b128 v[200:203], v140 offset:38912
	ds_read_b128 v[204:207], v140 offset:39936
	buffer_load_dwordx4 v136, s[16:19], s80 offen lds
	s_mov_b32 m0, s51
	s_add_i32 s80, s77, 0x180000
	buffer_load_dwordx4 v136, s[16:19], s80 offen lds
	s_waitcnt vmcnt(8) lgkmcnt(0)
	s_setprio 1
	v_mfma_f32_16x16x32_bf16 v[118:121], v[144:147], v[176:179], v[118:121]
	s_barrier
	v_mfma_f32_16x16x32_bf16 v[118:121], v[148:151], v[180:183], v[118:121]
	v_mfma_f32_16x16x32_bf16 v[110:113], v[144:147], v[184:187], v[110:113]
	v_mfma_f32_16x16x32_bf16 v[110:113], v[148:151], v[188:191], v[110:113]
	v_mfma_f32_16x16x32_bf16 v[94:97], v[144:147], v[192:195], v[94:97]
	v_mfma_f32_16x16x32_bf16 v[94:97], v[148:151], v[196:199], v[94:97]
	v_mfma_f32_16x16x32_bf16 v[78:81], v[144:147], v[200:203], v[78:81]
	v_mfma_f32_16x16x32_bf16 v[78:81], v[148:151], v[204:207], v[78:81]
	v_mfma_f32_16x16x32_bf16 v[66:69], v[152:155], v[200:203], v[66:69]
	v_mfma_f32_16x16x32_bf16 v[66:69], v[156:159], v[204:207], v[66:69]
	v_mfma_f32_16x16x32_bf16 v[86:89], v[152:155], v[192:195], v[86:89]
	v_mfma_f32_16x16x32_bf16 v[86:89], v[156:159], v[196:199], v[86:89]
	v_mfma_f32_16x16x32_bf16 v[102:105], v[152:155], v[184:187], v[102:105]
	v_mfma_f32_16x16x32_bf16 v[102:105], v[156:159], v[188:191], v[102:105]
	v_mfma_f32_16x16x32_bf16 v[114:117], v[152:155], v[176:179], v[114:117]
	v_mfma_f32_16x16x32_bf16 v[114:117], v[156:159], v[180:183], v[114:117]
	v_mfma_f32_16x16x32_bf16 v[126:129], v[160:163], v[176:179], v[126:129]
	v_mfma_f32_16x16x32_bf16 v[126:129], v[164:167], v[180:183], v[126:129]
	v_mfma_f32_16x16x32_bf16 v[106:109], v[160:163], v[184:187], v[106:109]
	v_mfma_f32_16x16x32_bf16 v[106:109], v[164:167], v[188:191], v[106:109]
	v_mfma_f32_16x16x32_bf16 v[90:93], v[160:163], v[192:195], v[90:93]
	v_mfma_f32_16x16x32_bf16 v[90:93], v[164:167], v[196:199], v[90:93]
	v_mfma_f32_16x16x32_bf16 v[74:77], v[160:163], v[200:203], v[74:77]
	v_mfma_f32_16x16x32_bf16 v[74:77], v[164:167], v[204:207], v[74:77]
	v_mfma_f32_16x16x32_bf16 v[70:73], v[168:171], v[200:203], v[70:73]
	v_mfma_f32_16x16x32_bf16 v[70:73], v[172:175], v[204:207], v[70:73]
	v_mfma_f32_16x16x32_bf16 v[82:85], v[168:171], v[192:195], v[82:85]
	v_mfma_f32_16x16x32_bf16 v[82:85], v[172:175], v[196:199], v[82:85]
	v_mfma_f32_16x16x32_bf16 v[98:101], v[168:171], v[184:187], v[98:101]
	v_mfma_f32_16x16x32_bf16 v[98:101], v[172:175], v[188:191], v[98:101]
	v_mfma_f32_16x16x32_bf16 v[122:125], v[168:171], v[176:179], v[122:125]
	v_mfma_f32_16x16x32_bf16 v[122:125], v[172:175], v[180:183], v[122:125]
	s_setprio 0
	s_barrier
	s_mov_b32 m0, s53
	s_or_b32 s80, s79, 0x80
	ds_read_b128 v[176:179], v140 offset:49152
	ds_read_b128 v[180:183], v140 offset:50176
	ds_read_b128 v[184:187], v140 offset:51200
	ds_read_b128 v[188:191], v140 offset:52224
	ds_read_b128 v[192:195], v140 offset:53248
	ds_read_b128 v[196:199], v140 offset:54272
	ds_read_b128 v[200:203], v140 offset:55296
	ds_read_b128 v[204:207], v140 offset:56320
	buffer_load_dwordx4 v137, s[12:15], s80 offen lds
	s_add_i32 s80, s79, 0x80080
	s_mov_b32 m0, s54
	s_add_i32 s77, s77, 0x80080
	buffer_load_dwordx4 v137, s[12:15], s80 offen lds
	s_add_i32 s80, s79, 0x100080
	s_mov_b32 m0, s57
	s_add_i32 s79, s79, 0x180080
	buffer_load_dwordx4 v137, s[12:15], s80 offen lds
	s_mov_b32 m0, s58
	s_nop 0
	buffer_load_dwordx4 v137, s[12:15], s79 offen lds
	s_mov_b32 m0, s55
	s_nop 0
	buffer_load_dwordx4 v136, s[16:19], s78 offen lds
	s_mov_b32 m0, s56
	s_nop 0
	buffer_load_dwordx4 v136, s[16:19], s77 offen lds
	s_waitcnt vmcnt(8) lgkmcnt(0)
	s_setprio 1
	v_mfma_f32_16x16x32_bf16 v[62:65], v[144:147], v[176:179], v[62:65]
	s_barrier
	v_mfma_f32_16x16x32_bf16 v[62:65], v[148:151], v[180:183], v[62:65]
	v_mfma_f32_16x16x32_bf16 v[46:49], v[144:147], v[184:187], v[46:49]
	v_mfma_f32_16x16x32_bf16 v[46:49], v[148:151], v[188:191], v[46:49]
	v_mfma_f32_16x16x32_bf16 v[30:33], v[144:147], v[192:195], v[30:33]
	v_mfma_f32_16x16x32_bf16 v[30:33], v[148:151], v[196:199], v[30:33]
	v_mfma_f32_16x16x32_bf16 v[14:17], v[144:147], v[200:203], v[14:17]
	v_mfma_f32_16x16x32_bf16 v[14:17], v[148:151], v[204:207], v[14:17]
	v_mfma_f32_16x16x32_bf16 v[6:9], v[152:155], v[200:203], v[6:9]
	v_mfma_f32_16x16x32_bf16 v[6:9], v[156:159], v[204:207], v[6:9]
	v_mfma_f32_16x16x32_bf16 v[22:25], v[152:155], v[192:195], v[22:25]
	v_mfma_f32_16x16x32_bf16 v[22:25], v[156:159], v[196:199], v[22:25]
	v_mfma_f32_16x16x32_bf16 v[38:41], v[152:155], v[184:187], v[38:41]
	v_mfma_f32_16x16x32_bf16 v[38:41], v[156:159], v[188:191], v[38:41]
	v_mfma_f32_16x16x32_bf16 v[54:57], v[152:155], v[176:179], v[54:57]
	v_mfma_f32_16x16x32_bf16 v[54:57], v[156:159], v[180:183], v[54:57]
	v_mfma_f32_16x16x32_bf16 v[58:61], v[160:163], v[176:179], v[58:61]
	v_mfma_f32_16x16x32_bf16 v[58:61], v[164:167], v[180:183], v[58:61]
	v_mfma_f32_16x16x32_bf16 v[42:45], v[160:163], v[184:187], v[42:45]
	v_mfma_f32_16x16x32_bf16 v[42:45], v[164:167], v[188:191], v[42:45]
	v_mfma_f32_16x16x32_bf16 v[26:29], v[160:163], v[192:195], v[26:29]
	v_mfma_f32_16x16x32_bf16 v[26:29], v[164:167], v[196:199], v[26:29]
	v_mfma_f32_16x16x32_bf16 v[10:13], v[160:163], v[200:203], v[10:13]
	v_mfma_f32_16x16x32_bf16 v[10:13], v[164:167], v[204:207], v[10:13]
	v_mfma_f32_16x16x32_bf16 v[2:5], v[168:171], v[200:203], v[2:5]
	v_mfma_f32_16x16x32_bf16 v[2:5], v[172:175], v[204:207], v[2:5]
	v_mfma_f32_16x16x32_bf16 v[18:21], v[168:171], v[192:195], v[18:21]
	v_mfma_f32_16x16x32_bf16 v[18:21], v[172:175], v[196:199], v[18:21]
	v_mfma_f32_16x16x32_bf16 v[34:37], v[168:171], v[184:187], v[34:37]
	v_mfma_f32_16x16x32_bf16 v[34:37], v[172:175], v[188:191], v[34:37]
	v_mfma_f32_16x16x32_bf16 v[50:53], v[168:171], v[176:179], v[50:53]
	v_mfma_f32_16x16x32_bf16 v[50:53], v[172:175], v[180:183], v[50:53]
	s_setprio 0
	s_barrier
	s_add_i32 s76, s76, 2
	s_addk_i32 s74, 0x100
	s_addk_i32 s75, 0x100
	s_cmp_ge_i32 s76, s27
	s_cbranch_scc0 .LBB0_1382
	s_and_b64 vcc, exec, s[42:43]
	s_cbranch_vccz .LBB0_1385

.LBB0_1402:
	ds_read_b128 v[146:149], v138
	ds_read_b128 v[150:153], v138 offset:1024
	ds_read_b128 v[154:157], v138 offset:2048
	ds_read_b128 v[158:161], v138 offset:3072
	ds_read_b128 v[162:165], v139
	ds_read_b128 v[166:169], v139 offset:1024
	ds_read_b128 v[170:173], v139 offset:2048
	ds_read_b128 v[174:177], v139 offset:3072
	s_add_i32 s22, s75, 0xffe80080
	s_cmp_eq_u32 s62, s77
	s_cselect_b32 s78, s73, s22
	s_cselect_b32 s80, s74, s76
	s_or_b32 s79, s78, 0x80
	s_add_i32 s22, s75, 0xfff80000
	s_mov_b32 m0, s63
	ds_read_b128 v[178:181], v140
	ds_read_b128 v[182:185], v140 offset:1024
	ds_read_b128 v[186:189], v140 offset:2048
	ds_read_b128 v[190:193], v140 offset:3072
	ds_read_b128 v[194:197], v140 offset:4096
	ds_read_b128 v[198:201], v140 offset:5120
	ds_read_b128 v[202:205], v140 offset:6144
	ds_read_b128 v[206:209], v140 offset:7168
	buffer_load_dwordx4 v136, s[16:19], s22 offen lds
	s_mov_b32 m0, s64
	s_nop 0
	buffer_load_dwordx4 v136, s[16:19], s75 offen lds
	s_waitcnt vmcnt(8) lgkmcnt(0)
	s_setprio 1
	v_mfma_f32_16x16x32_bf16 v[118:121], v[146:149], v[178:181], v[118:121]
	s_barrier
	v_mfma_f32_16x16x32_bf16 v[118:121], v[150:153], v[182:185], v[118:121]
	v_mfma_f32_16x16x32_bf16 v[110:113], v[146:149], v[186:189], v[110:113]
	v_mfma_f32_16x16x32_bf16 v[110:113], v[150:153], v[190:193], v[110:113]
	v_mfma_f32_16x16x32_bf16 v[94:97], v[146:149], v[194:197], v[94:97]
	v_mfma_f32_16x16x32_bf16 v[94:97], v[150:153], v[198:201], v[94:97]
	v_mfma_f32_16x16x32_bf16 v[78:81], v[146:149], v[202:205], v[78:81]
	v_mfma_f32_16x16x32_bf16 v[78:81], v[150:153], v[206:209], v[78:81]
	v_mfma_f32_16x16x32_bf16 v[66:69], v[154:157], v[202:205], v[66:69]
	v_mfma_f32_16x16x32_bf16 v[66:69], v[158:161], v[206:209], v[66:69]
	v_mfma_f32_16x16x32_bf16 v[86:89], v[154:157], v[194:197], v[86:89]
	v_mfma_f32_16x16x32_bf16 v[86:89], v[158:161], v[198:201], v[86:89]
	v_mfma_f32_16x16x32_bf16 v[102:105], v[154:157], v[186:189], v[102:105]
	v_mfma_f32_16x16x32_bf16 v[102:105], v[158:161], v[190:193], v[102:105]
	v_mfma_f32_16x16x32_bf16 v[114:117], v[154:157], v[178:181], v[114:117]
	v_mfma_f32_16x16x32_bf16 v[114:117], v[158:161], v[182:185], v[114:117]
	v_mfma_f32_16x16x32_bf16 v[126:129], v[162:165], v[178:181], v[126:129]
	v_mfma_f32_16x16x32_bf16 v[126:129], v[166:169], v[182:185], v[126:129]
	v_mfma_f32_16x16x32_bf16 v[106:109], v[162:165], v[186:189], v[106:109]
	v_mfma_f32_16x16x32_bf16 v[106:109], v[166:169], v[190:193], v[106:109]
	v_mfma_f32_16x16x32_bf16 v[90:93], v[162:165], v[194:197], v[90:93]
	v_mfma_f32_16x16x32_bf16 v[90:93], v[166:169], v[198:201], v[90:93]
	v_mfma_f32_16x16x32_bf16 v[74:77], v[162:165], v[202:205], v[74:77]
	v_mfma_f32_16x16x32_bf16 v[74:77], v[166:169], v[206:209], v[74:77]
	v_mfma_f32_16x16x32_bf16 v[70:73], v[170:173], v[202:205], v[70:73]
	v_mfma_f32_16x16x32_bf16 v[70:73], v[174:177], v[206:209], v[70:73]
	v_mfma_f32_16x16x32_bf16 v[82:85], v[170:173], v[194:197], v[82:85]
	v_mfma_f32_16x16x32_bf16 v[82:85], v[174:177], v[198:201], v[82:85]
	v_mfma_f32_16x16x32_bf16 v[98:101], v[170:173], v[186:189], v[98:101]
	v_mfma_f32_16x16x32_bf16 v[98:101], v[174:177], v[190:193], v[98:101]
	v_mfma_f32_16x16x32_bf16 v[122:125], v[170:173], v[178:181], v[122:125]
	v_mfma_f32_16x16x32_bf16 v[122:125], v[174:177], v[182:185], v[122:125]
	s_setprio 0
	s_barrier
	s_mov_b32 m0, s31
	s_mov_b32 s22, s18
	s_mov_b32 s23, s19
	ds_read_b128 v[178:181], v140 offset:16384
	ds_read_b128 v[182:185], v140 offset:17408
	ds_read_b128 v[186:189], v140 offset:18432
	ds_read_b128 v[190:193], v140 offset:19456
	ds_read_b128 v[194:197], v140 offset:20480
	ds_read_b128 v[198:201], v140 offset:21504
	ds_read_b128 v[202:205], v140 offset:22528
	ds_read_b128 v[206:209], v140 offset:23552
	buffer_load_dwordx4 v137, s[20:23], s80 offen lds
	s_mov_b32 m0, s48
	s_add_i32 s81, s80, 0x80000
	buffer_load_dwordx4 v137, s[20:23], s81 offen lds
	s_mov_b32 m0, s49
	s_add_i32 s81, s80, 0x100000
	buffer_load_dwordx4 v137, s[20:23], s81 offen lds
	s_mov_b32 m0, s50
	s_add_i32 s81, s80, 0x180000
	buffer_load_dwordx4 v137, s[20:23], s81 offen lds
	s_mov_b32 m0, s30
	s_add_i32 s81, s78, 0x80000
	buffer_load_dwordx4 v136, s[16:19], s78 offen lds
	s_mov_b32 m0, s51
	s_nop 0
	buffer_load_dwordx4 v136, s[16:19], s81 offen lds
	s_waitcnt vmcnt(8) lgkmcnt(0)
	s_setprio 1
	v_mfma_f32_16x16x32_bf16 v[62:65], v[146:149], v[178:181], v[62:65]
	s_barrier
	v_mfma_f32_16x16x32_bf16 v[62:65], v[150:153], v[182:185], v[62:65]
	v_mfma_f32_16x16x32_bf16 v[46:49], v[146:149], v[186:189], v[46:49]
	v_mfma_f32_16x16x32_bf16 v[46:49], v[150:153], v[190:193], v[46:49]
	v_mfma_f32_16x16x32_bf16 v[30:33], v[146:149], v[194:197], v[30:33]
	v_mfma_f32_16x16x32_bf16 v[30:33], v[150:153], v[198:201], v[30:33]
	v_mfma_f32_16x16x32_bf16 v[14:17], v[146:149], v[202:205], v[14:17]
	v_mfma_f32_16x16x32_bf16 v[14:17], v[150:153], v[206:209], v[14:17]
	v_mfma_f32_16x16x32_bf16 v[6:9], v[154:157], v[202:205], v[6:9]
	v_mfma_f32_16x16x32_bf16 v[6:9], v[158:161], v[206:209], v[6:9]
	v_mfma_f32_16x16x32_bf16 v[22:25], v[154:157], v[194:197], v[22:25]
	v_mfma_f32_16x16x32_bf16 v[22:25], v[158:161], v[198:201], v[22:25]
	v_mfma_f32_16x16x32_bf16 v[38:41], v[154:157], v[186:189], v[38:41]
	v_mfma_f32_16x16x32_bf16 v[38:41], v[158:161], v[190:193], v[38:41]
	v_mfma_f32_16x16x32_bf16 v[54:57], v[154:157], v[178:181], v[54:57]
	v_mfma_f32_16x16x32_bf16 v[54:57], v[158:161], v[182:185], v[54:57]
	v_mfma_f32_16x16x32_bf16 v[58:61], v[162:165], v[178:181], v[58:61]
	v_mfma_f32_16x16x32_bf16 v[58:61], v[166:169], v[182:185], v[58:61]
	v_mfma_f32_16x16x32_bf16 v[42:45], v[162:165], v[186:189], v[42:45]
	v_mfma_f32_16x16x32_bf16 v[42:45], v[166:169], v[190:193], v[42:45]
	v_mfma_f32_16x16x32_bf16 v[26:29], v[162:165], v[194:197], v[26:29]
	v_mfma_f32_16x16x32_bf16 v[26:29], v[166:169], v[198:201], v[26:29]
	v_mfma_f32_16x16x32_bf16 v[10:13], v[162:165], v[202:205], v[10:13]
	v_mfma_f32_16x16x32_bf16 v[10:13], v[166:169], v[206:209], v[10:13]
	v_mfma_f32_16x16x32_bf16 v[2:5], v[170:173], v[202:205], v[2:5]
	v_mfma_f32_16x16x32_bf16 v[2:5], v[174:177], v[206:209], v[2:5]
	v_mfma_f32_16x16x32_bf16 v[18:21], v[170:173], v[194:197], v[18:21]
	v_mfma_f32_16x16x32_bf16 v[18:21], v[174:177], v[198:201], v[18:21]
	v_mfma_f32_16x16x32_bf16 v[34:37], v[170:173], v[186:189], v[34:37]
	v_mfma_f32_16x16x32_bf16 v[34:37], v[174:177], v[190:193], v[34:37]
	v_mfma_f32_16x16x32_bf16 v[50:53], v[170:173], v[178:181], v[50:53]
	v_mfma_f32_16x16x32_bf16 v[50:53], v[174:177], v[182:185], v[50:53]
	s_setprio 0
	s_barrier
	ds_read_b128 v[146:149], v141
	ds_read_b128 v[150:153], v141 offset:1024
	ds_read_b128 v[154:157], v141 offset:2048
	ds_read_b128 v[158:161], v141 offset:3072
	ds_read_b128 v[162:165], v142
	ds_read_b128 v[166:169], v142 offset:1024
	ds_read_b128 v[170:173], v142 offset:2048
	ds_read_b128 v[174:177], v142 offset:3072
	s_mov_b32 m0, s52
	s_add_i32 s81, s78, 0x100000
	ds_read_b128 v[178:181], v140 offset:32768
	ds_read_b128 v[182:185], v140 offset:33792
	ds_read_b128 v[186:189], v140 offset:34816
	ds_read_b128 v[190:193], v140 offset:35840
	ds_read_b128 v[194:197], v140 offset:36864
	ds_read_b128 v[198:201], v140 offset:37888
	ds_read_b128 v[202:205], v140 offset:38912
	ds_read_b128 v[206:209], v140 offset:39936
	buffer_load_dwordx4 v136, s[16:19], s81 offen lds
	s_mov_b32 m0, s53
	s_add_i32 s81, s78, 0x180000
	buffer_load_dwordx4 v136, s[16:19], s81 offen lds
	s_waitcnt vmcnt(8) lgkmcnt(0)
	s_setprio 1
	v_mfma_f32_16x16x32_bf16 v[118:121], v[146:149], v[178:181], v[118:121]
	s_barrier
	v_mfma_f32_16x16x32_bf16 v[118:121], v[150:153], v[182:185], v[118:121]
	v_mfma_f32_16x16x32_bf16 v[110:113], v[146:149], v[186:189], v[110:113]
	v_mfma_f32_16x16x32_bf16 v[110:113], v[150:153], v[190:193], v[110:113]
	v_mfma_f32_16x16x32_bf16 v[94:97], v[146:149], v[194:197], v[94:97]
	v_mfma_f32_16x16x32_bf16 v[94:97], v[150:153], v[198:201], v[94:97]
	v_mfma_f32_16x16x32_bf16 v[78:81], v[146:149], v[202:205], v[78:81]
	v_mfma_f32_16x16x32_bf16 v[78:81], v[150:153], v[206:209], v[78:81]
	v_mfma_f32_16x16x32_bf16 v[66:69], v[154:157], v[202:205], v[66:69]
	v_mfma_f32_16x16x32_bf16 v[66:69], v[158:161], v[206:209], v[66:69]
	v_mfma_f32_16x16x32_bf16 v[86:89], v[154:157], v[194:197], v[86:89]
	v_mfma_f32_16x16x32_bf16 v[86:89], v[158:161], v[198:201], v[86:89]
	v_mfma_f32_16x16x32_bf16 v[102:105], v[154:157], v[186:189], v[102:105]
	v_mfma_f32_16x16x32_bf16 v[102:105], v[158:161], v[190:193], v[102:105]
	v_mfma_f32_16x16x32_bf16 v[114:117], v[154:157], v[178:181], v[114:117]
	v_mfma_f32_16x16x32_bf16 v[114:117], v[158:161], v[182:185], v[114:117]
	v_mfma_f32_16x16x32_bf16 v[126:129], v[162:165], v[178:181], v[126:129]
	v_mfma_f32_16x16x32_bf16 v[126:129], v[166:169], v[182:185], v[126:129]
	v_mfma_f32_16x16x32_bf16 v[106:109], v[162:165], v[186:189], v[106:109]
	v_mfma_f32_16x16x32_bf16 v[106:109], v[166:169], v[190:193], v[106:109]
	v_mfma_f32_16x16x32_bf16 v[90:93], v[162:165], v[194:197], v[90:93]
	v_mfma_f32_16x16x32_bf16 v[90:93], v[166:169], v[198:201], v[90:93]
	v_mfma_f32_16x16x32_bf16 v[74:77], v[162:165], v[202:205], v[74:77]
	v_mfma_f32_16x16x32_bf16 v[74:77], v[166:169], v[206:209], v[74:77]
	v_mfma_f32_16x16x32_bf16 v[70:73], v[170:173], v[202:205], v[70:73]
	v_mfma_f32_16x16x32_bf16 v[70:73], v[174:177], v[206:209], v[70:73]
	v_mfma_f32_16x16x32_bf16 v[82:85], v[170:173], v[194:197], v[82:85]
	v_mfma_f32_16x16x32_bf16 v[82:85], v[174:177], v[198:201], v[82:85]
	v_mfma_f32_16x16x32_bf16 v[98:101], v[170:173], v[186:189], v[98:101]
	v_mfma_f32_16x16x32_bf16 v[98:101], v[174:177], v[190:193], v[98:101]
	v_mfma_f32_16x16x32_bf16 v[122:125], v[170:173], v[178:181], v[122:125]
	v_mfma_f32_16x16x32_bf16 v[122:125], v[174:177], v[182:185], v[122:125]
	s_setprio 0
	s_barrier
	s_mov_b32 m0, s54
	s_or_b32 s81, s80, 0x80
	ds_read_b128 v[178:181], v140 offset:49152
	ds_read_b128 v[182:185], v140 offset:50176
	ds_read_b128 v[186:189], v140 offset:51200
	ds_read_b128 v[190:193], v140 offset:52224
	ds_read_b128 v[194:197], v140 offset:53248
	ds_read_b128 v[198:201], v140 offset:54272
	ds_read_b128 v[202:205], v140 offset:55296
	ds_read_b128 v[206:209], v140 offset:56320
	buffer_load_dwordx4 v137, s[20:23], s81 offen lds
	s_add_i32 s81, s80, 0x80080
	s_mov_b32 m0, s55
	s_add_i32 s78, s78, 0x80080
	buffer_load_dwordx4 v137, s[20:23], s81 offen lds
	s_add_i32 s81, s80, 0x100080
	s_mov_b32 m0, s58
	s_add_i32 s80, s80, 0x180080
	buffer_load_dwordx4 v137, s[20:23], s81 offen lds
	s_mov_b32 m0, s59
	s_nop 0
	buffer_load_dwordx4 v137, s[20:23], s80 offen lds
	s_mov_b32 m0, s56
	s_nop 0
	buffer_load_dwordx4 v136, s[16:19], s79 offen lds
	s_mov_b32 m0, s57
	s_nop 0
	buffer_load_dwordx4 v136, s[16:19], s78 offen lds
	s_waitcnt vmcnt(8) lgkmcnt(0)
	s_setprio 1
	v_mfma_f32_16x16x32_bf16 v[62:65], v[146:149], v[178:181], v[62:65]
	s_barrier
	v_mfma_f32_16x16x32_bf16 v[62:65], v[150:153], v[182:185], v[62:65]
	v_mfma_f32_16x16x32_bf16 v[46:49], v[146:149], v[186:189], v[46:49]
	v_mfma_f32_16x16x32_bf16 v[46:49], v[150:153], v[190:193], v[46:49]
	v_mfma_f32_16x16x32_bf16 v[30:33], v[146:149], v[194:197], v[30:33]
	v_mfma_f32_16x16x32_bf16 v[30:33], v[150:153], v[198:201], v[30:33]
	v_mfma_f32_16x16x32_bf16 v[14:17], v[146:149], v[202:205], v[14:17]
	v_mfma_f32_16x16x32_bf16 v[14:17], v[150:153], v[206:209], v[14:17]
	v_mfma_f32_16x16x32_bf16 v[6:9], v[154:157], v[202:205], v[6:9]
	v_mfma_f32_16x16x32_bf16 v[6:9], v[158:161], v[206:209], v[6:9]
	v_mfma_f32_16x16x32_bf16 v[22:25], v[154:157], v[194:197], v[22:25]
	v_mfma_f32_16x16x32_bf16 v[22:25], v[158:161], v[198:201], v[22:25]
	v_mfma_f32_16x16x32_bf16 v[38:41], v[154:157], v[186:189], v[38:41]
	v_mfma_f32_16x16x32_bf16 v[38:41], v[158:161], v[190:193], v[38:41]
	v_mfma_f32_16x16x32_bf16 v[54:57], v[154:157], v[178:181], v[54:57]
	v_mfma_f32_16x16x32_bf16 v[54:57], v[158:161], v[182:185], v[54:57]
	v_mfma_f32_16x16x32_bf16 v[58:61], v[162:165], v[178:181], v[58:61]
	v_mfma_f32_16x16x32_bf16 v[58:61], v[166:169], v[182:185], v[58:61]
	v_mfma_f32_16x16x32_bf16 v[42:45], v[162:165], v[186:189], v[42:45]
	v_mfma_f32_16x16x32_bf16 v[42:45], v[166:169], v[190:193], v[42:45]
	v_mfma_f32_16x16x32_bf16 v[26:29], v[162:165], v[194:197], v[26:29]
	v_mfma_f32_16x16x32_bf16 v[26:29], v[166:169], v[198:201], v[26:29]
	v_mfma_f32_16x16x32_bf16 v[10:13], v[162:165], v[202:205], v[10:13]
	v_mfma_f32_16x16x32_bf16 v[10:13], v[166:169], v[206:209], v[10:13]
	v_mfma_f32_16x16x32_bf16 v[2:5], v[170:173], v[202:205], v[2:5]
	v_mfma_f32_16x16x32_bf16 v[2:5], v[174:177], v[206:209], v[2:5]
	v_mfma_f32_16x16x32_bf16 v[18:21], v[170:173], v[194:197], v[18:21]
	v_mfma_f32_16x16x32_bf16 v[18:21], v[174:177], v[198:201], v[18:21]
	v_mfma_f32_16x16x32_bf16 v[34:37], v[170:173], v[186:189], v[34:37]
	v_mfma_f32_16x16x32_bf16 v[34:37], v[174:177], v[190:193], v[34:37]
	v_mfma_f32_16x16x32_bf16 v[50:53], v[170:173], v[178:181], v[50:53]
	v_mfma_f32_16x16x32_bf16 v[50:53], v[174:177], v[182:185], v[50:53]
	s_setprio 0
	s_barrier
	s_add_i32 s77, s77, 2
	s_addk_i32 s75, 0x100
	s_addk_i32 s76, 0x100
	s_cmp_ge_i32 s77, s13
	s_cbranch_scc0 .LBB0_1402
	s_and_b64 vcc, exec, s[46:47]
	s_cbranch_vccz .LBB0_1405

.LBB0_1519:
	ds_read_b128 v[134:137], v208
	ds_read_b128 v[138:141], v208 offset:1024
	ds_read_b128 v[142:145], v208 offset:2048
	ds_read_b128 v[146:149], v208 offset:3072
	ds_read_b128 v[150:153], v209
	ds_read_b128 v[154:157], v209 offset:1024
	ds_read_b128 v[158:161], v209 offset:2048
	ds_read_b128 v[162:165], v209 offset:3072
	s_add_i32 s18, s80, 0xffbf8080
	s_cmp_eq_u32 s65, s82
	s_cselect_b32 s83, s6, s18
	s_cselect_b32 s85, s7, s81
	s_or_b32 s84, s83, 0x80
	s_add_i32 s18, s80, 0xffea8000
	s_mov_b32 m0, s66
	ds_read_b128 v[166:169], v210
	ds_read_b128 v[170:173], v210 offset:1024
	ds_read_b128 v[174:177], v210 offset:2048
	ds_read_b128 v[178:181], v210 offset:3072
	ds_read_b128 v[182:185], v210 offset:4096
	ds_read_b128 v[186:189], v210 offset:5120
	ds_read_b128 v[190:193], v210 offset:6144
	ds_read_b128 v[194:197], v210 offset:7168
	buffer_load_dwordx4 v206, s[12:15], s18 offen lds
	s_mov_b32 m0, s69
	s_nop 0
	buffer_load_dwordx4 v206, s[12:15], s80 offen lds
	s_waitcnt vmcnt(8) lgkmcnt(0)
	s_setprio 1
	v_mfma_f32_16x16x32_bf16 v[126:129], v[134:137], v[166:169], v[126:129]
	s_barrier
	v_mfma_f32_16x16x32_bf16 v[126:129], v[138:141], v[170:173], v[126:129]
	v_mfma_f32_16x16x32_bf16 v[118:121], v[134:137], v[174:177], v[118:121]
	v_mfma_f32_16x16x32_bf16 v[118:121], v[138:141], v[178:181], v[118:121]
	v_mfma_f32_16x16x32_bf16 v[106:109], v[134:137], v[182:185], v[106:109]
	v_mfma_f32_16x16x32_bf16 v[106:109], v[138:141], v[186:189], v[106:109]
	v_mfma_f32_16x16x32_bf16 v[90:93], v[134:137], v[190:193], v[90:93]
	v_mfma_f32_16x16x32_bf16 v[90:93], v[138:141], v[194:197], v[90:93]
	v_mfma_f32_16x16x32_bf16 v[82:85], v[142:145], v[190:193], v[82:85]
	v_mfma_f32_16x16x32_bf16 v[82:85], v[146:149], v[194:197], v[82:85]
	v_mfma_f32_16x16x32_bf16 v[98:101], v[142:145], v[182:185], v[98:101]
	v_mfma_f32_16x16x32_bf16 v[98:101], v[146:149], v[186:189], v[98:101]
	v_mfma_f32_16x16x32_bf16 v[114:117], v[142:145], v[174:177], v[114:117]
	v_mfma_f32_16x16x32_bf16 v[114:117], v[146:149], v[178:181], v[114:117]
	v_mfma_f32_16x16x32_bf16 v[122:125], v[142:145], v[166:169], v[122:125]
	v_mfma_f32_16x16x32_bf16 v[122:125], v[146:149], v[170:173], v[122:125]
	v_mfma_f32_16x16x32_bf16 v[110:113], v[150:153], v[166:169], v[110:113]
	v_mfma_f32_16x16x32_bf16 v[110:113], v[154:157], v[170:173], v[110:113]
	v_mfma_f32_16x16x32_bf16 v[94:97], v[150:153], v[174:177], v[94:97]
	v_mfma_f32_16x16x32_bf16 v[94:97], v[154:157], v[178:181], v[94:97]
	v_mfma_f32_16x16x32_bf16 v[78:81], v[150:153], v[182:185], v[78:81]
	v_mfma_f32_16x16x32_bf16 v[78:81], v[154:157], v[186:189], v[78:81]
	v_mfma_f32_16x16x32_bf16 v[70:73], v[150:153], v[190:193], v[70:73]
	v_mfma_f32_16x16x32_bf16 v[70:73], v[154:157], v[194:197], v[70:73]
	v_mfma_f32_16x16x32_bf16 v[66:69], v[158:161], v[190:193], v[66:69]
	v_mfma_f32_16x16x32_bf16 v[66:69], v[162:165], v[194:197], v[66:69]
	v_mfma_f32_16x16x32_bf16 v[74:77], v[158:161], v[182:185], v[74:77]
	v_mfma_f32_16x16x32_bf16 v[74:77], v[162:165], v[186:189], v[74:77]
	v_mfma_f32_16x16x32_bf16 v[86:89], v[158:161], v[174:177], v[86:89]
	v_mfma_f32_16x16x32_bf16 v[86:89], v[162:165], v[178:181], v[86:89]
	v_mfma_f32_16x16x32_bf16 v[102:105], v[158:161], v[166:169], v[102:105]
	v_mfma_f32_16x16x32_bf16 v[102:105], v[162:165], v[170:173], v[102:105]
	s_setprio 0
	s_barrier
	s_mov_b32 m0, s27
	s_mov_b32 s18, s14
	s_mov_b32 s19, s15
	ds_read_b128 v[166:169], v210 offset:16384
	ds_read_b128 v[170:173], v210 offset:17408
	ds_read_b128 v[174:177], v210 offset:18432
	ds_read_b128 v[178:181], v210 offset:19456
	ds_read_b128 v[182:185], v210 offset:20480
	ds_read_b128 v[186:189], v210 offset:21504
	ds_read_b128 v[190:193], v210 offset:22528
	ds_read_b128 v[194:197], v210 offset:23552
	buffer_load_dwordx4 v207, s[16:19], s85 offen lds
	s_mov_b32 m0, s30
	s_add_i32 s86, s85, 0x158000
	buffer_load_dwordx4 v207, s[16:19], s86 offen lds
	s_mov_b32 m0, s31
	s_add_i32 s86, s85, 0x2b0000
	buffer_load_dwordx4 v207, s[16:19], s86 offen lds
	s_mov_b32 m0, s50
	s_add_i32 s86, s85, 0x408000
	buffer_load_dwordx4 v207, s[16:19], s86 offen lds
	s_mov_b32 m0, s25
	s_add_i32 s86, s83, 0x158000
	buffer_load_dwordx4 v206, s[12:15], s83 offen lds
	s_mov_b32 m0, s51
	s_nop 0
	buffer_load_dwordx4 v206, s[12:15], s86 offen lds
	s_waitcnt vmcnt(8) lgkmcnt(0)
	s_setprio 1
	v_mfma_f32_16x16x32_bf16 v[62:65], v[134:137], v[166:169], v[62:65]
	s_barrier
	v_mfma_f32_16x16x32_bf16 v[62:65], v[138:141], v[170:173], v[62:65]
	v_mfma_f32_16x16x32_bf16 v[54:57], v[134:137], v[174:177], v[54:57]
	v_mfma_f32_16x16x32_bf16 v[54:57], v[138:141], v[178:181], v[54:57]
	v_mfma_f32_16x16x32_bf16 v[42:45], v[134:137], v[182:185], v[42:45]
	v_mfma_f32_16x16x32_bf16 v[42:45], v[138:141], v[186:189], v[42:45]
	v_mfma_f32_16x16x32_bf16 v[26:29], v[134:137], v[190:193], v[26:29]
	v_mfma_f32_16x16x32_bf16 v[26:29], v[138:141], v[194:197], v[26:29]
	v_mfma_f32_16x16x32_bf16 v[18:21], v[142:145], v[190:193], v[18:21]
	v_mfma_f32_16x16x32_bf16 v[18:21], v[146:149], v[194:197], v[18:21]
	v_mfma_f32_16x16x32_bf16 v[34:37], v[142:145], v[182:185], v[34:37]
	v_mfma_f32_16x16x32_bf16 v[34:37], v[146:149], v[186:189], v[34:37]
	v_mfma_f32_16x16x32_bf16 v[50:53], v[142:145], v[174:177], v[50:53]
	v_mfma_f32_16x16x32_bf16 v[50:53], v[146:149], v[178:181], v[50:53]
	v_mfma_f32_16x16x32_bf16 v[58:61], v[142:145], v[166:169], v[58:61]
	v_mfma_f32_16x16x32_bf16 v[58:61], v[146:149], v[170:173], v[58:61]
	v_mfma_f32_16x16x32_bf16 v[46:49], v[150:153], v[166:169], v[46:49]
	v_mfma_f32_16x16x32_bf16 v[46:49], v[154:157], v[170:173], v[46:49]
	v_mfma_f32_16x16x32_bf16 v[30:33], v[150:153], v[174:177], v[30:33]
	v_mfma_f32_16x16x32_bf16 v[30:33], v[154:157], v[178:181], v[30:33]
	v_mfma_f32_16x16x32_bf16 v[14:17], v[150:153], v[182:185], v[14:17]
	v_mfma_f32_16x16x32_bf16 v[14:17], v[154:157], v[186:189], v[14:17]
	v_mfma_f32_16x16x32_bf16 v[6:9], v[150:153], v[190:193], v[6:9]
	v_mfma_f32_16x16x32_bf16 v[6:9], v[154:157], v[194:197], v[6:9]
	v_mfma_f32_16x16x32_bf16 v[2:5], v[158:161], v[190:193], v[2:5]
	v_mfma_f32_16x16x32_bf16 v[2:5], v[162:165], v[194:197], v[2:5]
	v_mfma_f32_16x16x32_bf16 v[10:13], v[158:161], v[182:185], v[10:13]
	v_mfma_f32_16x16x32_bf16 v[10:13], v[162:165], v[186:189], v[10:13]
	v_mfma_f32_16x16x32_bf16 v[22:25], v[158:161], v[174:177], v[22:25]
	v_mfma_f32_16x16x32_bf16 v[22:25], v[162:165], v[178:181], v[22:25]
	v_mfma_f32_16x16x32_bf16 v[38:41], v[158:161], v[166:169], v[38:41]
	v_mfma_f32_16x16x32_bf16 v[38:41], v[162:165], v[170:173], v[38:41]
	s_setprio 0
	s_barrier
	ds_read_b128 v[134:137], v211
	ds_read_b128 v[138:141], v211 offset:1024
	ds_read_b128 v[142:145], v211 offset:2048
	ds_read_b128 v[146:149], v211 offset:3072
	ds_read_b128 v[150:153], v212
	ds_read_b128 v[154:157], v212 offset:1024
	ds_read_b128 v[158:161], v212 offset:2048
	ds_read_b128 v[162:165], v212 offset:3072
	s_mov_b32 m0, s52
	s_add_i32 s86, s83, 0x2b0000
	ds_read_b128 v[166:169], v210 offset:32768
	ds_read_b128 v[170:173], v210 offset:33792
	ds_read_b128 v[174:177], v210 offset:34816
	ds_read_b128 v[178:181], v210 offset:35840
	ds_read_b128 v[182:185], v210 offset:36864
	ds_read_b128 v[186:189], v210 offset:37888
	ds_read_b128 v[190:193], v210 offset:38912
	ds_read_b128 v[194:197], v210 offset:39936
	buffer_load_dwordx4 v206, s[12:15], s86 offen lds
	s_mov_b32 m0, s53
	s_add_i32 s86, s83, 0x408000
	buffer_load_dwordx4 v206, s[12:15], s86 offen lds
	s_waitcnt vmcnt(8) lgkmcnt(0)
	s_setprio 1
	v_mfma_f32_16x16x32_bf16 v[126:129], v[134:137], v[166:169], v[126:129]
	s_barrier
	v_mfma_f32_16x16x32_bf16 v[126:129], v[138:141], v[170:173], v[126:129]
	v_mfma_f32_16x16x32_bf16 v[118:121], v[134:137], v[174:177], v[118:121]
	v_mfma_f32_16x16x32_bf16 v[118:121], v[138:141], v[178:181], v[118:121]
	v_mfma_f32_16x16x32_bf16 v[106:109], v[134:137], v[182:185], v[106:109]
	v_mfma_f32_16x16x32_bf16 v[106:109], v[138:141], v[186:189], v[106:109]
	v_mfma_f32_16x16x32_bf16 v[90:93], v[134:137], v[190:193], v[90:93]
	v_mfma_f32_16x16x32_bf16 v[90:93], v[138:141], v[194:197], v[90:93]
	v_mfma_f32_16x16x32_bf16 v[82:85], v[142:145], v[190:193], v[82:85]
	v_mfma_f32_16x16x32_bf16 v[82:85], v[146:149], v[194:197], v[82:85]
	v_mfma_f32_16x16x32_bf16 v[98:101], v[142:145], v[182:185], v[98:101]
	v_mfma_f32_16x16x32_bf16 v[98:101], v[146:149], v[186:189], v[98:101]
	v_mfma_f32_16x16x32_bf16 v[114:117], v[142:145], v[174:177], v[114:117]
	v_mfma_f32_16x16x32_bf16 v[114:117], v[146:149], v[178:181], v[114:117]
	v_mfma_f32_16x16x32_bf16 v[122:125], v[142:145], v[166:169], v[122:125]
	v_mfma_f32_16x16x32_bf16 v[122:125], v[146:149], v[170:173], v[122:125]
	v_mfma_f32_16x16x32_bf16 v[110:113], v[150:153], v[166:169], v[110:113]
	v_mfma_f32_16x16x32_bf16 v[110:113], v[154:157], v[170:173], v[110:113]
	v_mfma_f32_16x16x32_bf16 v[94:97], v[150:153], v[174:177], v[94:97]
	v_mfma_f32_16x16x32_bf16 v[94:97], v[154:157], v[178:181], v[94:97]
	v_mfma_f32_16x16x32_bf16 v[78:81], v[150:153], v[182:185], v[78:81]
	v_mfma_f32_16x16x32_bf16 v[78:81], v[154:157], v[186:189], v[78:81]
	v_mfma_f32_16x16x32_bf16 v[70:73], v[150:153], v[190:193], v[70:73]
	v_mfma_f32_16x16x32_bf16 v[70:73], v[154:157], v[194:197], v[70:73]
	v_mfma_f32_16x16x32_bf16 v[66:69], v[158:161], v[190:193], v[66:69]
	v_mfma_f32_16x16x32_bf16 v[66:69], v[162:165], v[194:197], v[66:69]
	v_mfma_f32_16x16x32_bf16 v[74:77], v[158:161], v[182:185], v[74:77]
	v_mfma_f32_16x16x32_bf16 v[74:77], v[162:165], v[186:189], v[74:77]
	v_mfma_f32_16x16x32_bf16 v[86:89], v[158:161], v[174:177], v[86:89]
	v_mfma_f32_16x16x32_bf16 v[86:89], v[162:165], v[178:181], v[86:89]
	v_mfma_f32_16x16x32_bf16 v[102:105], v[158:161], v[166:169], v[102:105]
	v_mfma_f32_16x16x32_bf16 v[102:105], v[162:165], v[170:173], v[102:105]
	s_setprio 0
	s_barrier
	s_mov_b32 m0, s57
	s_or_b32 s86, s85, 0x80
	ds_read_b128 v[166:169], v210 offset:49152
	ds_read_b128 v[170:173], v210 offset:50176
	ds_read_b128 v[174:177], v210 offset:51200
	ds_read_b128 v[178:181], v210 offset:52224
	ds_read_b128 v[182:185], v210 offset:53248
	ds_read_b128 v[186:189], v210 offset:54272
	ds_read_b128 v[190:193], v210 offset:55296
	ds_read_b128 v[194:197], v210 offset:56320
	buffer_load_dwordx4 v207, s[16:19], s86 offen lds
	s_add_i32 s86, s85, 0x158080
	s_mov_b32 m0, s58
	s_add_i32 s83, s83, 0x158080
	buffer_load_dwordx4 v207, s[16:19], s86 offen lds
	s_add_i32 s86, s85, 0x2b0080
	s_mov_b32 m0, s61
	s_add_i32 s85, s85, 0x408080
	buffer_load_dwordx4 v207, s[16:19], s86 offen lds
	s_mov_b32 m0, s62
	s_nop 0
	buffer_load_dwordx4 v207, s[16:19], s85 offen lds
	s_mov_b32 m0, s59
	s_nop 0
	buffer_load_dwordx4 v206, s[12:15], s84 offen lds
	s_mov_b32 m0, s60
	s_nop 0
	buffer_load_dwordx4 v206, s[12:15], s83 offen lds
	s_waitcnt vmcnt(8) lgkmcnt(0)
	s_setprio 1
	v_mfma_f32_16x16x32_bf16 v[62:65], v[134:137], v[166:169], v[62:65]
	s_barrier
	v_mfma_f32_16x16x32_bf16 v[62:65], v[138:141], v[170:173], v[62:65]
	v_mfma_f32_16x16x32_bf16 v[54:57], v[134:137], v[174:177], v[54:57]
	v_mfma_f32_16x16x32_bf16 v[54:57], v[138:141], v[178:181], v[54:57]
	v_mfma_f32_16x16x32_bf16 v[42:45], v[134:137], v[182:185], v[42:45]
	v_mfma_f32_16x16x32_bf16 v[42:45], v[138:141], v[186:189], v[42:45]
	v_mfma_f32_16x16x32_bf16 v[26:29], v[134:137], v[190:193], v[26:29]
	v_mfma_f32_16x16x32_bf16 v[26:29], v[138:141], v[194:197], v[26:29]
	v_mfma_f32_16x16x32_bf16 v[18:21], v[142:145], v[190:193], v[18:21]
	v_mfma_f32_16x16x32_bf16 v[18:21], v[146:149], v[194:197], v[18:21]
	v_mfma_f32_16x16x32_bf16 v[34:37], v[142:145], v[182:185], v[34:37]
	v_mfma_f32_16x16x32_bf16 v[34:37], v[146:149], v[186:189], v[34:37]
	v_mfma_f32_16x16x32_bf16 v[50:53], v[142:145], v[174:177], v[50:53]
	v_mfma_f32_16x16x32_bf16 v[50:53], v[146:149], v[178:181], v[50:53]
	v_mfma_f32_16x16x32_bf16 v[58:61], v[142:145], v[166:169], v[58:61]
	v_mfma_f32_16x16x32_bf16 v[58:61], v[146:149], v[170:173], v[58:61]
	v_mfma_f32_16x16x32_bf16 v[46:49], v[150:153], v[166:169], v[46:49]
	v_mfma_f32_16x16x32_bf16 v[46:49], v[154:157], v[170:173], v[46:49]
	v_mfma_f32_16x16x32_bf16 v[30:33], v[150:153], v[174:177], v[30:33]
	v_mfma_f32_16x16x32_bf16 v[30:33], v[154:157], v[178:181], v[30:33]
	v_mfma_f32_16x16x32_bf16 v[14:17], v[150:153], v[182:185], v[14:17]
	v_mfma_f32_16x16x32_bf16 v[14:17], v[154:157], v[186:189], v[14:17]
	v_mfma_f32_16x16x32_bf16 v[6:9], v[150:153], v[190:193], v[6:9]
	v_mfma_f32_16x16x32_bf16 v[6:9], v[154:157], v[194:197], v[6:9]
	v_mfma_f32_16x16x32_bf16 v[2:5], v[158:161], v[190:193], v[2:5]
	v_mfma_f32_16x16x32_bf16 v[2:5], v[162:165], v[194:197], v[2:5]
	v_mfma_f32_16x16x32_bf16 v[10:13], v[158:161], v[182:185], v[10:13]
	v_mfma_f32_16x16x32_bf16 v[10:13], v[162:165], v[186:189], v[10:13]
	v_mfma_f32_16x16x32_bf16 v[22:25], v[158:161], v[174:177], v[22:25]
	v_mfma_f32_16x16x32_bf16 v[22:25], v[162:165], v[178:181], v[22:25]
	v_mfma_f32_16x16x32_bf16 v[38:41], v[158:161], v[166:169], v[38:41]
	v_mfma_f32_16x16x32_bf16 v[38:41], v[162:165], v[170:173], v[38:41]
	s_setprio 0
	s_barrier
	s_add_i32 s82, s82, 2
	s_addk_i32 s80, 0x100
	s_addk_i32 s81, 0x100
	s_cmp_ge_i32 s82, s3
	s_cbranch_scc0 .LBB0_1519
	v_pk_mul_f32 v[182:183], v[128:129], 0.5 op_sel_hi:[1,0]
	v_pk_mul_f32 v[184:185], v[126:127], 0.5 op_sel_hi:[1,0]
	v_pk_mul_f32 v[186:187], v[124:125], 0.5 op_sel_hi:[1,0]
	v_pk_mul_f32 v[188:189], v[122:123], 0.5 op_sel_hi:[1,0]
	v_pk_mul_f32 v[196:197], v[112:113], 0.5 op_sel_hi:[1,0]
	v_pk_mul_f32 v[194:195], v[110:111], 0.5 op_sel_hi:[1,0]
	v_pk_mul_f32 v[192:193], v[104:105], 0.5 op_sel_hi:[1,0]
	v_pk_mul_f32 v[190:191], v[102:103], 0.5 op_sel_hi:[1,0]
	v_pk_mul_f32 v[180:181], v[120:121], 0.5 op_sel_hi:[1,0]
	v_pk_mul_f32 v[178:179], v[118:119], 0.5 op_sel_hi:[1,0]
	v_pk_mul_f32 v[176:177], v[116:117], 0.5 op_sel_hi:[1,0]
	v_pk_mul_f32 v[174:175], v[114:115], 0.5 op_sel_hi:[1,0]
	v_pk_mul_f32 v[170:171], v[96:97], 0.5 op_sel_hi:[1,0]
	v_pk_mul_f32 v[168:169], v[94:95], 0.5 op_sel_hi:[1,0]
	v_pk_mul_f32 v[166:167], v[88:89], 0.5 op_sel_hi:[1,0]
	v_pk_mul_f32 v[164:165], v[86:87], 0.5 op_sel_hi:[1,0]
	v_pk_mul_f32 v[162:163], v[108:109], 0.5 op_sel_hi:[1,0]
	v_pk_mul_f32 v[160:161], v[106:107], 0.5 op_sel_hi:[1,0]
	v_pk_mul_f32 v[158:159], v[100:101], 0.5 op_sel_hi:[1,0]
	v_pk_mul_f32 v[156:157], v[98:99], 0.5 op_sel_hi:[1,0]
	v_pk_mul_f32 v[154:155], v[80:81], 0.5 op_sel_hi:[1,0]
	v_pk_mul_f32 v[152:153], v[78:79], 0.5 op_sel_hi:[1,0]
	v_pk_mul_f32 v[150:151], v[76:77], 0.5 op_sel_hi:[1,0]
	v_pk_mul_f32 v[148:149], v[74:75], 0.5 op_sel_hi:[1,0]
	v_pk_mul_f32 v[144:145], v[92:93], 0.5 op_sel_hi:[1,0]
	v_pk_mul_f32 v[142:143], v[90:91], 0.5 op_sel_hi:[1,0]
	v_pk_mul_f32 v[140:141], v[84:85], 0.5 op_sel_hi:[1,0]
	v_pk_mul_f32 v[138:139], v[82:83], 0.5 op_sel_hi:[1,0]
	v_pk_mul_f32 v[136:137], v[72:73], 0.5 op_sel_hi:[1,0]
	v_pk_mul_f32 v[134:135], v[70:71], 0.5 op_sel_hi:[1,0]
	v_pk_mul_f32 v[128:129], v[68:69], 0.5 op_sel_hi:[1,0]
	v_pk_mul_f32 v[126:127], v[66:67], 0.5 op_sel_hi:[1,0]
	v_pk_mul_f32 v[122:123], v[64:65], 0.5 op_sel_hi:[1,0]
	v_pk_mul_f32 v[120:121], v[62:63], 0.5 op_sel_hi:[1,0]
	v_pk_mul_f32 v[118:119], v[60:61], 0.5 op_sel_hi:[1,0]
	v_pk_mul_f32 v[116:117], v[58:59], 0.5 op_sel_hi:[1,0]
	v_pk_mul_f32 v[112:113], v[48:49], 0.5 op_sel_hi:[1,0]
	v_pk_mul_f32 v[110:111], v[46:47], 0.5 op_sel_hi:[1,0]
	v_pk_mul_f32 v[108:109], v[40:41], 0.5 op_sel_hi:[1,0]
	v_pk_mul_f32 v[106:107], v[38:39], 0.5 op_sel_hi:[1,0]
	v_pk_mul_f32 v[104:105], v[56:57], 0.5 op_sel_hi:[1,0]
	v_pk_mul_f32 v[102:103], v[54:55], 0.5 op_sel_hi:[1,0]
	v_pk_mul_f32 v[100:101], v[52:53], 0.5 op_sel_hi:[1,0]
	v_pk_mul_f32 v[98:99], v[50:51], 0.5 op_sel_hi:[1,0]
	v_pk_mul_f32 v[96:97], v[32:33], 0.5 op_sel_hi:[1,0]
	v_pk_mul_f32 v[94:95], v[30:31], 0.5 op_sel_hi:[1,0]
	v_pk_mul_f32 v[92:93], v[24:25], 0.5 op_sel_hi:[1,0]
	v_pk_mul_f32 v[90:91], v[22:23], 0.5 op_sel_hi:[1,0]
	v_pk_mul_f32 v[88:89], v[44:45], 0.5 op_sel_hi:[1,0]
	v_pk_mul_f32 v[86:87], v[42:43], 0.5 op_sel_hi:[1,0]
	v_pk_mul_f32 v[84:85], v[36:37], 0.5 op_sel_hi:[1,0]
	v_pk_mul_f32 v[82:83], v[34:35], 0.5 op_sel_hi:[1,0]
	v_pk_mul_f32 v[80:81], v[16:17], 0.5 op_sel_hi:[1,0]
	v_pk_mul_f32 v[78:79], v[14:15], 0.5 op_sel_hi:[1,0]
	v_pk_mul_f32 v[76:77], v[12:13], 0.5 op_sel_hi:[1,0]
	v_pk_mul_f32 v[74:75], v[10:11], 0.5 op_sel_hi:[1,0]
	v_pk_mul_f32 v[72:73], v[28:29], 0.5 op_sel_hi:[1,0]
	v_pk_mul_f32 v[70:71], v[26:27], 0.5 op_sel_hi:[1,0]
	v_pk_mul_f32 v[68:69], v[20:21], 0.5 op_sel_hi:[1,0]
	v_pk_mul_f32 v[66:67], v[18:19], 0.5 op_sel_hi:[1,0]
	v_pk_mul_f32 v[64:65], v[8:9], 0.5 op_sel_hi:[1,0]
	v_pk_mul_f32 v[62:63], v[6:7], 0.5 op_sel_hi:[1,0]
	v_pk_mul_f32 v[60:61], v[4:5], 0.5 op_sel_hi:[1,0]
	v_pk_mul_f32 v[58:59], v[2:3], 0.5 op_sel_hi:[1,0]
	s_and_b64 vcc, exec, s[40:41]
	s_cbranch_vccz .LBB0_1522
